# K-loop: the 4 tail MFMAs behind the early barrier interleaved with the first LDS-DMA pieces of the following 6-piece load segment
# baseline (speedup 1.0000x reference)
.LBB0_322:
	s_ashr_i32 s43, s42, 31
	s_lshl_b64 s[46:47], s[42:43], 19
	s_add_u32 s46, s12, s46
	s_addc_u32 s47, s13, s47
	s_and_b64 s[48:49], s[4:5], exec
	s_cselect_b32 s18, s47, s7
	s_cselect_b32 s43, s46, s6
	s_ashr_i32 s45, s44, 31
	s_lshl_b64 s[48:49], s[44:45], 19
	s_add_u32 s48, s59, s48
	s_addc_u32 s49, s60, s49
	s_and_b64 s[50:51], s[4:5], exec
	s_cselect_b32 s45, s49, s9
	s_cselect_b32 s55, s48, s8
	s_add_u32 s6, s6, 0x40080
	s_addc_u32 s7, s7, 0
	s_add_u32 s56, s8, 0x100
	s_addc_u32 s57, s9, 0
	s_mov_b32 s78, -2
	ds_read_b128 v[96:99], v209
	ds_read_b128 v[100:103], v209 offset:1024
	ds_read_b128 v[120:123], v209 offset:2048
	ds_read_b128 v[124:127], v209 offset:3072
	ds_read_b128 v[144:147], v210
	ds_read_b128 v[148:151], v210 offset:1024
	ds_read_b128 v[152:155], v210 offset:2048
	ds_read_b128 v[156:159], v210 offset:3072
	s_add_u32 s8, s6, 0xfffc0080
	s_addc_u32 s9, s7, -1
	s_cmp_eq_u32 s78, 12
	s_cselect_b32 s51, s18, s9
	s_cselect_b32 s50, s43, s8
	s_cselect_b32 s9, s45, s57
	s_cselect_b32 s8, s55, s56
	v_lshl_add_u64 v[206:207], s[6:7], 0, v[170:171]
	s_add_i32 m0, s17, 0xc000
	ds_read_b128 v[178:181], v211
	ds_read_b128 v[182:185], v211 offset:1024
	ds_read_b128 v[186:189], v211 offset:2048
	ds_read_b128 v[190:193], v211 offset:3072
	ds_read_b128 v[194:197], v211 offset:4096
	ds_read_b128 v[198:201], v211 offset:5120
	ds_read_b128 v[202:205], v211 offset:6144
	ds_read_b128 v[218:221], v211 offset:7168
	global_load_lds_dwordx4 v[206:207], off
	s_add_i32 m0, s17, 0xe000
	v_lshl_add_u64 v[206:207], s[6:7], 0, v[172:173]
	global_load_lds_dwordx4 v[206:207], off
	s_waitcnt vmcnt(8)
	s_waitcnt lgkmcnt(0)
	s_barrier
	s_setprio 1
	s_waitcnt lgkmcnt(0)
	v_mfma_f32_16x16x32_bf16 v[140:143], v[96:99], v[178:181], 0
	v_mfma_f32_16x16x32_bf16 v[136:139], v[120:123], v[178:181], 0
	v_mfma_f32_16x16x32_bf16 v[116:119], v[96:99], v[186:189], 0
	v_mfma_f32_16x16x32_bf16 v[112:115], v[120:123], v[186:189], 0
	v_mfma_f32_16x16x32_bf16 v[92:95], v[96:99], v[194:197], 0
	v_mfma_f32_16x16x32_bf16 v[88:91], v[120:123], v[194:197], 0
	v_mfma_f32_16x16x32_bf16 v[76:79], v[96:99], v[202:205], 0
	v_mfma_f32_16x16x32_bf16 v[72:75], v[120:123], v[202:205], 0
	v_mfma_f32_16x16x32_bf16 v[140:143], v[100:103], v[182:185], v[140:143]
	v_mfma_f32_16x16x32_bf16 v[136:139], v[124:127], v[182:185], v[136:139]
	v_mfma_f32_16x16x32_bf16 v[116:119], v[100:103], v[190:193], v[116:119]
	v_mfma_f32_16x16x32_bf16 v[112:115], v[124:127], v[190:193], v[112:115]
	v_mfma_f32_16x16x32_bf16 v[92:95], v[100:103], v[198:201], v[92:95]
	v_mfma_f32_16x16x32_bf16 v[88:91], v[124:127], v[198:201], v[88:91]
	v_mfma_f32_16x16x32_bf16 v[76:79], v[100:103], v[218:221], v[76:79]
	v_mfma_f32_16x16x32_bf16 v[72:75], v[124:127], v[218:221], v[72:75]
	s_setprio 0
	s_setprio 1
	v_mfma_f32_16x16x32_bf16 v[132:135], v[144:147], v[178:181], 0
	v_mfma_f32_16x16x32_bf16 v[128:131], v[152:155], v[178:181], 0
	v_mfma_f32_16x16x32_bf16 v[108:111], v[144:147], v[186:189], 0
	v_mfma_f32_16x16x32_bf16 v[104:107], v[152:155], v[186:189], 0
	v_mfma_f32_16x16x32_bf16 v[84:87], v[144:147], v[194:197], 0
	v_mfma_f32_16x16x32_bf16 v[80:83], v[152:155], v[194:197], 0
	v_mfma_f32_16x16x32_bf16 v[68:71], v[144:147], v[202:205], 0
	v_mfma_f32_16x16x32_bf16 v[64:67], v[152:155], v[202:205], 0
	v_mfma_f32_16x16x32_bf16 v[132:135], v[148:151], v[182:185], v[132:135]
	v_mfma_f32_16x16x32_bf16 v[128:131], v[156:159], v[182:185], v[128:131]
	v_mfma_f32_16x16x32_bf16 v[108:111], v[148:151], v[190:193], v[108:111]
	v_mfma_f32_16x16x32_bf16 v[104:107], v[156:159], v[190:193], v[104:107]
	s_setprio 2
	s_barrier
	s_add_i32 s79, s73, s61
	s_mov_b32 m0, s79
	v_lshl_add_u64 v[206:207], s[8:9], 0, v[162:163]
	global_load_lds_dwordx4 v[206:207], off
	v_mfma_f32_16x16x32_bf16 v[84:87], v[148:151], v[198:201], v[84:87]
	s_add_i32 m0, s79, 0x2000
	s_add_u32 s80, s8, 0x40000
	v_lshl_add_u64 v[222:223], s[8:9], 0, v[166:167]
	s_addc_u32 s81, s9, 0
	s_add_i32 s79, s74, s61
	global_load_lds_dwordx4 v[222:223], off
	v_mfma_f32_16x16x32_bf16 v[80:83], v[156:159], v[198:201], v[80:83]
	v_lshl_add_u64 v[224:225], s[80:81], 0, v[162:163]
	s_mov_b32 m0, s79
	v_lshl_add_u64 v[226:227], s[50:51], 0, v[164:165]
	global_load_lds_dwordx4 v[224:225], off
	v_mfma_f32_16x16x32_bf16 v[68:71], v[148:151], v[218:221], v[68:71]
	s_add_i32 m0, s79, 0x2000
	v_lshl_add_u64 v[224:225], s[80:81], 0, v[166:167]
	global_load_lds_dwordx4 v[224:225], off
	v_mfma_f32_16x16x32_bf16 v[64:67], v[156:159], v[218:221], v[64:67]
	ds_read_b128 v[178:181], v211 offset:16384
	ds_read_b128 v[182:185], v211 offset:17408
	ds_read_b128 v[186:189], v211 offset:18432
	ds_read_b128 v[190:193], v211 offset:19456
	ds_read_b128 v[194:197], v211 offset:20480
	ds_read_b128 v[198:201], v211 offset:21504
	ds_read_b128 v[202:205], v211 offset:22528
	ds_read_b128 v[218:221], v211 offset:23552
	s_mov_b32 m0, s17
	v_lshl_add_u64 v[224:225], s[50:51], 0, v[160:161]
	global_load_lds_dwordx4 v[224:225], off
	s_mov_b32 m0, s62
	s_nop 0
	global_load_lds_dwordx4 v[226:227], off
	s_waitcnt vmcnt(8)
	s_waitcnt lgkmcnt(0)
	s_barrier
	s_setprio 1
	s_waitcnt lgkmcnt(0)
	v_mfma_f32_16x16x32_bf16 v[60:63], v[96:99], v[178:181], 0
	v_mfma_f32_16x16x32_bf16 v[56:59], v[120:123], v[178:181], 0
	v_mfma_f32_16x16x32_bf16 v[44:47], v[96:99], v[186:189], 0
	v_mfma_f32_16x16x32_bf16 v[40:43], v[120:123], v[186:189], 0
	v_mfma_f32_16x16x32_bf16 v[28:31], v[96:99], v[194:197], 0
	v_mfma_f32_16x16x32_bf16 v[24:27], v[120:123], v[194:197], 0
	v_mfma_f32_16x16x32_bf16 v[12:15], v[96:99], v[202:205], 0
	v_mfma_f32_16x16x32_bf16 v[8:11], v[120:123], v[202:205], 0
	v_mfma_f32_16x16x32_bf16 v[60:63], v[100:103], v[182:185], v[60:63]
	v_mfma_f32_16x16x32_bf16 v[56:59], v[124:127], v[182:185], v[56:59]
	v_mfma_f32_16x16x32_bf16 v[44:47], v[100:103], v[190:193], v[44:47]
	v_mfma_f32_16x16x32_bf16 v[40:43], v[124:127], v[190:193], v[40:43]
	v_mfma_f32_16x16x32_bf16 v[28:31], v[100:103], v[198:201], v[28:31]
	v_mfma_f32_16x16x32_bf16 v[24:27], v[124:127], v[198:201], v[24:27]
	v_mfma_f32_16x16x32_bf16 v[12:15], v[100:103], v[218:221], v[12:15]
	v_mfma_f32_16x16x32_bf16 v[8:11], v[124:127], v[218:221], v[8:11]
	s_setprio 0
	s_setprio 1
	v_mfma_f32_16x16x32_bf16 v[52:55], v[144:147], v[178:181], 0
	v_mfma_f32_16x16x32_bf16 v[48:51], v[152:155], v[178:181], 0
	v_mfma_f32_16x16x32_bf16 v[36:39], v[144:147], v[186:189], 0
	v_mfma_f32_16x16x32_bf16 v[32:35], v[152:155], v[186:189], 0
	v_mfma_f32_16x16x32_bf16 v[20:23], v[144:147], v[194:197], 0
	v_mfma_f32_16x16x32_bf16 v[16:19], v[152:155], v[194:197], 0
	v_mfma_f32_16x16x32_bf16 v[4:7], v[144:147], v[202:205], 0
	v_mfma_f32_16x16x32_bf16 v[0:3], v[152:155], v[202:205], 0
	v_mfma_f32_16x16x32_bf16 v[52:55], v[148:151], v[182:185], v[52:55]
	v_mfma_f32_16x16x32_bf16 v[48:51], v[156:159], v[182:185], v[48:51]
	v_mfma_f32_16x16x32_bf16 v[36:39], v[148:151], v[190:193], v[36:39]
	v_mfma_f32_16x16x32_bf16 v[32:35], v[156:159], v[190:193], v[32:35]
	s_setprio 2
	s_barrier
	v_mfma_f32_16x16x32_bf16 v[20:23], v[148:151], v[198:201], v[20:23]
	v_mfma_f32_16x16x32_bf16 v[16:19], v[156:159], v[198:201], v[16:19]
	v_mfma_f32_16x16x32_bf16 v[4:7], v[148:151], v[218:221], v[4:7]
	v_mfma_f32_16x16x32_bf16 v[0:3], v[156:159], v[218:221], v[0:3]
	s_setprio 0
	s_add_i32 s79, 0, 0x18000
	s_add_i32 s80, 0, 0x1c000
	v_add_u32_e32 v124, s79, v208
	v_add_u32_e32 v156, s80, v208
	ds_read_b128 v[96:99], v124
	ds_read_b128 v[100:103], v124 offset:1024
	ds_read_b128 v[120:123], v124 offset:2048
	ds_read_b128 v[124:127], v124 offset:3072
	ds_read_b128 v[144:147], v156
	ds_read_b128 v[148:151], v156 offset:1024
	ds_read_b128 v[152:155], v156 offset:2048
	ds_read_b128 v[156:159], v156 offset:3072
	s_add_u32 s50, s50, 0x40000
	s_addc_u32 s51, s51, 0
	s_mov_b32 m0, s63
	v_lshl_add_u64 v[228:229], s[50:51], 0, v[160:161]
	ds_read_b128 v[178:181], v211 offset:32768
	ds_read_b128 v[182:185], v211 offset:33792
	ds_read_b128 v[186:189], v211 offset:34816
	ds_read_b128 v[190:193], v211 offset:35840
	ds_read_b128 v[194:197], v211 offset:36864
	ds_read_b128 v[198:201], v211 offset:37888
	ds_read_b128 v[202:205], v211 offset:38912
	ds_read_b128 v[218:221], v211 offset:39936
	global_load_lds_dwordx4 v[228:229], off
	s_mov_b32 m0, s64
	v_lshl_add_u64 v[228:229], s[50:51], 0, v[164:165]
	global_load_lds_dwordx4 v[228:229], off
	s_waitcnt vmcnt(8)
	s_waitcnt lgkmcnt(0)
	s_barrier
	s_setprio 1
	s_waitcnt lgkmcnt(0)
	v_mfma_f32_16x16x32_bf16 v[140:143], v[96:99], v[178:181], v[140:143]
	v_mfma_f32_16x16x32_bf16 v[136:139], v[120:123], v[178:181], v[136:139]
	v_mfma_f32_16x16x32_bf16 v[116:119], v[96:99], v[186:189], v[116:119]
	v_mfma_f32_16x16x32_bf16 v[112:115], v[120:123], v[186:189], v[112:115]
	v_mfma_f32_16x16x32_bf16 v[92:95], v[96:99], v[194:197], v[92:95]
	v_mfma_f32_16x16x32_bf16 v[88:91], v[120:123], v[194:197], v[88:91]
	v_mfma_f32_16x16x32_bf16 v[76:79], v[96:99], v[202:205], v[76:79]
	v_mfma_f32_16x16x32_bf16 v[72:75], v[120:123], v[202:205], v[72:75]
	v_mfma_f32_16x16x32_bf16 v[140:143], v[100:103], v[182:185], v[140:143]
	v_mfma_f32_16x16x32_bf16 v[136:139], v[124:127], v[182:185], v[136:139]
	v_mfma_f32_16x16x32_bf16 v[116:119], v[100:103], v[190:193], v[116:119]
	v_mfma_f32_16x16x32_bf16 v[112:115], v[124:127], v[190:193], v[112:115]
	v_mfma_f32_16x16x32_bf16 v[92:95], v[100:103], v[198:201], v[92:95]
	v_mfma_f32_16x16x32_bf16 v[88:91], v[124:127], v[198:201], v[88:91]
	v_mfma_f32_16x16x32_bf16 v[76:79], v[100:103], v[218:221], v[76:79]
	v_mfma_f32_16x16x32_bf16 v[72:75], v[124:127], v[218:221], v[72:75]
	s_setprio 0
	s_setprio 1
	v_mfma_f32_16x16x32_bf16 v[132:135], v[144:147], v[178:181], v[132:135]
	v_mfma_f32_16x16x32_bf16 v[128:131], v[152:155], v[178:181], v[128:131]
	v_mfma_f32_16x16x32_bf16 v[108:111], v[144:147], v[186:189], v[108:111]
	v_mfma_f32_16x16x32_bf16 v[104:107], v[152:155], v[186:189], v[104:107]
	v_mfma_f32_16x16x32_bf16 v[84:87], v[144:147], v[194:197], v[84:87]
	v_mfma_f32_16x16x32_bf16 v[80:83], v[152:155], v[194:197], v[80:83]
	v_mfma_f32_16x16x32_bf16 v[68:71], v[144:147], v[202:205], v[68:71]
	v_mfma_f32_16x16x32_bf16 v[64:67], v[152:155], v[202:205], v[64:67]
	v_mfma_f32_16x16x32_bf16 v[132:135], v[148:151], v[182:185], v[132:135]
	v_mfma_f32_16x16x32_bf16 v[128:131], v[156:159], v[182:185], v[128:131]
	v_mfma_f32_16x16x32_bf16 v[108:111], v[148:151], v[190:193], v[108:111]
	v_mfma_f32_16x16x32_bf16 v[104:107], v[156:159], v[190:193], v[104:107]
	s_setprio 2
	s_barrier
	s_add_i32 s50, s79, s61
	s_mov_b32 m0, s50
	v_lshl_add_u64 v[206:207], v[206:207], 0, s[36:37]
	global_load_lds_dwordx4 v[206:207], off
	v_mfma_f32_16x16x32_bf16 v[84:87], v[148:151], v[198:201], v[84:87]
	s_add_i32 m0, s50, 0x2000
	s_add_u32 s8, s8, 0x40080
	v_lshl_add_u64 v[206:207], v[222:223], 0, s[36:37]
	s_addc_u32 s9, s9, 0
	s_add_i32 s50, s80, s61
	global_load_lds_dwordx4 v[206:207], off
	v_mfma_f32_16x16x32_bf16 v[80:83], v[156:159], v[198:201], v[80:83]
	s_mov_b32 m0, s50
	v_lshl_add_u64 v[206:207], s[8:9], 0, v[162:163]
	global_load_lds_dwordx4 v[206:207], off
	v_mfma_f32_16x16x32_bf16 v[68:71], v[148:151], v[218:221], v[68:71]
	s_add_i32 m0, s50, 0x2000
	v_lshl_add_u64 v[206:207], s[8:9], 0, v[166:167]
	global_load_lds_dwordx4 v[206:207], off
	v_mfma_f32_16x16x32_bf16 v[64:67], v[156:159], v[218:221], v[64:67]
	ds_read_b128 v[178:181], v211 offset:49152
	ds_read_b128 v[182:185], v211 offset:50176
	ds_read_b128 v[186:189], v211 offset:51200
	ds_read_b128 v[190:193], v211 offset:52224
	ds_read_b128 v[194:197], v211 offset:53248
	ds_read_b128 v[198:201], v211 offset:54272
	ds_read_b128 v[202:205], v211 offset:55296
	ds_read_b128 v[218:221], v211 offset:56320
	s_mov_b32 m0, s68
	v_lshl_add_u64 v[206:207], v[224:225], 0, s[36:37]
	global_load_lds_dwordx4 v[206:207], off
	s_mov_b32 m0, s69
	v_lshl_add_u64 v[206:207], v[226:227], 0, s[36:37]
	global_load_lds_dwordx4 v[206:207], off
	s_waitcnt vmcnt(8)
	s_waitcnt lgkmcnt(0)
	s_barrier
	s_setprio 1
	s_waitcnt lgkmcnt(0)
	v_mfma_f32_16x16x32_bf16 v[60:63], v[96:99], v[178:181], v[60:63]
	v_mfma_f32_16x16x32_bf16 v[56:59], v[120:123], v[178:181], v[56:59]
	v_mfma_f32_16x16x32_bf16 v[44:47], v[96:99], v[186:189], v[44:47]
	v_mfma_f32_16x16x32_bf16 v[40:43], v[120:123], v[186:189], v[40:43]
	v_mfma_f32_16x16x32_bf16 v[28:31], v[96:99], v[194:197], v[28:31]
	v_mfma_f32_16x16x32_bf16 v[24:27], v[120:123], v[194:197], v[24:27]
	v_mfma_f32_16x16x32_bf16 v[12:15], v[96:99], v[202:205], v[12:15]
	v_mfma_f32_16x16x32_bf16 v[8:11], v[120:123], v[202:205], v[8:11]
	v_mfma_f32_16x16x32_bf16 v[60:63], v[100:103], v[182:185], v[60:63]
	v_mfma_f32_16x16x32_bf16 v[56:59], v[124:127], v[182:185], v[56:59]
	v_mfma_f32_16x16x32_bf16 v[44:47], v[100:103], v[190:193], v[44:47]
	v_mfma_f32_16x16x32_bf16 v[40:43], v[124:127], v[190:193], v[40:43]
	v_mfma_f32_16x16x32_bf16 v[28:31], v[100:103], v[198:201], v[28:31]
	v_mfma_f32_16x16x32_bf16 v[24:27], v[124:127], v[198:201], v[24:27]
	v_mfma_f32_16x16x32_bf16 v[12:15], v[100:103], v[218:221], v[12:15]
	v_mfma_f32_16x16x32_bf16 v[8:11], v[124:127], v[218:221], v[8:11]
	s_setprio 0
	s_setprio 1
	v_mfma_f32_16x16x32_bf16 v[52:55], v[144:147], v[178:181], v[52:55]
	v_mfma_f32_16x16x32_bf16 v[48:51], v[152:155], v[178:181], v[48:51]
	v_mfma_f32_16x16x32_bf16 v[36:39], v[144:147], v[186:189], v[36:39]
	v_mfma_f32_16x16x32_bf16 v[32:35], v[152:155], v[186:189], v[32:35]
	v_mfma_f32_16x16x32_bf16 v[20:23], v[144:147], v[194:197], v[20:23]
	v_mfma_f32_16x16x32_bf16 v[16:19], v[152:155], v[194:197], v[16:19]
	v_mfma_f32_16x16x32_bf16 v[4:7], v[144:147], v[202:205], v[4:7]
	v_mfma_f32_16x16x32_bf16 v[0:3], v[152:155], v[202:205], v[0:3]
	v_mfma_f32_16x16x32_bf16 v[52:55], v[148:151], v[182:185], v[52:55]
	v_mfma_f32_16x16x32_bf16 v[48:51], v[156:159], v[182:185], v[48:51]
	v_mfma_f32_16x16x32_bf16 v[36:39], v[148:151], v[190:193], v[36:39]
	v_mfma_f32_16x16x32_bf16 v[32:35], v[156:159], v[190:193], v[32:35]
	s_setprio 2
	s_barrier
	v_mfma_f32_16x16x32_bf16 v[20:23], v[148:151], v[198:201], v[20:23]
	v_mfma_f32_16x16x32_bf16 v[16:19], v[156:159], v[198:201], v[16:19]
	v_mfma_f32_16x16x32_bf16 v[4:7], v[148:151], v[218:221], v[4:7]
	v_mfma_f32_16x16x32_bf16 v[0:3], v[156:159], v[218:221], v[0:3]
	s_setprio 0
	s_add_i32 s78, s78, 2
	s_add_u32 s6, s6, 0x100
	s_addc_u32 s7, s7, 0
	s_add_u32 s56, s56, 0x100
	s_addc_u32 s57, s57, 0
	s_cmp_gt_u32 s78, 13
.LBB0_323:
	ds_read_b128 v[96:99], v209
	ds_read_b128 v[100:103], v209 offset:1024
	ds_read_b128 v[120:123], v209 offset:2048
	ds_read_b128 v[124:127], v209 offset:3072
	ds_read_b128 v[144:147], v210
	ds_read_b128 v[148:151], v210 offset:1024
	ds_read_b128 v[152:155], v210 offset:2048
	ds_read_b128 v[156:159], v210 offset:3072
	s_add_u32 s8, s6, 0xfffc0080
	s_addc_u32 s9, s7, -1
	s_cmp_eq_u32 s78, 12
	s_cselect_b32 s51, s18, s9
	s_cselect_b32 s50, s43, s8
	s_cselect_b32 s9, s45, s57
	s_cselect_b32 s8, s55, s56
	v_lshl_add_u64 v[206:207], s[6:7], 0, v[170:171]
	s_add_i32 m0, s17, 0xc000
	ds_read_b128 v[178:181], v211
	ds_read_b128 v[182:185], v211 offset:1024
	ds_read_b128 v[186:189], v211 offset:2048
	ds_read_b128 v[190:193], v211 offset:3072
	ds_read_b128 v[194:197], v211 offset:4096
	ds_read_b128 v[198:201], v211 offset:5120
	ds_read_b128 v[202:205], v211 offset:6144
	ds_read_b128 v[218:221], v211 offset:7168
	global_load_lds_dwordx4 v[206:207], off
	s_add_i32 m0, s17, 0xe000
	v_lshl_add_u64 v[206:207], s[6:7], 0, v[172:173]
	global_load_lds_dwordx4 v[206:207], off
	s_waitcnt vmcnt(8)
	s_waitcnt lgkmcnt(0)
	s_barrier
	s_setprio 1
	s_waitcnt lgkmcnt(0)
	v_mfma_f32_16x16x32_bf16 v[140:143], v[96:99], v[178:181], v[140:143]
	v_mfma_f32_16x16x32_bf16 v[136:139], v[120:123], v[178:181], v[136:139]
	v_mfma_f32_16x16x32_bf16 v[116:119], v[96:99], v[186:189], v[116:119]
	v_mfma_f32_16x16x32_bf16 v[112:115], v[120:123], v[186:189], v[112:115]
	v_mfma_f32_16x16x32_bf16 v[92:95], v[96:99], v[194:197], v[92:95]
	v_mfma_f32_16x16x32_bf16 v[88:91], v[120:123], v[194:197], v[88:91]
	v_mfma_f32_16x16x32_bf16 v[76:79], v[96:99], v[202:205], v[76:79]
	v_mfma_f32_16x16x32_bf16 v[72:75], v[120:123], v[202:205], v[72:75]
	v_mfma_f32_16x16x32_bf16 v[140:143], v[100:103], v[182:185], v[140:143]
	v_mfma_f32_16x16x32_bf16 v[136:139], v[124:127], v[182:185], v[136:139]
	v_mfma_f32_16x16x32_bf16 v[116:119], v[100:103], v[190:193], v[116:119]
	v_mfma_f32_16x16x32_bf16 v[112:115], v[124:127], v[190:193], v[112:115]
	v_mfma_f32_16x16x32_bf16 v[92:95], v[100:103], v[198:201], v[92:95]
	v_mfma_f32_16x16x32_bf16 v[88:91], v[124:127], v[198:201], v[88:91]
	v_mfma_f32_16x16x32_bf16 v[76:79], v[100:103], v[218:221], v[76:79]
	v_mfma_f32_16x16x32_bf16 v[72:75], v[124:127], v[218:221], v[72:75]
	s_setprio 0
	s_setprio 1
	v_mfma_f32_16x16x32_bf16 v[132:135], v[144:147], v[178:181], v[132:135]
	v_mfma_f32_16x16x32_bf16 v[128:131], v[152:155], v[178:181], v[128:131]
	v_mfma_f32_16x16x32_bf16 v[108:111], v[144:147], v[186:189], v[108:111]
	v_mfma_f32_16x16x32_bf16 v[104:107], v[152:155], v[186:189], v[104:107]
	v_mfma_f32_16x16x32_bf16 v[84:87], v[144:147], v[194:197], v[84:87]
	v_mfma_f32_16x16x32_bf16 v[80:83], v[152:155], v[194:197], v[80:83]
	v_mfma_f32_16x16x32_bf16 v[68:71], v[144:147], v[202:205], v[68:71]
	v_mfma_f32_16x16x32_bf16 v[64:67], v[152:155], v[202:205], v[64:67]
	v_mfma_f32_16x16x32_bf16 v[132:135], v[148:151], v[182:185], v[132:135]
	v_mfma_f32_16x16x32_bf16 v[128:131], v[156:159], v[182:185], v[128:131]
	v_mfma_f32_16x16x32_bf16 v[108:111], v[148:151], v[190:193], v[108:111]
	v_mfma_f32_16x16x32_bf16 v[104:107], v[156:159], v[190:193], v[104:107]
	s_setprio 2
	s_barrier
	s_add_i32 s79, s73, s61
	s_mov_b32 m0, s79
	v_lshl_add_u64 v[206:207], s[8:9], 0, v[162:163]
	global_load_lds_dwordx4 v[206:207], off
	v_mfma_f32_16x16x32_bf16 v[84:87], v[148:151], v[198:201], v[84:87]
	s_add_i32 m0, s79, 0x2000
	s_add_u32 s80, s8, 0x40000
	v_lshl_add_u64 v[222:223], s[8:9], 0, v[166:167]
	s_addc_u32 s81, s9, 0
	s_add_i32 s79, s74, s61
	global_load_lds_dwordx4 v[222:223], off
	v_mfma_f32_16x16x32_bf16 v[80:83], v[156:159], v[198:201], v[80:83]
	v_lshl_add_u64 v[224:225], s[80:81], 0, v[162:163]
	s_mov_b32 m0, s79
	v_lshl_add_u64 v[226:227], s[50:51], 0, v[164:165]
	global_load_lds_dwordx4 v[224:225], off
	v_mfma_f32_16x16x32_bf16 v[68:71], v[148:151], v[218:221], v[68:71]
	s_add_i32 m0, s79, 0x2000
	v_lshl_add_u64 v[224:225], s[80:81], 0, v[166:167]
	global_load_lds_dwordx4 v[224:225], off
	v_mfma_f32_16x16x32_bf16 v[64:67], v[156:159], v[218:221], v[64:67]
	ds_read_b128 v[178:181], v211 offset:16384
	ds_read_b128 v[182:185], v211 offset:17408
	ds_read_b128 v[186:189], v211 offset:18432
	ds_read_b128 v[190:193], v211 offset:19456
	ds_read_b128 v[194:197], v211 offset:20480
	ds_read_b128 v[198:201], v211 offset:21504
	ds_read_b128 v[202:205], v211 offset:22528
	ds_read_b128 v[218:221], v211 offset:23552
	s_mov_b32 m0, s17
	v_lshl_add_u64 v[224:225], s[50:51], 0, v[160:161]
	global_load_lds_dwordx4 v[224:225], off
	s_mov_b32 m0, s62
	s_nop 0
	global_load_lds_dwordx4 v[226:227], off
	s_waitcnt vmcnt(8)
	s_waitcnt lgkmcnt(0)
	s_barrier
	s_setprio 1
	s_waitcnt lgkmcnt(0)
	v_mfma_f32_16x16x32_bf16 v[60:63], v[96:99], v[178:181], v[60:63]
	v_mfma_f32_16x16x32_bf16 v[56:59], v[120:123], v[178:181], v[56:59]
	v_mfma_f32_16x16x32_bf16 v[44:47], v[96:99], v[186:189], v[44:47]
	v_mfma_f32_16x16x32_bf16 v[40:43], v[120:123], v[186:189], v[40:43]
	v_mfma_f32_16x16x32_bf16 v[28:31], v[96:99], v[194:197], v[28:31]
	v_mfma_f32_16x16x32_bf16 v[24:27], v[120:123], v[194:197], v[24:27]
	v_mfma_f32_16x16x32_bf16 v[12:15], v[96:99], v[202:205], v[12:15]
	v_mfma_f32_16x16x32_bf16 v[8:11], v[120:123], v[202:205], v[8:11]
	v_mfma_f32_16x16x32_bf16 v[60:63], v[100:103], v[182:185], v[60:63]
	v_mfma_f32_16x16x32_bf16 v[56:59], v[124:127], v[182:185], v[56:59]
	v_mfma_f32_16x16x32_bf16 v[44:47], v[100:103], v[190:193], v[44:47]
	v_mfma_f32_16x16x32_bf16 v[40:43], v[124:127], v[190:193], v[40:43]
	v_mfma_f32_16x16x32_bf16 v[28:31], v[100:103], v[198:201], v[28:31]
	v_mfma_f32_16x16x32_bf16 v[24:27], v[124:127], v[198:201], v[24:27]
	v_mfma_f32_16x16x32_bf16 v[12:15], v[100:103], v[218:221], v[12:15]
	v_mfma_f32_16x16x32_bf16 v[8:11], v[124:127], v[218:221], v[8:11]
	s_setprio 0
	s_setprio 1
	v_mfma_f32_16x16x32_bf16 v[52:55], v[144:147], v[178:181], v[52:55]
	v_mfma_f32_16x16x32_bf16 v[48:51], v[152:155], v[178:181], v[48:51]
	v_mfma_f32_16x16x32_bf16 v[36:39], v[144:147], v[186:189], v[36:39]
	v_mfma_f32_16x16x32_bf16 v[32:35], v[152:155], v[186:189], v[32:35]
	v_mfma_f32_16x16x32_bf16 v[20:23], v[144:147], v[194:197], v[20:23]
	v_mfma_f32_16x16x32_bf16 v[16:19], v[152:155], v[194:197], v[16:19]
	v_mfma_f32_16x16x32_bf16 v[4:7], v[144:147], v[202:205], v[4:7]
	v_mfma_f32_16x16x32_bf16 v[0:3], v[152:155], v[202:205], v[0:3]
	v_mfma_f32_16x16x32_bf16 v[52:55], v[148:151], v[182:185], v[52:55]
	v_mfma_f32_16x16x32_bf16 v[48:51], v[156:159], v[182:185], v[48:51]
	v_mfma_f32_16x16x32_bf16 v[36:39], v[148:151], v[190:193], v[36:39]
	v_mfma_f32_16x16x32_bf16 v[32:35], v[156:159], v[190:193], v[32:35]
	s_setprio 2
	s_barrier
	v_mfma_f32_16x16x32_bf16 v[20:23], v[148:151], v[198:201], v[20:23]
	v_mfma_f32_16x16x32_bf16 v[16:19], v[156:159], v[198:201], v[16:19]
	v_mfma_f32_16x16x32_bf16 v[4:7], v[148:151], v[218:221], v[4:7]
	v_mfma_f32_16x16x32_bf16 v[0:3], v[156:159], v[218:221], v[0:3]
	s_setprio 0
	s_add_i32 s79, 0, 0x18000
	s_add_i32 s80, 0, 0x1c000
	v_add_u32_e32 v124, s79, v208
	v_add_u32_e32 v156, s80, v208
	ds_read_b128 v[96:99], v124
	ds_read_b128 v[100:103], v124 offset:1024
	ds_read_b128 v[120:123], v124 offset:2048
	ds_read_b128 v[124:127], v124 offset:3072
	ds_read_b128 v[144:147], v156
	ds_read_b128 v[148:151], v156 offset:1024
	ds_read_b128 v[152:155], v156 offset:2048
	ds_read_b128 v[156:159], v156 offset:3072
	s_add_u32 s50, s50, 0x40000
	s_addc_u32 s51, s51, 0
	s_mov_b32 m0, s63
	v_lshl_add_u64 v[228:229], s[50:51], 0, v[160:161]
	ds_read_b128 v[178:181], v211 offset:32768
	ds_read_b128 v[182:185], v211 offset:33792
	ds_read_b128 v[186:189], v211 offset:34816
	ds_read_b128 v[190:193], v211 offset:35840
	ds_read_b128 v[194:197], v211 offset:36864
	ds_read_b128 v[198:201], v211 offset:37888
	ds_read_b128 v[202:205], v211 offset:38912
	ds_read_b128 v[218:221], v211 offset:39936
	global_load_lds_dwordx4 v[228:229], off
	s_mov_b32 m0, s64
	v_lshl_add_u64 v[228:229], s[50:51], 0, v[164:165]
	global_load_lds_dwordx4 v[228:229], off
	s_waitcnt vmcnt(8)
	s_waitcnt lgkmcnt(0)
	s_barrier
	s_setprio 1
	s_waitcnt lgkmcnt(0)
	v_mfma_f32_16x16x32_bf16 v[140:143], v[96:99], v[178:181], v[140:143]
	v_mfma_f32_16x16x32_bf16 v[136:139], v[120:123], v[178:181], v[136:139]
	v_mfma_f32_16x16x32_bf16 v[116:119], v[96:99], v[186:189], v[116:119]
	v_mfma_f32_16x16x32_bf16 v[112:115], v[120:123], v[186:189], v[112:115]
	v_mfma_f32_16x16x32_bf16 v[92:95], v[96:99], v[194:197], v[92:95]
	v_mfma_f32_16x16x32_bf16 v[88:91], v[120:123], v[194:197], v[88:91]
	v_mfma_f32_16x16x32_bf16 v[76:79], v[96:99], v[202:205], v[76:79]
	v_mfma_f32_16x16x32_bf16 v[72:75], v[120:123], v[202:205], v[72:75]
	v_mfma_f32_16x16x32_bf16 v[140:143], v[100:103], v[182:185], v[140:143]
	v_mfma_f32_16x16x32_bf16 v[136:139], v[124:127], v[182:185], v[136:139]
	v_mfma_f32_16x16x32_bf16 v[116:119], v[100:103], v[190:193], v[116:119]
	v_mfma_f32_16x16x32_bf16 v[112:115], v[124:127], v[190:193], v[112:115]
	v_mfma_f32_16x16x32_bf16 v[92:95], v[100:103], v[198:201], v[92:95]
	v_mfma_f32_16x16x32_bf16 v[88:91], v[124:127], v[198:201], v[88:91]
	v_mfma_f32_16x16x32_bf16 v[76:79], v[100:103], v[218:221], v[76:79]
	v_mfma_f32_16x16x32_bf16 v[72:75], v[124:127], v[218:221], v[72:75]
	s_setprio 0
	s_setprio 1
	v_mfma_f32_16x16x32_bf16 v[132:135], v[144:147], v[178:181], v[132:135]
	v_mfma_f32_16x16x32_bf16 v[128:131], v[152:155], v[178:181], v[128:131]
	v_mfma_f32_16x16x32_bf16 v[108:111], v[144:147], v[186:189], v[108:111]
	v_mfma_f32_16x16x32_bf16 v[104:107], v[152:155], v[186:189], v[104:107]
	v_mfma_f32_16x16x32_bf16 v[84:87], v[144:147], v[194:197], v[84:87]
	v_mfma_f32_16x16x32_bf16 v[80:83], v[152:155], v[194:197], v[80:83]
	v_mfma_f32_16x16x32_bf16 v[68:71], v[144:147], v[202:205], v[68:71]
	v_mfma_f32_16x16x32_bf16 v[64:67], v[152:155], v[202:205], v[64:67]
	v_mfma_f32_16x16x32_bf16 v[132:135], v[148:151], v[182:185], v[132:135]
	v_mfma_f32_16x16x32_bf16 v[128:131], v[156:159], v[182:185], v[128:131]
	v_mfma_f32_16x16x32_bf16 v[108:111], v[148:151], v[190:193], v[108:111]
	v_mfma_f32_16x16x32_bf16 v[104:107], v[156:159], v[190:193], v[104:107]
	s_setprio 2
	s_barrier
	s_add_i32 s50, s79, s61
	s_mov_b32 m0, s50
	v_lshl_add_u64 v[206:207], v[206:207], 0, s[36:37]
	global_load_lds_dwordx4 v[206:207], off
	v_mfma_f32_16x16x32_bf16 v[84:87], v[148:151], v[198:201], v[84:87]
	s_add_i32 m0, s50, 0x2000
	s_add_u32 s8, s8, 0x40080
	v_lshl_add_u64 v[206:207], v[222:223], 0, s[36:37]
	s_addc_u32 s9, s9, 0
	s_add_i32 s50, s80, s61
	global_load_lds_dwordx4 v[206:207], off
	v_mfma_f32_16x16x32_bf16 v[80:83], v[156:159], v[198:201], v[80:83]
	s_mov_b32 m0, s50
	v_lshl_add_u64 v[206:207], s[8:9], 0, v[162:163]
	global_load_lds_dwordx4 v[206:207], off
	v_mfma_f32_16x16x32_bf16 v[68:71], v[148:151], v[218:221], v[68:71]
	s_add_i32 m0, s50, 0x2000
	v_lshl_add_u64 v[206:207], s[8:9], 0, v[166:167]
	global_load_lds_dwordx4 v[206:207], off
	v_mfma_f32_16x16x32_bf16 v[64:67], v[156:159], v[218:221], v[64:67]
	ds_read_b128 v[178:181], v211 offset:49152
	ds_read_b128 v[182:185], v211 offset:50176
	ds_read_b128 v[186:189], v211 offset:51200
	ds_read_b128 v[190:193], v211 offset:52224
	ds_read_b128 v[194:197], v211 offset:53248
	ds_read_b128 v[198:201], v211 offset:54272
	ds_read_b128 v[202:205], v211 offset:55296
	ds_read_b128 v[218:221], v211 offset:56320
	s_mov_b32 m0, s68
	v_lshl_add_u64 v[206:207], v[224:225], 0, s[36:37]
	global_load_lds_dwordx4 v[206:207], off
	s_mov_b32 m0, s69
	v_lshl_add_u64 v[206:207], v[226:227], 0, s[36:37]
	global_load_lds_dwordx4 v[206:207], off
	s_waitcnt vmcnt(8)
	s_waitcnt lgkmcnt(0)
	s_barrier
	s_setprio 1
	s_waitcnt lgkmcnt(0)
	v_mfma_f32_16x16x32_bf16 v[60:63], v[96:99], v[178:181], v[60:63]
	v_mfma_f32_16x16x32_bf16 v[56:59], v[120:123], v[178:181], v[56:59]
	v_mfma_f32_16x16x32_bf16 v[44:47], v[96:99], v[186:189], v[44:47]
	v_mfma_f32_16x16x32_bf16 v[40:43], v[120:123], v[186:189], v[40:43]
	v_mfma_f32_16x16x32_bf16 v[28:31], v[96:99], v[194:197], v[28:31]
	v_mfma_f32_16x16x32_bf16 v[24:27], v[120:123], v[194:197], v[24:27]
	v_mfma_f32_16x16x32_bf16 v[12:15], v[96:99], v[202:205], v[12:15]
	v_mfma_f32_16x16x32_bf16 v[8:11], v[120:123], v[202:205], v[8:11]
	v_mfma_f32_16x16x32_bf16 v[60:63], v[100:103], v[182:185], v[60:63]
	v_mfma_f32_16x16x32_bf16 v[56:59], v[124:127], v[182:185], v[56:59]
	v_mfma_f32_16x16x32_bf16 v[44:47], v[100:103], v[190:193], v[44:47]
	v_mfma_f32_16x16x32_bf16 v[40:43], v[124:127], v[190:193], v[40:43]
	v_mfma_f32_16x16x32_bf16 v[28:31], v[100:103], v[198:201], v[28:31]
	v_mfma_f32_16x16x32_bf16 v[24:27], v[124:127], v[198:201], v[24:27]
	v_mfma_f32_16x16x32_bf16 v[12:15], v[100:103], v[218:221], v[12:15]
	v_mfma_f32_16x16x32_bf16 v[8:11], v[124:127], v[218:221], v[8:11]
	s_setprio 0
	s_setprio 1
	v_mfma_f32_16x16x32_bf16 v[52:55], v[144:147], v[178:181], v[52:55]
	v_mfma_f32_16x16x32_bf16 v[48:51], v[152:155], v[178:181], v[48:51]
	v_mfma_f32_16x16x32_bf16 v[36:39], v[144:147], v[186:189], v[36:39]
	v_mfma_f32_16x16x32_bf16 v[32:35], v[152:155], v[186:189], v[32:35]
	v_mfma_f32_16x16x32_bf16 v[20:23], v[144:147], v[194:197], v[20:23]
	v_mfma_f32_16x16x32_bf16 v[16:19], v[152:155], v[194:197], v[16:19]
	v_mfma_f32_16x16x32_bf16 v[4:7], v[144:147], v[202:205], v[4:7]
	v_mfma_f32_16x16x32_bf16 v[0:3], v[152:155], v[202:205], v[0:3]
	v_mfma_f32_16x16x32_bf16 v[52:55], v[148:151], v[182:185], v[52:55]
	v_mfma_f32_16x16x32_bf16 v[48:51], v[156:159], v[182:185], v[48:51]
	v_mfma_f32_16x16x32_bf16 v[36:39], v[148:151], v[190:193], v[36:39]
	v_mfma_f32_16x16x32_bf16 v[32:35], v[156:159], v[190:193], v[32:35]
	s_setprio 2
	s_barrier
	v_mfma_f32_16x16x32_bf16 v[20:23], v[148:151], v[198:201], v[20:23]
	v_mfma_f32_16x16x32_bf16 v[16:19], v[156:159], v[198:201], v[16:19]
	v_mfma_f32_16x16x32_bf16 v[4:7], v[148:151], v[218:221], v[4:7]
	v_mfma_f32_16x16x32_bf16 v[0:3], v[156:159], v[218:221], v[0:3]
	s_setprio 0
	s_add_i32 s78, s78, 2
	s_add_u32 s6, s6, 0x100
	s_addc_u32 s7, s7, 0
	s_add_u32 s56, s56, 0x100
	s_addc_u32 s57, s57, 0
	s_cmp_gt_u32 s78, 13
	s_cbranch_scc0 .LBB0_323

.LBB0_783:
	s_ashr_i32 s23, s22, 31
	s_lshl_b64 s[26:27], s[22:23], 19
	s_add_u32 s26, s43, s26
	s_addc_u32 s27, s44, s27
	s_and_b64 s[28:29], s[4:5], exec
	s_cselect_b32 s23, s27, s37
	s_cselect_b32 s31, s26, s36
	s_ashr_i32 s25, s24, 31
	s_lshl_b64 s[28:29], s[24:25], 19
	s_add_u32 s28, s45, s28
	s_addc_u32 s29, s46, s29
	s_and_b64 s[40:41], s[4:5], exec
	s_cselect_b32 s25, s29, s39
	s_cselect_b32 s62, s28, s38
	s_add_u32 s36, s36, 0x40080
	s_addc_u32 s37, s37, 0
	s_add_u32 s63, s38, 0x100
	s_addc_u32 s64, s39, 0
	s_mov_b32 s65, -2
	ds_read_b128 v[144:147], v163
	ds_read_b128 v[148:151], v163 offset:1024
	ds_read_b128 v[152:155], v163 offset:2048
	ds_read_b128 v[156:159], v163 offset:3072
	ds_read_b128 v[168:171], v164
	ds_read_b128 v[172:175], v164 offset:1024
	ds_read_b128 v[176:179], v164 offset:2048
	ds_read_b128 v[180:183], v164 offset:3072
	s_add_u32 s38, s36, 0xfffc0080
	s_addc_u32 s39, s37, -1
	s_cmp_eq_u32 s65, 12
	s_cselect_b32 s41, s23, s39
	s_cselect_b32 s40, s31, s38
	s_cselect_b32 s39, s25, s64
	s_cselect_b32 s38, s62, s63
	v_lshl_add_u64 v[160:161], s[36:37], 0, v[136:137]
	s_add_i32 m0, s50, 0xc000
	ds_read_b128 v[184:187], v165
	ds_read_b128 v[188:191], v165 offset:1024
	ds_read_b128 v[192:195], v165 offset:2048
	ds_read_b128 v[196:199], v165 offset:3072
	ds_read_b128 v[200:203], v165 offset:4096
	ds_read_b128 v[204:207], v165 offset:5120
	ds_read_b128 v[208:211], v165 offset:6144
	ds_read_b128 v[212:215], v165 offset:7168
	global_load_lds_dwordx4 v[160:161], off
	s_add_i32 m0, s50, 0xe000
	v_lshl_add_u64 v[160:161], s[36:37], 0, v[138:139]
	global_load_lds_dwordx4 v[160:161], off
	s_waitcnt vmcnt(8)
	s_waitcnt lgkmcnt(0)
	s_barrier
	s_setprio 1
	s_waitcnt lgkmcnt(0)
	v_mfma_f32_16x16x32_bf16 v[124:127], v[144:147], v[184:187], 0
	v_mfma_f32_16x16x32_bf16 v[120:123], v[152:155], v[184:187], 0
	v_mfma_f32_16x16x32_bf16 v[108:111], v[144:147], v[192:195], 0
	v_mfma_f32_16x16x32_bf16 v[104:107], v[152:155], v[192:195], 0
	v_mfma_f32_16x16x32_bf16 v[92:95], v[144:147], v[200:203], 0
	v_mfma_f32_16x16x32_bf16 v[88:91], v[152:155], v[200:203], 0
	v_mfma_f32_16x16x32_bf16 v[76:79], v[144:147], v[208:211], 0
	v_mfma_f32_16x16x32_bf16 v[72:75], v[152:155], v[208:211], 0
	v_mfma_f32_16x16x32_bf16 v[124:127], v[148:151], v[188:191], v[124:127]
	v_mfma_f32_16x16x32_bf16 v[120:123], v[156:159], v[188:191], v[120:123]
	v_mfma_f32_16x16x32_bf16 v[108:111], v[148:151], v[196:199], v[108:111]
	v_mfma_f32_16x16x32_bf16 v[104:107], v[156:159], v[196:199], v[104:107]
	v_mfma_f32_16x16x32_bf16 v[92:95], v[148:151], v[204:207], v[92:95]
	v_mfma_f32_16x16x32_bf16 v[88:91], v[156:159], v[204:207], v[88:91]
	v_mfma_f32_16x16x32_bf16 v[76:79], v[148:151], v[212:215], v[76:79]
	v_mfma_f32_16x16x32_bf16 v[72:75], v[156:159], v[212:215], v[72:75]
	s_setprio 0
	s_setprio 1
	v_mfma_f32_16x16x32_bf16 v[116:119], v[168:171], v[184:187], 0
	v_mfma_f32_16x16x32_bf16 v[112:115], v[176:179], v[184:187], 0
	v_mfma_f32_16x16x32_bf16 v[100:103], v[168:171], v[192:195], 0
	v_mfma_f32_16x16x32_bf16 v[96:99], v[176:179], v[192:195], 0
	v_mfma_f32_16x16x32_bf16 v[84:87], v[168:171], v[200:203], 0
	v_mfma_f32_16x16x32_bf16 v[80:83], v[176:179], v[200:203], 0
	v_mfma_f32_16x16x32_bf16 v[68:71], v[168:171], v[208:211], 0
	v_mfma_f32_16x16x32_bf16 v[64:67], v[176:179], v[208:211], 0
	v_mfma_f32_16x16x32_bf16 v[116:119], v[172:175], v[188:191], v[116:119]
	v_mfma_f32_16x16x32_bf16 v[112:115], v[180:183], v[188:191], v[112:115]
	v_mfma_f32_16x16x32_bf16 v[100:103], v[172:175], v[196:199], v[100:103]
	v_mfma_f32_16x16x32_bf16 v[96:99], v[180:183], v[196:199], v[96:99]
	s_setprio 2
	s_barrier
	s_add_i32 s66, s59, s47
	s_mov_b32 m0, s66
	v_lshl_add_u64 v[160:161], s[38:39], 0, v[132:133]
	global_load_lds_dwordx4 v[160:161], off
	v_mfma_f32_16x16x32_bf16 v[84:87], v[172:175], v[204:207], v[84:87]
	s_add_i32 m0, s66, 0x2000
	s_add_u32 s66, s38, 0x40000
	v_lshl_add_u64 v[216:217], s[38:39], 0, v[128:129]
	s_addc_u32 s67, s39, 0
	s_add_i32 s68, s60, s47
	global_load_lds_dwordx4 v[216:217], off
	v_mfma_f32_16x16x32_bf16 v[80:83], v[180:183], v[204:207], v[80:83]
	v_lshl_add_u64 v[218:219], s[66:67], 0, v[132:133]
	s_mov_b32 m0, s68
	v_lshl_add_u64 v[220:221], s[40:41], 0, v[130:131]
	global_load_lds_dwordx4 v[218:219], off
	v_mfma_f32_16x16x32_bf16 v[68:71], v[172:175], v[212:215], v[68:71]
	s_add_i32 m0, s68, 0x2000
	v_lshl_add_u64 v[218:219], s[66:67], 0, v[128:129]
	global_load_lds_dwordx4 v[218:219], off
	v_mfma_f32_16x16x32_bf16 v[64:67], v[180:183], v[212:215], v[64:67]
	ds_read_b128 v[184:187], v165 offset:16384
	ds_read_b128 v[188:191], v165 offset:17408
	ds_read_b128 v[192:195], v165 offset:18432
	ds_read_b128 v[196:199], v165 offset:19456
	ds_read_b128 v[200:203], v165 offset:20480
	ds_read_b128 v[204:207], v165 offset:21504
	ds_read_b128 v[208:211], v165 offset:22528
	ds_read_b128 v[212:215], v165 offset:23552
	s_mov_b32 m0, s50
	v_lshl_add_u64 v[218:219], s[40:41], 0, v[134:135]
	global_load_lds_dwordx4 v[218:219], off
	s_mov_b32 m0, s51
	s_nop 0
	global_load_lds_dwordx4 v[220:221], off
	s_waitcnt vmcnt(8)
	s_waitcnt lgkmcnt(0)
	s_barrier
	s_setprio 1
	s_waitcnt lgkmcnt(0)
	v_mfma_f32_16x16x32_bf16 v[60:63], v[144:147], v[184:187], 0
	v_mfma_f32_16x16x32_bf16 v[56:59], v[152:155], v[184:187], 0
	v_mfma_f32_16x16x32_bf16 v[44:47], v[144:147], v[192:195], 0
	v_mfma_f32_16x16x32_bf16 v[40:43], v[152:155], v[192:195], 0
	v_mfma_f32_16x16x32_bf16 v[28:31], v[144:147], v[200:203], 0
	v_mfma_f32_16x16x32_bf16 v[24:27], v[152:155], v[200:203], 0
	v_mfma_f32_16x16x32_bf16 v[12:15], v[144:147], v[208:211], 0
	v_mfma_f32_16x16x32_bf16 v[8:11], v[152:155], v[208:211], 0
	v_mfma_f32_16x16x32_bf16 v[60:63], v[148:151], v[188:191], v[60:63]
	v_mfma_f32_16x16x32_bf16 v[56:59], v[156:159], v[188:191], v[56:59]
	v_mfma_f32_16x16x32_bf16 v[44:47], v[148:151], v[196:199], v[44:47]
	v_mfma_f32_16x16x32_bf16 v[40:43], v[156:159], v[196:199], v[40:43]
	v_mfma_f32_16x16x32_bf16 v[28:31], v[148:151], v[204:207], v[28:31]
	v_mfma_f32_16x16x32_bf16 v[24:27], v[156:159], v[204:207], v[24:27]
	v_mfma_f32_16x16x32_bf16 v[12:15], v[148:151], v[212:215], v[12:15]
	v_mfma_f32_16x16x32_bf16 v[8:11], v[156:159], v[212:215], v[8:11]
	s_setprio 0
	s_setprio 1
	v_mfma_f32_16x16x32_bf16 v[52:55], v[168:171], v[184:187], 0
	v_mfma_f32_16x16x32_bf16 v[48:51], v[176:179], v[184:187], 0
	v_mfma_f32_16x16x32_bf16 v[36:39], v[168:171], v[192:195], 0
	v_mfma_f32_16x16x32_bf16 v[32:35], v[176:179], v[192:195], 0
	v_mfma_f32_16x16x32_bf16 v[20:23], v[168:171], v[200:203], 0
	v_mfma_f32_16x16x32_bf16 v[16:19], v[176:179], v[200:203], 0
	v_mfma_f32_16x16x32_bf16 v[4:7], v[168:171], v[208:211], 0
	v_mfma_f32_16x16x32_bf16 v[0:3], v[176:179], v[208:211], 0
	v_mfma_f32_16x16x32_bf16 v[52:55], v[172:175], v[188:191], v[52:55]
	v_mfma_f32_16x16x32_bf16 v[48:51], v[180:183], v[188:191], v[48:51]
	v_mfma_f32_16x16x32_bf16 v[36:39], v[172:175], v[196:199], v[36:39]
	v_mfma_f32_16x16x32_bf16 v[32:35], v[180:183], v[196:199], v[32:35]
	s_setprio 2
	s_barrier
	v_mfma_f32_16x16x32_bf16 v[20:23], v[172:175], v[204:207], v[20:23]
	v_mfma_f32_16x16x32_bf16 v[16:19], v[180:183], v[204:207], v[16:19]
	v_mfma_f32_16x16x32_bf16 v[4:7], v[172:175], v[212:215], v[4:7]
	v_mfma_f32_16x16x32_bf16 v[0:3], v[180:183], v[212:215], v[0:3]
	s_setprio 0
	s_add_i32 s66, 0, 0x18000
	s_add_i32 s67, 0, 0x1c000
	v_add_u32_e32 v156, s66, v162
	v_add_u32_e32 v167, s67, v162
	ds_read_b128 v[144:147], v156
	ds_read_b128 v[148:151], v156 offset:1024
	ds_read_b128 v[152:155], v156 offset:2048
	ds_read_b128 v[156:159], v156 offset:3072
	ds_read_b128 v[168:171], v167
	ds_read_b128 v[172:175], v167 offset:1024
	ds_read_b128 v[176:179], v167 offset:2048
	ds_read_b128 v[180:183], v167 offset:3072
	s_add_u32 s40, s40, 0x40000
	s_addc_u32 s41, s41, 0
	s_mov_b32 m0, s54
	v_lshl_add_u64 v[222:223], s[40:41], 0, v[134:135]
	ds_read_b128 v[184:187], v165 offset:32768
	ds_read_b128 v[188:191], v165 offset:33792
	ds_read_b128 v[192:195], v165 offset:34816
	ds_read_b128 v[196:199], v165 offset:35840
	ds_read_b128 v[200:203], v165 offset:36864
	ds_read_b128 v[204:207], v165 offset:37888
	ds_read_b128 v[208:211], v165 offset:38912
	ds_read_b128 v[212:215], v165 offset:39936
	global_load_lds_dwordx4 v[222:223], off
	s_mov_b32 m0, s55
	v_lshl_add_u64 v[222:223], s[40:41], 0, v[130:131]
	global_load_lds_dwordx4 v[222:223], off
	s_waitcnt vmcnt(8)
	s_waitcnt lgkmcnt(0)
	s_barrier
	s_setprio 1
	s_waitcnt lgkmcnt(0)
	v_mfma_f32_16x16x32_bf16 v[124:127], v[144:147], v[184:187], v[124:127]
	v_mfma_f32_16x16x32_bf16 v[120:123], v[152:155], v[184:187], v[120:123]
	v_mfma_f32_16x16x32_bf16 v[108:111], v[144:147], v[192:195], v[108:111]
	v_mfma_f32_16x16x32_bf16 v[104:107], v[152:155], v[192:195], v[104:107]
	v_mfma_f32_16x16x32_bf16 v[92:95], v[144:147], v[200:203], v[92:95]
	v_mfma_f32_16x16x32_bf16 v[88:91], v[152:155], v[200:203], v[88:91]
	v_mfma_f32_16x16x32_bf16 v[76:79], v[144:147], v[208:211], v[76:79]
	v_mfma_f32_16x16x32_bf16 v[72:75], v[152:155], v[208:211], v[72:75]
	v_mfma_f32_16x16x32_bf16 v[124:127], v[148:151], v[188:191], v[124:127]
	v_mfma_f32_16x16x32_bf16 v[120:123], v[156:159], v[188:191], v[120:123]
	v_mfma_f32_16x16x32_bf16 v[108:111], v[148:151], v[196:199], v[108:111]
	v_mfma_f32_16x16x32_bf16 v[104:107], v[156:159], v[196:199], v[104:107]
	v_mfma_f32_16x16x32_bf16 v[92:95], v[148:151], v[204:207], v[92:95]
	v_mfma_f32_16x16x32_bf16 v[88:91], v[156:159], v[204:207], v[88:91]
	v_mfma_f32_16x16x32_bf16 v[76:79], v[148:151], v[212:215], v[76:79]
	v_mfma_f32_16x16x32_bf16 v[72:75], v[156:159], v[212:215], v[72:75]
	s_setprio 0
	s_setprio 1
	v_mfma_f32_16x16x32_bf16 v[116:119], v[168:171], v[184:187], v[116:119]
	v_mfma_f32_16x16x32_bf16 v[112:115], v[176:179], v[184:187], v[112:115]
	v_mfma_f32_16x16x32_bf16 v[100:103], v[168:171], v[192:195], v[100:103]
	v_mfma_f32_16x16x32_bf16 v[96:99], v[176:179], v[192:195], v[96:99]
	v_mfma_f32_16x16x32_bf16 v[84:87], v[168:171], v[200:203], v[84:87]
	v_mfma_f32_16x16x32_bf16 v[80:83], v[176:179], v[200:203], v[80:83]
	v_mfma_f32_16x16x32_bf16 v[68:71], v[168:171], v[208:211], v[68:71]
	v_mfma_f32_16x16x32_bf16 v[64:67], v[176:179], v[208:211], v[64:67]
	v_mfma_f32_16x16x32_bf16 v[116:119], v[172:175], v[188:191], v[116:119]
	v_mfma_f32_16x16x32_bf16 v[112:115], v[180:183], v[188:191], v[112:115]
	v_mfma_f32_16x16x32_bf16 v[100:103], v[172:175], v[196:199], v[100:103]
	v_mfma_f32_16x16x32_bf16 v[96:99], v[180:183], v[196:199], v[96:99]
	s_setprio 2
	s_barrier
	s_add_i32 s40, s66, s47
	s_mov_b32 m0, s40
	v_lshl_add_u64 v[160:161], v[160:161], 0, s[16:17]
	global_load_lds_dwordx4 v[160:161], off
	v_mfma_f32_16x16x32_bf16 v[84:87], v[172:175], v[204:207], v[84:87]
	s_add_i32 m0, s40, 0x2000
	s_add_u32 s38, s38, 0x40080
	v_lshl_add_u64 v[160:161], v[216:217], 0, s[16:17]
	s_addc_u32 s39, s39, 0
	s_add_i32 s40, s67, s47
	global_load_lds_dwordx4 v[160:161], off
	v_mfma_f32_16x16x32_bf16 v[80:83], v[180:183], v[204:207], v[80:83]
	s_mov_b32 m0, s40
	v_lshl_add_u64 v[160:161], s[38:39], 0, v[132:133]
	global_load_lds_dwordx4 v[160:161], off
	v_mfma_f32_16x16x32_bf16 v[68:71], v[172:175], v[212:215], v[68:71]
	s_add_i32 m0, s40, 0x2000
	v_lshl_add_u64 v[160:161], s[38:39], 0, v[128:129]
	global_load_lds_dwordx4 v[160:161], off
	v_mfma_f32_16x16x32_bf16 v[64:67], v[180:183], v[212:215], v[64:67]
	ds_read_b128 v[184:187], v165 offset:49152
	ds_read_b128 v[188:191], v165 offset:50176
	ds_read_b128 v[192:195], v165 offset:51200
	ds_read_b128 v[196:199], v165 offset:52224
	ds_read_b128 v[200:203], v165 offset:53248
	ds_read_b128 v[204:207], v165 offset:54272
	ds_read_b128 v[208:211], v165 offset:55296
	ds_read_b128 v[212:215], v165 offset:56320
	s_mov_b32 m0, s57
	v_lshl_add_u64 v[160:161], v[218:219], 0, s[16:17]
	global_load_lds_dwordx4 v[160:161], off
	s_mov_b32 m0, s58
	v_lshl_add_u64 v[160:161], v[220:221], 0, s[16:17]
	global_load_lds_dwordx4 v[160:161], off
	s_waitcnt vmcnt(8)
	s_waitcnt lgkmcnt(0)
	s_barrier
	s_setprio 1
	s_waitcnt lgkmcnt(0)
	v_mfma_f32_16x16x32_bf16 v[60:63], v[144:147], v[184:187], v[60:63]
	v_mfma_f32_16x16x32_bf16 v[56:59], v[152:155], v[184:187], v[56:59]
	v_mfma_f32_16x16x32_bf16 v[44:47], v[144:147], v[192:195], v[44:47]
	v_mfma_f32_16x16x32_bf16 v[40:43], v[152:155], v[192:195], v[40:43]
	v_mfma_f32_16x16x32_bf16 v[28:31], v[144:147], v[200:203], v[28:31]
	v_mfma_f32_16x16x32_bf16 v[24:27], v[152:155], v[200:203], v[24:27]
	v_mfma_f32_16x16x32_bf16 v[12:15], v[144:147], v[208:211], v[12:15]
	v_mfma_f32_16x16x32_bf16 v[8:11], v[152:155], v[208:211], v[8:11]
	v_mfma_f32_16x16x32_bf16 v[60:63], v[148:151], v[188:191], v[60:63]
	v_mfma_f32_16x16x32_bf16 v[56:59], v[156:159], v[188:191], v[56:59]
	v_mfma_f32_16x16x32_bf16 v[44:47], v[148:151], v[196:199], v[44:47]
	v_mfma_f32_16x16x32_bf16 v[40:43], v[156:159], v[196:199], v[40:43]
	v_mfma_f32_16x16x32_bf16 v[28:31], v[148:151], v[204:207], v[28:31]
	v_mfma_f32_16x16x32_bf16 v[24:27], v[156:159], v[204:207], v[24:27]
	v_mfma_f32_16x16x32_bf16 v[12:15], v[148:151], v[212:215], v[12:15]
	v_mfma_f32_16x16x32_bf16 v[8:11], v[156:159], v[212:215], v[8:11]
	s_setprio 0
	s_setprio 1
	v_mfma_f32_16x16x32_bf16 v[52:55], v[168:171], v[184:187], v[52:55]
	v_mfma_f32_16x16x32_bf16 v[48:51], v[176:179], v[184:187], v[48:51]
	v_mfma_f32_16x16x32_bf16 v[36:39], v[168:171], v[192:195], v[36:39]
	v_mfma_f32_16x16x32_bf16 v[32:35], v[176:179], v[192:195], v[32:35]
	v_mfma_f32_16x16x32_bf16 v[20:23], v[168:171], v[200:203], v[20:23]
	v_mfma_f32_16x16x32_bf16 v[16:19], v[176:179], v[200:203], v[16:19]
	v_mfma_f32_16x16x32_bf16 v[4:7], v[168:171], v[208:211], v[4:7]
	v_mfma_f32_16x16x32_bf16 v[0:3], v[176:179], v[208:211], v[0:3]
	v_mfma_f32_16x16x32_bf16 v[52:55], v[172:175], v[188:191], v[52:55]
	v_mfma_f32_16x16x32_bf16 v[48:51], v[180:183], v[188:191], v[48:51]
	v_mfma_f32_16x16x32_bf16 v[36:39], v[172:175], v[196:199], v[36:39]
	v_mfma_f32_16x16x32_bf16 v[32:35], v[180:183], v[196:199], v[32:35]
	s_setprio 2
	s_barrier
	v_mfma_f32_16x16x32_bf16 v[20:23], v[172:175], v[204:207], v[20:23]
	v_mfma_f32_16x16x32_bf16 v[16:19], v[180:183], v[204:207], v[16:19]
	v_mfma_f32_16x16x32_bf16 v[4:7], v[172:175], v[212:215], v[4:7]
	v_mfma_f32_16x16x32_bf16 v[0:3], v[180:183], v[212:215], v[0:3]
	s_setprio 0
	s_add_i32 s65, s65, 2
	s_add_u32 s36, s36, 0x100
	s_addc_u32 s37, s37, 0
	s_add_u32 s63, s63, 0x100
	s_addc_u32 s64, s64, 0
	s_cmp_gt_u32 s65, 13
.LBB0_784:
	ds_read_b128 v[144:147], v163
	ds_read_b128 v[148:151], v163 offset:1024
	ds_read_b128 v[152:155], v163 offset:2048
	ds_read_b128 v[156:159], v163 offset:3072
	ds_read_b128 v[168:171], v164
	ds_read_b128 v[172:175], v164 offset:1024
	ds_read_b128 v[176:179], v164 offset:2048
	ds_read_b128 v[180:183], v164 offset:3072
	s_add_u32 s38, s36, 0xfffc0080
	s_addc_u32 s39, s37, -1
	s_cmp_eq_u32 s65, 12
	s_cselect_b32 s41, s23, s39
	s_cselect_b32 s40, s31, s38
	s_cselect_b32 s39, s25, s64
	s_cselect_b32 s38, s62, s63
	v_lshl_add_u64 v[160:161], s[36:37], 0, v[136:137]
	s_add_i32 m0, s50, 0xc000
	ds_read_b128 v[184:187], v165
	ds_read_b128 v[188:191], v165 offset:1024
	ds_read_b128 v[192:195], v165 offset:2048
	ds_read_b128 v[196:199], v165 offset:3072
	ds_read_b128 v[200:203], v165 offset:4096
	ds_read_b128 v[204:207], v165 offset:5120
	ds_read_b128 v[208:211], v165 offset:6144
	ds_read_b128 v[212:215], v165 offset:7168
	global_load_lds_dwordx4 v[160:161], off
	s_add_i32 m0, s50, 0xe000
	v_lshl_add_u64 v[160:161], s[36:37], 0, v[138:139]
	global_load_lds_dwordx4 v[160:161], off
	s_waitcnt vmcnt(8)
	s_waitcnt lgkmcnt(0)
	s_barrier
	s_setprio 1
	s_waitcnt lgkmcnt(0)
	v_mfma_f32_16x16x32_bf16 v[124:127], v[144:147], v[184:187], v[124:127]
	v_mfma_f32_16x16x32_bf16 v[120:123], v[152:155], v[184:187], v[120:123]
	v_mfma_f32_16x16x32_bf16 v[108:111], v[144:147], v[192:195], v[108:111]
	v_mfma_f32_16x16x32_bf16 v[104:107], v[152:155], v[192:195], v[104:107]
	v_mfma_f32_16x16x32_bf16 v[92:95], v[144:147], v[200:203], v[92:95]
	v_mfma_f32_16x16x32_bf16 v[88:91], v[152:155], v[200:203], v[88:91]
	v_mfma_f32_16x16x32_bf16 v[76:79], v[144:147], v[208:211], v[76:79]
	v_mfma_f32_16x16x32_bf16 v[72:75], v[152:155], v[208:211], v[72:75]
	v_mfma_f32_16x16x32_bf16 v[124:127], v[148:151], v[188:191], v[124:127]
	v_mfma_f32_16x16x32_bf16 v[120:123], v[156:159], v[188:191], v[120:123]
	v_mfma_f32_16x16x32_bf16 v[108:111], v[148:151], v[196:199], v[108:111]
	v_mfma_f32_16x16x32_bf16 v[104:107], v[156:159], v[196:199], v[104:107]
	v_mfma_f32_16x16x32_bf16 v[92:95], v[148:151], v[204:207], v[92:95]
	v_mfma_f32_16x16x32_bf16 v[88:91], v[156:159], v[204:207], v[88:91]
	v_mfma_f32_16x16x32_bf16 v[76:79], v[148:151], v[212:215], v[76:79]
	v_mfma_f32_16x16x32_bf16 v[72:75], v[156:159], v[212:215], v[72:75]
	s_setprio 0
	s_setprio 1
	v_mfma_f32_16x16x32_bf16 v[116:119], v[168:171], v[184:187], v[116:119]
	v_mfma_f32_16x16x32_bf16 v[112:115], v[176:179], v[184:187], v[112:115]
	v_mfma_f32_16x16x32_bf16 v[100:103], v[168:171], v[192:195], v[100:103]
	v_mfma_f32_16x16x32_bf16 v[96:99], v[176:179], v[192:195], v[96:99]
	v_mfma_f32_16x16x32_bf16 v[84:87], v[168:171], v[200:203], v[84:87]
	v_mfma_f32_16x16x32_bf16 v[80:83], v[176:179], v[200:203], v[80:83]
	v_mfma_f32_16x16x32_bf16 v[68:71], v[168:171], v[208:211], v[68:71]
	v_mfma_f32_16x16x32_bf16 v[64:67], v[176:179], v[208:211], v[64:67]
	v_mfma_f32_16x16x32_bf16 v[116:119], v[172:175], v[188:191], v[116:119]
	v_mfma_f32_16x16x32_bf16 v[112:115], v[180:183], v[188:191], v[112:115]
	v_mfma_f32_16x16x32_bf16 v[100:103], v[172:175], v[196:199], v[100:103]
	v_mfma_f32_16x16x32_bf16 v[96:99], v[180:183], v[196:199], v[96:99]
	s_setprio 2
	s_barrier
	s_add_i32 s66, s59, s47
	s_mov_b32 m0, s66
	v_lshl_add_u64 v[160:161], s[38:39], 0, v[132:133]
	global_load_lds_dwordx4 v[160:161], off
	v_mfma_f32_16x16x32_bf16 v[84:87], v[172:175], v[204:207], v[84:87]
	s_add_i32 m0, s66, 0x2000
	s_add_u32 s66, s38, 0x40000
	v_lshl_add_u64 v[216:217], s[38:39], 0, v[128:129]
	s_addc_u32 s67, s39, 0
	s_add_i32 s68, s60, s47
	global_load_lds_dwordx4 v[216:217], off
	v_mfma_f32_16x16x32_bf16 v[80:83], v[180:183], v[204:207], v[80:83]
	v_lshl_add_u64 v[218:219], s[66:67], 0, v[132:133]
	s_mov_b32 m0, s68
	v_lshl_add_u64 v[220:221], s[40:41], 0, v[130:131]
	global_load_lds_dwordx4 v[218:219], off
	v_mfma_f32_16x16x32_bf16 v[68:71], v[172:175], v[212:215], v[68:71]
	s_add_i32 m0, s68, 0x2000
	v_lshl_add_u64 v[218:219], s[66:67], 0, v[128:129]
	global_load_lds_dwordx4 v[218:219], off
	v_mfma_f32_16x16x32_bf16 v[64:67], v[180:183], v[212:215], v[64:67]
	ds_read_b128 v[184:187], v165 offset:16384
	ds_read_b128 v[188:191], v165 offset:17408
	ds_read_b128 v[192:195], v165 offset:18432
	ds_read_b128 v[196:199], v165 offset:19456
	ds_read_b128 v[200:203], v165 offset:20480
	ds_read_b128 v[204:207], v165 offset:21504
	ds_read_b128 v[208:211], v165 offset:22528
	ds_read_b128 v[212:215], v165 offset:23552
	s_mov_b32 m0, s50
	v_lshl_add_u64 v[218:219], s[40:41], 0, v[134:135]
	global_load_lds_dwordx4 v[218:219], off
	s_mov_b32 m0, s51
	s_nop 0
	global_load_lds_dwordx4 v[220:221], off
	s_waitcnt vmcnt(8)
	s_waitcnt lgkmcnt(0)
	s_barrier
	s_setprio 1
	s_waitcnt lgkmcnt(0)
	v_mfma_f32_16x16x32_bf16 v[60:63], v[144:147], v[184:187], v[60:63]
	v_mfma_f32_16x16x32_bf16 v[56:59], v[152:155], v[184:187], v[56:59]
	v_mfma_f32_16x16x32_bf16 v[44:47], v[144:147], v[192:195], v[44:47]
	v_mfma_f32_16x16x32_bf16 v[40:43], v[152:155], v[192:195], v[40:43]
	v_mfma_f32_16x16x32_bf16 v[28:31], v[144:147], v[200:203], v[28:31]
	v_mfma_f32_16x16x32_bf16 v[24:27], v[152:155], v[200:203], v[24:27]
	v_mfma_f32_16x16x32_bf16 v[12:15], v[144:147], v[208:211], v[12:15]
	v_mfma_f32_16x16x32_bf16 v[8:11], v[152:155], v[208:211], v[8:11]
	v_mfma_f32_16x16x32_bf16 v[60:63], v[148:151], v[188:191], v[60:63]
	v_mfma_f32_16x16x32_bf16 v[56:59], v[156:159], v[188:191], v[56:59]
	v_mfma_f32_16x16x32_bf16 v[44:47], v[148:151], v[196:199], v[44:47]
	v_mfma_f32_16x16x32_bf16 v[40:43], v[156:159], v[196:199], v[40:43]
	v_mfma_f32_16x16x32_bf16 v[28:31], v[148:151], v[204:207], v[28:31]
	v_mfma_f32_16x16x32_bf16 v[24:27], v[156:159], v[204:207], v[24:27]
	v_mfma_f32_16x16x32_bf16 v[12:15], v[148:151], v[212:215], v[12:15]
	v_mfma_f32_16x16x32_bf16 v[8:11], v[156:159], v[212:215], v[8:11]
	s_setprio 0
	s_setprio 1
	v_mfma_f32_16x16x32_bf16 v[52:55], v[168:171], v[184:187], v[52:55]
	v_mfma_f32_16x16x32_bf16 v[48:51], v[176:179], v[184:187], v[48:51]
	v_mfma_f32_16x16x32_bf16 v[36:39], v[168:171], v[192:195], v[36:39]
	v_mfma_f32_16x16x32_bf16 v[32:35], v[176:179], v[192:195], v[32:35]
	v_mfma_f32_16x16x32_bf16 v[20:23], v[168:171], v[200:203], v[20:23]
	v_mfma_f32_16x16x32_bf16 v[16:19], v[176:179], v[200:203], v[16:19]
	v_mfma_f32_16x16x32_bf16 v[4:7], v[168:171], v[208:211], v[4:7]
	v_mfma_f32_16x16x32_bf16 v[0:3], v[176:179], v[208:211], v[0:3]
	v_mfma_f32_16x16x32_bf16 v[52:55], v[172:175], v[188:191], v[52:55]
	v_mfma_f32_16x16x32_bf16 v[48:51], v[180:183], v[188:191], v[48:51]
	v_mfma_f32_16x16x32_bf16 v[36:39], v[172:175], v[196:199], v[36:39]
	v_mfma_f32_16x16x32_bf16 v[32:35], v[180:183], v[196:199], v[32:35]
	s_setprio 2
	s_barrier
	v_mfma_f32_16x16x32_bf16 v[20:23], v[172:175], v[204:207], v[20:23]
	v_mfma_f32_16x16x32_bf16 v[16:19], v[180:183], v[204:207], v[16:19]
	v_mfma_f32_16x16x32_bf16 v[4:7], v[172:175], v[212:215], v[4:7]
	v_mfma_f32_16x16x32_bf16 v[0:3], v[180:183], v[212:215], v[0:3]
	s_setprio 0
	s_add_i32 s66, 0, 0x18000
	s_add_i32 s67, 0, 0x1c000
	v_add_u32_e32 v156, s66, v162
	v_add_u32_e32 v167, s67, v162
	ds_read_b128 v[144:147], v156
	ds_read_b128 v[148:151], v156 offset:1024
	ds_read_b128 v[152:155], v156 offset:2048
	ds_read_b128 v[156:159], v156 offset:3072
	ds_read_b128 v[168:171], v167
	ds_read_b128 v[172:175], v167 offset:1024
	ds_read_b128 v[176:179], v167 offset:2048
	ds_read_b128 v[180:183], v167 offset:3072
	s_add_u32 s40, s40, 0x40000
	s_addc_u32 s41, s41, 0
	s_mov_b32 m0, s54
	v_lshl_add_u64 v[222:223], s[40:41], 0, v[134:135]
	ds_read_b128 v[184:187], v165 offset:32768
	ds_read_b128 v[188:191], v165 offset:33792
	ds_read_b128 v[192:195], v165 offset:34816
	ds_read_b128 v[196:199], v165 offset:35840
	ds_read_b128 v[200:203], v165 offset:36864
	ds_read_b128 v[204:207], v165 offset:37888
	ds_read_b128 v[208:211], v165 offset:38912
	ds_read_b128 v[212:215], v165 offset:39936
	global_load_lds_dwordx4 v[222:223], off
	s_mov_b32 m0, s55
	v_lshl_add_u64 v[222:223], s[40:41], 0, v[130:131]
	global_load_lds_dwordx4 v[222:223], off
	s_waitcnt vmcnt(8)
	s_waitcnt lgkmcnt(0)
	s_barrier
	s_setprio 1
	s_waitcnt lgkmcnt(0)
	v_mfma_f32_16x16x32_bf16 v[124:127], v[144:147], v[184:187], v[124:127]
	v_mfma_f32_16x16x32_bf16 v[120:123], v[152:155], v[184:187], v[120:123]
	v_mfma_f32_16x16x32_bf16 v[108:111], v[144:147], v[192:195], v[108:111]
	v_mfma_f32_16x16x32_bf16 v[104:107], v[152:155], v[192:195], v[104:107]
	v_mfma_f32_16x16x32_bf16 v[92:95], v[144:147], v[200:203], v[92:95]
	v_mfma_f32_16x16x32_bf16 v[88:91], v[152:155], v[200:203], v[88:91]
	v_mfma_f32_16x16x32_bf16 v[76:79], v[144:147], v[208:211], v[76:79]
	v_mfma_f32_16x16x32_bf16 v[72:75], v[152:155], v[208:211], v[72:75]
	v_mfma_f32_16x16x32_bf16 v[124:127], v[148:151], v[188:191], v[124:127]
	v_mfma_f32_16x16x32_bf16 v[120:123], v[156:159], v[188:191], v[120:123]
	v_mfma_f32_16x16x32_bf16 v[108:111], v[148:151], v[196:199], v[108:111]
	v_mfma_f32_16x16x32_bf16 v[104:107], v[156:159], v[196:199], v[104:107]
	v_mfma_f32_16x16x32_bf16 v[92:95], v[148:151], v[204:207], v[92:95]
	v_mfma_f32_16x16x32_bf16 v[88:91], v[156:159], v[204:207], v[88:91]
	v_mfma_f32_16x16x32_bf16 v[76:79], v[148:151], v[212:215], v[76:79]
	v_mfma_f32_16x16x32_bf16 v[72:75], v[156:159], v[212:215], v[72:75]
	s_setprio 0
	s_setprio 1
	v_mfma_f32_16x16x32_bf16 v[116:119], v[168:171], v[184:187], v[116:119]
	v_mfma_f32_16x16x32_bf16 v[112:115], v[176:179], v[184:187], v[112:115]
	v_mfma_f32_16x16x32_bf16 v[100:103], v[168:171], v[192:195], v[100:103]
	v_mfma_f32_16x16x32_bf16 v[96:99], v[176:179], v[192:195], v[96:99]
	v_mfma_f32_16x16x32_bf16 v[84:87], v[168:171], v[200:203], v[84:87]
	v_mfma_f32_16x16x32_bf16 v[80:83], v[176:179], v[200:203], v[80:83]
	v_mfma_f32_16x16x32_bf16 v[68:71], v[168:171], v[208:211], v[68:71]
	v_mfma_f32_16x16x32_bf16 v[64:67], v[176:179], v[208:211], v[64:67]
	v_mfma_f32_16x16x32_bf16 v[116:119], v[172:175], v[188:191], v[116:119]
	v_mfma_f32_16x16x32_bf16 v[112:115], v[180:183], v[188:191], v[112:115]
	v_mfma_f32_16x16x32_bf16 v[100:103], v[172:175], v[196:199], v[100:103]
	v_mfma_f32_16x16x32_bf16 v[96:99], v[180:183], v[196:199], v[96:99]
	s_setprio 2
	s_barrier
	s_add_i32 s40, s66, s47
	s_mov_b32 m0, s40
	v_lshl_add_u64 v[160:161], v[160:161], 0, s[16:17]
	global_load_lds_dwordx4 v[160:161], off
	v_mfma_f32_16x16x32_bf16 v[84:87], v[172:175], v[204:207], v[84:87]
	s_add_i32 m0, s40, 0x2000
	s_add_u32 s38, s38, 0x40080
	v_lshl_add_u64 v[160:161], v[216:217], 0, s[16:17]
	s_addc_u32 s39, s39, 0
	s_add_i32 s40, s67, s47
	global_load_lds_dwordx4 v[160:161], off
	v_mfma_f32_16x16x32_bf16 v[80:83], v[180:183], v[204:207], v[80:83]
	s_mov_b32 m0, s40
	v_lshl_add_u64 v[160:161], s[38:39], 0, v[132:133]
	global_load_lds_dwordx4 v[160:161], off
	v_mfma_f32_16x16x32_bf16 v[68:71], v[172:175], v[212:215], v[68:71]
	s_add_i32 m0, s40, 0x2000
	v_lshl_add_u64 v[160:161], s[38:39], 0, v[128:129]
	global_load_lds_dwordx4 v[160:161], off
	v_mfma_f32_16x16x32_bf16 v[64:67], v[180:183], v[212:215], v[64:67]
	ds_read_b128 v[184:187], v165 offset:49152
	ds_read_b128 v[188:191], v165 offset:50176
	ds_read_b128 v[192:195], v165 offset:51200
	ds_read_b128 v[196:199], v165 offset:52224
	ds_read_b128 v[200:203], v165 offset:53248
	ds_read_b128 v[204:207], v165 offset:54272
	ds_read_b128 v[208:211], v165 offset:55296
	ds_read_b128 v[212:215], v165 offset:56320
	s_mov_b32 m0, s57
	v_lshl_add_u64 v[160:161], v[218:219], 0, s[16:17]
	global_load_lds_dwordx4 v[160:161], off
	s_mov_b32 m0, s58
	v_lshl_add_u64 v[160:161], v[220:221], 0, s[16:17]
	global_load_lds_dwordx4 v[160:161], off
	s_waitcnt vmcnt(8)
	s_waitcnt lgkmcnt(0)
	s_barrier
	s_setprio 1
	s_waitcnt lgkmcnt(0)
	v_mfma_f32_16x16x32_bf16 v[60:63], v[144:147], v[184:187], v[60:63]
	v_mfma_f32_16x16x32_bf16 v[56:59], v[152:155], v[184:187], v[56:59]
	v_mfma_f32_16x16x32_bf16 v[44:47], v[144:147], v[192:195], v[44:47]
	v_mfma_f32_16x16x32_bf16 v[40:43], v[152:155], v[192:195], v[40:43]
	v_mfma_f32_16x16x32_bf16 v[28:31], v[144:147], v[200:203], v[28:31]
	v_mfma_f32_16x16x32_bf16 v[24:27], v[152:155], v[200:203], v[24:27]
	v_mfma_f32_16x16x32_bf16 v[12:15], v[144:147], v[208:211], v[12:15]
	v_mfma_f32_16x16x32_bf16 v[8:11], v[152:155], v[208:211], v[8:11]
	v_mfma_f32_16x16x32_bf16 v[60:63], v[148:151], v[188:191], v[60:63]
	v_mfma_f32_16x16x32_bf16 v[56:59], v[156:159], v[188:191], v[56:59]
	v_mfma_f32_16x16x32_bf16 v[44:47], v[148:151], v[196:199], v[44:47]
	v_mfma_f32_16x16x32_bf16 v[40:43], v[156:159], v[196:199], v[40:43]
	v_mfma_f32_16x16x32_bf16 v[28:31], v[148:151], v[204:207], v[28:31]
	v_mfma_f32_16x16x32_bf16 v[24:27], v[156:159], v[204:207], v[24:27]
	v_mfma_f32_16x16x32_bf16 v[12:15], v[148:151], v[212:215], v[12:15]
	v_mfma_f32_16x16x32_bf16 v[8:11], v[156:159], v[212:215], v[8:11]
	s_setprio 0
	s_setprio 1
	v_mfma_f32_16x16x32_bf16 v[52:55], v[168:171], v[184:187], v[52:55]
	v_mfma_f32_16x16x32_bf16 v[48:51], v[176:179], v[184:187], v[48:51]
	v_mfma_f32_16x16x32_bf16 v[36:39], v[168:171], v[192:195], v[36:39]
	v_mfma_f32_16x16x32_bf16 v[32:35], v[176:179], v[192:195], v[32:35]
	v_mfma_f32_16x16x32_bf16 v[20:23], v[168:171], v[200:203], v[20:23]
	v_mfma_f32_16x16x32_bf16 v[16:19], v[176:179], v[200:203], v[16:19]
	v_mfma_f32_16x16x32_bf16 v[4:7], v[168:171], v[208:211], v[4:7]
	v_mfma_f32_16x16x32_bf16 v[0:3], v[176:179], v[208:211], v[0:3]
	v_mfma_f32_16x16x32_bf16 v[52:55], v[172:175], v[188:191], v[52:55]
	v_mfma_f32_16x16x32_bf16 v[48:51], v[180:183], v[188:191], v[48:51]
	v_mfma_f32_16x16x32_bf16 v[36:39], v[172:175], v[196:199], v[36:39]
	v_mfma_f32_16x16x32_bf16 v[32:35], v[180:183], v[196:199], v[32:35]
	s_setprio 2
	s_barrier
	v_mfma_f32_16x16x32_bf16 v[20:23], v[172:175], v[204:207], v[20:23]
	v_mfma_f32_16x16x32_bf16 v[16:19], v[180:183], v[204:207], v[16:19]
	v_mfma_f32_16x16x32_bf16 v[4:7], v[172:175], v[212:215], v[4:7]
	v_mfma_f32_16x16x32_bf16 v[0:3], v[180:183], v[212:215], v[0:3]
	s_setprio 0
	s_add_i32 s65, s65, 2
	s_add_u32 s36, s36, 0x100
	s_addc_u32 s37, s37, 0
	s_add_u32 s63, s63, 0x100
	s_addc_u32 s64, s64, 0
	s_cmp_gt_u32 s65, 13
	s_cbranch_scc0 .LBB0_784

.LBB0_865:
	s_add_u32 s62, s28, 0x100
	s_addc_u32 s63, s29, 0
	s_mov_b32 s64, -2
	ds_read_b128 v[120:123], v233
	ds_read_b128 v[124:127], v233 offset:1024
	ds_read_b128 v[136:139], v233 offset:2048
	ds_read_b128 v[140:143], v233 offset:3072
	ds_read_b128 v[144:147], v234
	ds_read_b128 v[148:151], v234 offset:1024
	ds_read_b128 v[152:155], v234 offset:2048
	ds_read_b128 v[156:159], v234 offset:3072
	s_add_u32 s28, s26, 0x100
	s_addc_u32 s29, s27, 0
	s_cmp_eq_u32 s64, 40
	s_cselect_b32 s37, s7, s29
	s_cselect_b32 s36, s6, s28
	s_cselect_b32 s31, s25, s63
	s_cselect_b32 s30, s24, s62
	v_lshl_add_u64 v[208:209], s[26:27], 0, v[192:193]
	s_add_i32 m0, s44, 0xc000
	ds_read_b128 v[160:163], v235
	ds_read_b128 v[164:167], v235 offset:1024
	ds_read_b128 v[168:171], v235 offset:2048
	ds_read_b128 v[172:175], v235 offset:3072
	ds_read_b128 v[176:179], v235 offset:4096
	ds_read_b128 v[180:183], v235 offset:5120
	ds_read_b128 v[200:203], v235 offset:6144
	ds_read_b128 v[204:207], v235 offset:7168
	global_load_lds_dwordx4 v[208:209], off
	s_add_i32 m0, s44, 0xe000
	v_lshl_add_u64 v[208:209], s[26:27], 0, v[194:195]
	global_load_lds_dwordx4 v[208:209], off
	s_waitcnt vmcnt(8)
	s_waitcnt lgkmcnt(0)
	s_barrier
	s_setprio 1
	s_waitcnt lgkmcnt(0)
	v_mfma_f32_16x16x32_bf16 v[132:135], v[120:123], v[160:163], 0
	v_mfma_f32_16x16x32_bf16 v[128:131], v[136:139], v[160:163], 0
	v_mfma_f32_16x16x32_bf16 v[108:111], v[120:123], v[168:171], 0
	v_mfma_f32_16x16x32_bf16 v[104:107], v[136:139], v[168:171], 0
	v_mfma_f32_16x16x32_bf16 v[92:95], v[120:123], v[176:179], 0
	v_mfma_f32_16x16x32_bf16 v[88:91], v[136:139], v[176:179], 0
	v_mfma_f32_16x16x32_bf16 v[76:79], v[120:123], v[200:203], 0
	v_mfma_f32_16x16x32_bf16 v[72:75], v[136:139], v[200:203], 0
	v_mfma_f32_16x16x32_bf16 v[132:135], v[124:127], v[164:167], v[132:135]
	v_mfma_f32_16x16x32_bf16 v[128:131], v[140:143], v[164:167], v[128:131]
	v_mfma_f32_16x16x32_bf16 v[108:111], v[124:127], v[172:175], v[108:111]
	v_mfma_f32_16x16x32_bf16 v[104:107], v[140:143], v[172:175], v[104:107]
	v_mfma_f32_16x16x32_bf16 v[92:95], v[124:127], v[180:183], v[92:95]
	v_mfma_f32_16x16x32_bf16 v[88:91], v[140:143], v[180:183], v[88:91]
	v_mfma_f32_16x16x32_bf16 v[76:79], v[124:127], v[204:207], v[76:79]
	v_mfma_f32_16x16x32_bf16 v[72:75], v[140:143], v[204:207], v[72:75]
	s_setprio 0
	s_setprio 1
	v_mfma_f32_16x16x32_bf16 v[116:119], v[144:147], v[160:163], 0
	v_mfma_f32_16x16x32_bf16 v[112:115], v[152:155], v[160:163], 0
	v_mfma_f32_16x16x32_bf16 v[100:103], v[144:147], v[168:171], 0
	v_mfma_f32_16x16x32_bf16 v[96:99], v[152:155], v[168:171], 0
	v_mfma_f32_16x16x32_bf16 v[84:87], v[144:147], v[176:179], 0
	v_mfma_f32_16x16x32_bf16 v[80:83], v[152:155], v[176:179], 0
	v_mfma_f32_16x16x32_bf16 v[68:71], v[144:147], v[200:203], 0
	v_mfma_f32_16x16x32_bf16 v[64:67], v[152:155], v[200:203], 0
	v_mfma_f32_16x16x32_bf16 v[116:119], v[148:151], v[164:167], v[116:119]
	v_mfma_f32_16x16x32_bf16 v[112:115], v[156:159], v[164:167], v[112:115]
	v_mfma_f32_16x16x32_bf16 v[100:103], v[148:151], v[172:175], v[100:103]
	v_mfma_f32_16x16x32_bf16 v[96:99], v[156:159], v[172:175], v[96:99]
	s_setprio 2
	s_barrier
	s_add_i32 s26, s56, s43
	s_mov_b32 m0, s26
	v_lshl_add_u64 v[208:209], s[30:31], 0, v[186:187]
	global_load_lds_dwordx4 v[208:209], off
	v_mfma_f32_16x16x32_bf16 v[84:87], v[148:151], v[180:183], v[84:87]
	s_add_i32 m0, s26, 0x2000
	s_add_u32 s26, s30, 0xb0000
	v_lshl_add_u64 v[210:211], s[30:31], 0, v[190:191]
	s_addc_u32 s27, s31, 0
	s_add_i32 s65, s57, s43
	global_load_lds_dwordx4 v[210:211], off
	v_mfma_f32_16x16x32_bf16 v[80:83], v[156:159], v[180:183], v[80:83]
	v_lshl_add_u64 v[212:213], s[26:27], 0, v[186:187]
	s_mov_b32 m0, s65
	v_lshl_add_u64 v[214:215], s[36:37], 0, v[188:189]
	global_load_lds_dwordx4 v[212:213], off
	v_mfma_f32_16x16x32_bf16 v[68:71], v[148:151], v[204:207], v[68:71]
	s_add_i32 m0, s65, 0x2000
	v_lshl_add_u64 v[212:213], s[26:27], 0, v[190:191]
	global_load_lds_dwordx4 v[212:213], off
	v_mfma_f32_16x16x32_bf16 v[64:67], v[156:159], v[204:207], v[64:67]
	ds_read_b128 v[160:163], v235 offset:16384
	ds_read_b128 v[164:167], v235 offset:17408
	ds_read_b128 v[168:171], v235 offset:18432
	ds_read_b128 v[172:175], v235 offset:19456
	ds_read_b128 v[176:179], v235 offset:20480
	ds_read_b128 v[180:183], v235 offset:21504
	ds_read_b128 v[200:203], v235 offset:22528
	ds_read_b128 v[204:207], v235 offset:23552
	s_mov_b32 m0, s44
	v_lshl_add_u64 v[212:213], s[36:37], 0, v[184:185]
	global_load_lds_dwordx4 v[212:213], off
	s_mov_b32 m0, s45
	s_nop 0
	global_load_lds_dwordx4 v[214:215], off
	s_waitcnt vmcnt(8)
	s_waitcnt lgkmcnt(0)
	s_barrier
	s_setprio 1
	s_waitcnt lgkmcnt(0)
	v_mfma_f32_16x16x32_bf16 v[60:63], v[120:123], v[160:163], 0
	v_mfma_f32_16x16x32_bf16 v[56:59], v[136:139], v[160:163], 0
	v_mfma_f32_16x16x32_bf16 v[44:47], v[120:123], v[168:171], 0
	v_mfma_f32_16x16x32_bf16 v[40:43], v[136:139], v[168:171], 0
	v_mfma_f32_16x16x32_bf16 v[28:31], v[120:123], v[176:179], 0
	v_mfma_f32_16x16x32_bf16 v[24:27], v[136:139], v[176:179], 0
	v_mfma_f32_16x16x32_bf16 v[12:15], v[120:123], v[200:203], 0
	v_mfma_f32_16x16x32_bf16 v[8:11], v[136:139], v[200:203], 0
	v_mfma_f32_16x16x32_bf16 v[60:63], v[124:127], v[164:167], v[60:63]
	v_mfma_f32_16x16x32_bf16 v[56:59], v[140:143], v[164:167], v[56:59]
	v_mfma_f32_16x16x32_bf16 v[44:47], v[124:127], v[172:175], v[44:47]
	v_mfma_f32_16x16x32_bf16 v[40:43], v[140:143], v[172:175], v[40:43]
	v_mfma_f32_16x16x32_bf16 v[28:31], v[124:127], v[180:183], v[28:31]
	v_mfma_f32_16x16x32_bf16 v[24:27], v[140:143], v[180:183], v[24:27]
	v_mfma_f32_16x16x32_bf16 v[12:15], v[124:127], v[204:207], v[12:15]
	v_mfma_f32_16x16x32_bf16 v[8:11], v[140:143], v[204:207], v[8:11]
	s_setprio 0
	s_setprio 1
	v_mfma_f32_16x16x32_bf16 v[52:55], v[144:147], v[160:163], 0
	v_mfma_f32_16x16x32_bf16 v[48:51], v[152:155], v[160:163], 0
	v_mfma_f32_16x16x32_bf16 v[36:39], v[144:147], v[168:171], 0
	v_mfma_f32_16x16x32_bf16 v[32:35], v[152:155], v[168:171], 0
	v_mfma_f32_16x16x32_bf16 v[20:23], v[144:147], v[176:179], 0
	v_mfma_f32_16x16x32_bf16 v[16:19], v[152:155], v[176:179], 0
	v_mfma_f32_16x16x32_bf16 v[4:7], v[144:147], v[200:203], 0
	v_mfma_f32_16x16x32_bf16 v[0:3], v[152:155], v[200:203], 0
	v_mfma_f32_16x16x32_bf16 v[52:55], v[148:151], v[164:167], v[52:55]
	v_mfma_f32_16x16x32_bf16 v[48:51], v[156:159], v[164:167], v[48:51]
	v_mfma_f32_16x16x32_bf16 v[36:39], v[148:151], v[172:175], v[36:39]
	v_mfma_f32_16x16x32_bf16 v[32:35], v[156:159], v[172:175], v[32:35]
	s_setprio 2
	s_barrier
	v_mfma_f32_16x16x32_bf16 v[20:23], v[148:151], v[180:183], v[20:23]
	v_mfma_f32_16x16x32_bf16 v[16:19], v[156:159], v[180:183], v[16:19]
	v_mfma_f32_16x16x32_bf16 v[4:7], v[148:151], v[204:207], v[4:7]
	v_mfma_f32_16x16x32_bf16 v[0:3], v[156:159], v[204:207], v[0:3]
	s_setprio 0
	s_add_i32 s65, 0, 0x18000
	s_add_i32 s66, 0, 0x1c000
	v_add_u32_e32 v140, s65, v232
	v_add_u32_e32 v156, s66, v232
	ds_read_b128 v[120:123], v140
	ds_read_b128 v[124:127], v140 offset:1024
	ds_read_b128 v[136:139], v140 offset:2048
	ds_read_b128 v[140:143], v140 offset:3072
	ds_read_b128 v[144:147], v156
	ds_read_b128 v[148:151], v156 offset:1024
	ds_read_b128 v[152:155], v156 offset:2048
	ds_read_b128 v[156:159], v156 offset:3072
	s_add_u32 s26, s36, 0xb0000
	s_addc_u32 s27, s37, 0
	s_mov_b32 m0, s46
	v_lshl_add_u64 v[216:217], s[26:27], 0, v[184:185]
	ds_read_b128 v[160:163], v235 offset:32768
	ds_read_b128 v[164:167], v235 offset:33792
	ds_read_b128 v[168:171], v235 offset:34816
	ds_read_b128 v[172:175], v235 offset:35840
	ds_read_b128 v[176:179], v235 offset:36864
	ds_read_b128 v[180:183], v235 offset:37888
	ds_read_b128 v[200:203], v235 offset:38912
	ds_read_b128 v[204:207], v235 offset:39936
	global_load_lds_dwordx4 v[216:217], off
	s_mov_b32 m0, s47
	v_lshl_add_u64 v[216:217], s[26:27], 0, v[188:189]
	global_load_lds_dwordx4 v[216:217], off
	s_waitcnt vmcnt(8)
	s_waitcnt lgkmcnt(0)
	s_barrier
	s_setprio 1
	s_waitcnt lgkmcnt(0)
	v_mfma_f32_16x16x32_bf16 v[132:135], v[120:123], v[160:163], v[132:135]
	v_mfma_f32_16x16x32_bf16 v[128:131], v[136:139], v[160:163], v[128:131]
	v_mfma_f32_16x16x32_bf16 v[108:111], v[120:123], v[168:171], v[108:111]
	v_mfma_f32_16x16x32_bf16 v[104:107], v[136:139], v[168:171], v[104:107]
	v_mfma_f32_16x16x32_bf16 v[92:95], v[120:123], v[176:179], v[92:95]
	v_mfma_f32_16x16x32_bf16 v[88:91], v[136:139], v[176:179], v[88:91]
	v_mfma_f32_16x16x32_bf16 v[76:79], v[120:123], v[200:203], v[76:79]
	v_mfma_f32_16x16x32_bf16 v[72:75], v[136:139], v[200:203], v[72:75]
	v_mfma_f32_16x16x32_bf16 v[132:135], v[124:127], v[164:167], v[132:135]
	v_mfma_f32_16x16x32_bf16 v[128:131], v[140:143], v[164:167], v[128:131]
	v_mfma_f32_16x16x32_bf16 v[108:111], v[124:127], v[172:175], v[108:111]
	v_mfma_f32_16x16x32_bf16 v[104:107], v[140:143], v[172:175], v[104:107]
	v_mfma_f32_16x16x32_bf16 v[92:95], v[124:127], v[180:183], v[92:95]
	v_mfma_f32_16x16x32_bf16 v[88:91], v[140:143], v[180:183], v[88:91]
	v_mfma_f32_16x16x32_bf16 v[76:79], v[124:127], v[204:207], v[76:79]
	v_mfma_f32_16x16x32_bf16 v[72:75], v[140:143], v[204:207], v[72:75]
	s_setprio 0
	s_setprio 1
	v_mfma_f32_16x16x32_bf16 v[116:119], v[144:147], v[160:163], v[116:119]
	v_mfma_f32_16x16x32_bf16 v[112:115], v[152:155], v[160:163], v[112:115]
	v_mfma_f32_16x16x32_bf16 v[100:103], v[144:147], v[168:171], v[100:103]
	v_mfma_f32_16x16x32_bf16 v[96:99], v[152:155], v[168:171], v[96:99]
	v_mfma_f32_16x16x32_bf16 v[84:87], v[144:147], v[176:179], v[84:87]
	v_mfma_f32_16x16x32_bf16 v[80:83], v[152:155], v[176:179], v[80:83]
	v_mfma_f32_16x16x32_bf16 v[68:71], v[144:147], v[200:203], v[68:71]
	v_mfma_f32_16x16x32_bf16 v[64:67], v[152:155], v[200:203], v[64:67]
	v_mfma_f32_16x16x32_bf16 v[116:119], v[148:151], v[164:167], v[116:119]
	v_mfma_f32_16x16x32_bf16 v[112:115], v[156:159], v[164:167], v[112:115]
	v_mfma_f32_16x16x32_bf16 v[100:103], v[148:151], v[172:175], v[100:103]
	v_mfma_f32_16x16x32_bf16 v[96:99], v[156:159], v[172:175], v[96:99]
	s_setprio 2
	s_barrier
	s_add_i32 s26, s65, s43
	s_mov_b32 m0, s26
	v_lshl_add_u64 v[208:209], v[208:209], 0, s[20:21]
	global_load_lds_dwordx4 v[208:209], off
	v_mfma_f32_16x16x32_bf16 v[84:87], v[148:151], v[180:183], v[84:87]
	s_add_i32 m0, s26, 0x2000
	s_add_u32 s26, s30, 0xb0080
	v_lshl_add_u64 v[208:209], v[210:211], 0, s[20:21]
	s_addc_u32 s27, s31, 0
	s_add_i32 s30, s66, s43
	global_load_lds_dwordx4 v[208:209], off
	v_mfma_f32_16x16x32_bf16 v[80:83], v[156:159], v[180:183], v[80:83]
	s_mov_b32 m0, s30
	v_lshl_add_u64 v[208:209], s[26:27], 0, v[186:187]
	global_load_lds_dwordx4 v[208:209], off
	v_mfma_f32_16x16x32_bf16 v[68:71], v[148:151], v[204:207], v[68:71]
	s_add_i32 m0, s30, 0x2000
	v_lshl_add_u64 v[208:209], s[26:27], 0, v[190:191]
	global_load_lds_dwordx4 v[208:209], off
	v_mfma_f32_16x16x32_bf16 v[64:67], v[156:159], v[204:207], v[64:67]
	ds_read_b128 v[160:163], v235 offset:49152
	ds_read_b128 v[164:167], v235 offset:50176
	ds_read_b128 v[168:171], v235 offset:51200
	ds_read_b128 v[172:175], v235 offset:52224
	ds_read_b128 v[176:179], v235 offset:53248
	ds_read_b128 v[180:183], v235 offset:54272
	ds_read_b128 v[200:203], v235 offset:55296
	ds_read_b128 v[204:207], v235 offset:56320
	s_mov_b32 m0, s49
	v_lshl_add_u64 v[208:209], v[212:213], 0, s[20:21]
	global_load_lds_dwordx4 v[208:209], off
	s_mov_b32 m0, s50
	v_lshl_add_u64 v[208:209], v[214:215], 0, s[20:21]
	global_load_lds_dwordx4 v[208:209], off
	s_waitcnt vmcnt(8)
	s_waitcnt lgkmcnt(0)
	s_barrier
	s_setprio 1
	s_waitcnt lgkmcnt(0)
	v_mfma_f32_16x16x32_bf16 v[60:63], v[120:123], v[160:163], v[60:63]
	v_mfma_f32_16x16x32_bf16 v[56:59], v[136:139], v[160:163], v[56:59]
	v_mfma_f32_16x16x32_bf16 v[44:47], v[120:123], v[168:171], v[44:47]
	v_mfma_f32_16x16x32_bf16 v[40:43], v[136:139], v[168:171], v[40:43]
	v_mfma_f32_16x16x32_bf16 v[28:31], v[120:123], v[176:179], v[28:31]
	v_mfma_f32_16x16x32_bf16 v[24:27], v[136:139], v[176:179], v[24:27]
	v_mfma_f32_16x16x32_bf16 v[12:15], v[120:123], v[200:203], v[12:15]
	v_mfma_f32_16x16x32_bf16 v[8:11], v[136:139], v[200:203], v[8:11]
	v_mfma_f32_16x16x32_bf16 v[60:63], v[124:127], v[164:167], v[60:63]
	v_mfma_f32_16x16x32_bf16 v[56:59], v[140:143], v[164:167], v[56:59]
	v_mfma_f32_16x16x32_bf16 v[44:47], v[124:127], v[172:175], v[44:47]
	v_mfma_f32_16x16x32_bf16 v[40:43], v[140:143], v[172:175], v[40:43]
	v_mfma_f32_16x16x32_bf16 v[28:31], v[124:127], v[180:183], v[28:31]
	v_mfma_f32_16x16x32_bf16 v[24:27], v[140:143], v[180:183], v[24:27]
	v_mfma_f32_16x16x32_bf16 v[12:15], v[124:127], v[204:207], v[12:15]
	v_mfma_f32_16x16x32_bf16 v[8:11], v[140:143], v[204:207], v[8:11]
	s_setprio 0
	s_setprio 1
	v_mfma_f32_16x16x32_bf16 v[52:55], v[144:147], v[160:163], v[52:55]
	v_mfma_f32_16x16x32_bf16 v[48:51], v[152:155], v[160:163], v[48:51]
	v_mfma_f32_16x16x32_bf16 v[36:39], v[144:147], v[168:171], v[36:39]
	v_mfma_f32_16x16x32_bf16 v[32:35], v[152:155], v[168:171], v[32:35]
	v_mfma_f32_16x16x32_bf16 v[20:23], v[144:147], v[176:179], v[20:23]
	v_mfma_f32_16x16x32_bf16 v[16:19], v[152:155], v[176:179], v[16:19]
	v_mfma_f32_16x16x32_bf16 v[4:7], v[144:147], v[200:203], v[4:7]
	v_mfma_f32_16x16x32_bf16 v[0:3], v[152:155], v[200:203], v[0:3]
	v_mfma_f32_16x16x32_bf16 v[52:55], v[148:151], v[164:167], v[52:55]
	v_mfma_f32_16x16x32_bf16 v[48:51], v[156:159], v[164:167], v[48:51]
	v_mfma_f32_16x16x32_bf16 v[36:39], v[148:151], v[172:175], v[36:39]
	v_mfma_f32_16x16x32_bf16 v[32:35], v[156:159], v[172:175], v[32:35]
	s_setprio 2
	s_barrier
	v_mfma_f32_16x16x32_bf16 v[20:23], v[148:151], v[180:183], v[20:23]
	v_mfma_f32_16x16x32_bf16 v[16:19], v[156:159], v[180:183], v[16:19]
	v_mfma_f32_16x16x32_bf16 v[4:7], v[148:151], v[204:207], v[4:7]
	v_mfma_f32_16x16x32_bf16 v[0:3], v[156:159], v[204:207], v[0:3]
	s_setprio 0
	s_add_i32 s64, s64, 2
	s_add_u32 s62, s62, 0x100
	s_addc_u32 s63, s63, 0
	s_cmp_gt_u32 s64, 41
	s_mov_b64 s[26:27], s[28:29]
.LBB0_866:
	ds_read_b128 v[120:123], v233
	ds_read_b128 v[124:127], v233 offset:1024
	ds_read_b128 v[136:139], v233 offset:2048
	ds_read_b128 v[140:143], v233 offset:3072
	ds_read_b128 v[144:147], v234
	ds_read_b128 v[148:151], v234 offset:1024
	ds_read_b128 v[152:155], v234 offset:2048
	ds_read_b128 v[156:159], v234 offset:3072
	s_add_u32 s28, s26, 0x100
	s_addc_u32 s29, s27, 0
	s_cmp_eq_u32 s64, 40
	s_cselect_b32 s37, s7, s29
	s_cselect_b32 s36, s6, s28
	s_cselect_b32 s31, s25, s63
	s_cselect_b32 s30, s24, s62
	v_lshl_add_u64 v[208:209], s[26:27], 0, v[192:193]
	s_add_i32 m0, s44, 0xc000
	ds_read_b128 v[160:163], v235
	ds_read_b128 v[164:167], v235 offset:1024
	ds_read_b128 v[168:171], v235 offset:2048
	ds_read_b128 v[172:175], v235 offset:3072
	ds_read_b128 v[176:179], v235 offset:4096
	ds_read_b128 v[180:183], v235 offset:5120
	ds_read_b128 v[200:203], v235 offset:6144
	ds_read_b128 v[204:207], v235 offset:7168
	global_load_lds_dwordx4 v[208:209], off
	s_add_i32 m0, s44, 0xe000
	v_lshl_add_u64 v[208:209], s[26:27], 0, v[194:195]
	global_load_lds_dwordx4 v[208:209], off
	s_waitcnt vmcnt(8)
	s_waitcnt lgkmcnt(0)
	s_barrier
	s_setprio 1
	s_waitcnt lgkmcnt(0)
	v_mfma_f32_16x16x32_bf16 v[132:135], v[120:123], v[160:163], v[132:135]
	v_mfma_f32_16x16x32_bf16 v[128:131], v[136:139], v[160:163], v[128:131]
	v_mfma_f32_16x16x32_bf16 v[108:111], v[120:123], v[168:171], v[108:111]
	v_mfma_f32_16x16x32_bf16 v[104:107], v[136:139], v[168:171], v[104:107]
	v_mfma_f32_16x16x32_bf16 v[92:95], v[120:123], v[176:179], v[92:95]
	v_mfma_f32_16x16x32_bf16 v[88:91], v[136:139], v[176:179], v[88:91]
	v_mfma_f32_16x16x32_bf16 v[76:79], v[120:123], v[200:203], v[76:79]
	v_mfma_f32_16x16x32_bf16 v[72:75], v[136:139], v[200:203], v[72:75]
	v_mfma_f32_16x16x32_bf16 v[132:135], v[124:127], v[164:167], v[132:135]
	v_mfma_f32_16x16x32_bf16 v[128:131], v[140:143], v[164:167], v[128:131]
	v_mfma_f32_16x16x32_bf16 v[108:111], v[124:127], v[172:175], v[108:111]
	v_mfma_f32_16x16x32_bf16 v[104:107], v[140:143], v[172:175], v[104:107]
	v_mfma_f32_16x16x32_bf16 v[92:95], v[124:127], v[180:183], v[92:95]
	v_mfma_f32_16x16x32_bf16 v[88:91], v[140:143], v[180:183], v[88:91]
	v_mfma_f32_16x16x32_bf16 v[76:79], v[124:127], v[204:207], v[76:79]
	v_mfma_f32_16x16x32_bf16 v[72:75], v[140:143], v[204:207], v[72:75]
	s_setprio 0
	s_setprio 1
	v_mfma_f32_16x16x32_bf16 v[116:119], v[144:147], v[160:163], v[116:119]
	v_mfma_f32_16x16x32_bf16 v[112:115], v[152:155], v[160:163], v[112:115]
	v_mfma_f32_16x16x32_bf16 v[100:103], v[144:147], v[168:171], v[100:103]
	v_mfma_f32_16x16x32_bf16 v[96:99], v[152:155], v[168:171], v[96:99]
	v_mfma_f32_16x16x32_bf16 v[84:87], v[144:147], v[176:179], v[84:87]
	v_mfma_f32_16x16x32_bf16 v[80:83], v[152:155], v[176:179], v[80:83]
	v_mfma_f32_16x16x32_bf16 v[68:71], v[144:147], v[200:203], v[68:71]
	v_mfma_f32_16x16x32_bf16 v[64:67], v[152:155], v[200:203], v[64:67]
	v_mfma_f32_16x16x32_bf16 v[116:119], v[148:151], v[164:167], v[116:119]
	v_mfma_f32_16x16x32_bf16 v[112:115], v[156:159], v[164:167], v[112:115]
	v_mfma_f32_16x16x32_bf16 v[100:103], v[148:151], v[172:175], v[100:103]
	v_mfma_f32_16x16x32_bf16 v[96:99], v[156:159], v[172:175], v[96:99]
	s_setprio 2
	s_barrier
	s_add_i32 s26, s56, s43
	s_mov_b32 m0, s26
	v_lshl_add_u64 v[208:209], s[30:31], 0, v[186:187]
	global_load_lds_dwordx4 v[208:209], off
	v_mfma_f32_16x16x32_bf16 v[84:87], v[148:151], v[180:183], v[84:87]
	s_add_i32 m0, s26, 0x2000
	s_add_u32 s26, s30, 0xb0000
	v_lshl_add_u64 v[210:211], s[30:31], 0, v[190:191]
	s_addc_u32 s27, s31, 0
	s_add_i32 s65, s57, s43
	global_load_lds_dwordx4 v[210:211], off
	v_mfma_f32_16x16x32_bf16 v[80:83], v[156:159], v[180:183], v[80:83]
	v_lshl_add_u64 v[212:213], s[26:27], 0, v[186:187]
	s_mov_b32 m0, s65
	v_lshl_add_u64 v[214:215], s[36:37], 0, v[188:189]
	global_load_lds_dwordx4 v[212:213], off
	v_mfma_f32_16x16x32_bf16 v[68:71], v[148:151], v[204:207], v[68:71]
	s_add_i32 m0, s65, 0x2000
	v_lshl_add_u64 v[212:213], s[26:27], 0, v[190:191]
	global_load_lds_dwordx4 v[212:213], off
	v_mfma_f32_16x16x32_bf16 v[64:67], v[156:159], v[204:207], v[64:67]
	ds_read_b128 v[160:163], v235 offset:16384
	ds_read_b128 v[164:167], v235 offset:17408
	ds_read_b128 v[168:171], v235 offset:18432
	ds_read_b128 v[172:175], v235 offset:19456
	ds_read_b128 v[176:179], v235 offset:20480
	ds_read_b128 v[180:183], v235 offset:21504
	ds_read_b128 v[200:203], v235 offset:22528
	ds_read_b128 v[204:207], v235 offset:23552
	s_mov_b32 m0, s44
	v_lshl_add_u64 v[212:213], s[36:37], 0, v[184:185]
	global_load_lds_dwordx4 v[212:213], off
	s_mov_b32 m0, s45
	s_nop 0
	global_load_lds_dwordx4 v[214:215], off
	s_waitcnt vmcnt(8)
	s_waitcnt lgkmcnt(0)
	s_barrier
	s_setprio 1
	s_waitcnt lgkmcnt(0)
	v_mfma_f32_16x16x32_bf16 v[60:63], v[120:123], v[160:163], v[60:63]
	v_mfma_f32_16x16x32_bf16 v[56:59], v[136:139], v[160:163], v[56:59]
	v_mfma_f32_16x16x32_bf16 v[44:47], v[120:123], v[168:171], v[44:47]
	v_mfma_f32_16x16x32_bf16 v[40:43], v[136:139], v[168:171], v[40:43]
	v_mfma_f32_16x16x32_bf16 v[28:31], v[120:123], v[176:179], v[28:31]
	v_mfma_f32_16x16x32_bf16 v[24:27], v[136:139], v[176:179], v[24:27]
	v_mfma_f32_16x16x32_bf16 v[12:15], v[120:123], v[200:203], v[12:15]
	v_mfma_f32_16x16x32_bf16 v[8:11], v[136:139], v[200:203], v[8:11]
	v_mfma_f32_16x16x32_bf16 v[60:63], v[124:127], v[164:167], v[60:63]
	v_mfma_f32_16x16x32_bf16 v[56:59], v[140:143], v[164:167], v[56:59]
	v_mfma_f32_16x16x32_bf16 v[44:47], v[124:127], v[172:175], v[44:47]
	v_mfma_f32_16x16x32_bf16 v[40:43], v[140:143], v[172:175], v[40:43]
	v_mfma_f32_16x16x32_bf16 v[28:31], v[124:127], v[180:183], v[28:31]
	v_mfma_f32_16x16x32_bf16 v[24:27], v[140:143], v[180:183], v[24:27]
	v_mfma_f32_16x16x32_bf16 v[12:15], v[124:127], v[204:207], v[12:15]
	v_mfma_f32_16x16x32_bf16 v[8:11], v[140:143], v[204:207], v[8:11]
	s_setprio 0
	s_setprio 1
	v_mfma_f32_16x16x32_bf16 v[52:55], v[144:147], v[160:163], v[52:55]
	v_mfma_f32_16x16x32_bf16 v[48:51], v[152:155], v[160:163], v[48:51]
	v_mfma_f32_16x16x32_bf16 v[36:39], v[144:147], v[168:171], v[36:39]
	v_mfma_f32_16x16x32_bf16 v[32:35], v[152:155], v[168:171], v[32:35]
	v_mfma_f32_16x16x32_bf16 v[20:23], v[144:147], v[176:179], v[20:23]
	v_mfma_f32_16x16x32_bf16 v[16:19], v[152:155], v[176:179], v[16:19]
	v_mfma_f32_16x16x32_bf16 v[4:7], v[144:147], v[200:203], v[4:7]
	v_mfma_f32_16x16x32_bf16 v[0:3], v[152:155], v[200:203], v[0:3]
	v_mfma_f32_16x16x32_bf16 v[52:55], v[148:151], v[164:167], v[52:55]
	v_mfma_f32_16x16x32_bf16 v[48:51], v[156:159], v[164:167], v[48:51]
	v_mfma_f32_16x16x32_bf16 v[36:39], v[148:151], v[172:175], v[36:39]
	v_mfma_f32_16x16x32_bf16 v[32:35], v[156:159], v[172:175], v[32:35]
	s_setprio 2
	s_barrier
	v_mfma_f32_16x16x32_bf16 v[20:23], v[148:151], v[180:183], v[20:23]
	v_mfma_f32_16x16x32_bf16 v[16:19], v[156:159], v[180:183], v[16:19]
	v_mfma_f32_16x16x32_bf16 v[4:7], v[148:151], v[204:207], v[4:7]
	v_mfma_f32_16x16x32_bf16 v[0:3], v[156:159], v[204:207], v[0:3]
	s_setprio 0
	s_add_i32 s65, 0, 0x18000
	s_add_i32 s66, 0, 0x1c000
	v_add_u32_e32 v140, s65, v232
	v_add_u32_e32 v156, s66, v232
	ds_read_b128 v[120:123], v140
	ds_read_b128 v[124:127], v140 offset:1024
	ds_read_b128 v[136:139], v140 offset:2048
	ds_read_b128 v[140:143], v140 offset:3072
	ds_read_b128 v[144:147], v156
	ds_read_b128 v[148:151], v156 offset:1024
	ds_read_b128 v[152:155], v156 offset:2048
	ds_read_b128 v[156:159], v156 offset:3072
	s_add_u32 s26, s36, 0xb0000
	s_addc_u32 s27, s37, 0
	s_mov_b32 m0, s46
	v_lshl_add_u64 v[216:217], s[26:27], 0, v[184:185]
	ds_read_b128 v[160:163], v235 offset:32768
	ds_read_b128 v[164:167], v235 offset:33792
	ds_read_b128 v[168:171], v235 offset:34816
	ds_read_b128 v[172:175], v235 offset:35840
	ds_read_b128 v[176:179], v235 offset:36864
	ds_read_b128 v[180:183], v235 offset:37888
	ds_read_b128 v[200:203], v235 offset:38912
	ds_read_b128 v[204:207], v235 offset:39936
	global_load_lds_dwordx4 v[216:217], off
	s_mov_b32 m0, s47
	v_lshl_add_u64 v[216:217], s[26:27], 0, v[188:189]
	global_load_lds_dwordx4 v[216:217], off
	s_waitcnt vmcnt(8)
	s_waitcnt lgkmcnt(0)
	s_barrier
	s_setprio 1
	s_waitcnt lgkmcnt(0)
	v_mfma_f32_16x16x32_bf16 v[132:135], v[120:123], v[160:163], v[132:135]
	v_mfma_f32_16x16x32_bf16 v[128:131], v[136:139], v[160:163], v[128:131]
	v_mfma_f32_16x16x32_bf16 v[108:111], v[120:123], v[168:171], v[108:111]
	v_mfma_f32_16x16x32_bf16 v[104:107], v[136:139], v[168:171], v[104:107]
	v_mfma_f32_16x16x32_bf16 v[92:95], v[120:123], v[176:179], v[92:95]
	v_mfma_f32_16x16x32_bf16 v[88:91], v[136:139], v[176:179], v[88:91]
	v_mfma_f32_16x16x32_bf16 v[76:79], v[120:123], v[200:203], v[76:79]
	v_mfma_f32_16x16x32_bf16 v[72:75], v[136:139], v[200:203], v[72:75]
	v_mfma_f32_16x16x32_bf16 v[132:135], v[124:127], v[164:167], v[132:135]
	v_mfma_f32_16x16x32_bf16 v[128:131], v[140:143], v[164:167], v[128:131]
	v_mfma_f32_16x16x32_bf16 v[108:111], v[124:127], v[172:175], v[108:111]
	v_mfma_f32_16x16x32_bf16 v[104:107], v[140:143], v[172:175], v[104:107]
	v_mfma_f32_16x16x32_bf16 v[92:95], v[124:127], v[180:183], v[92:95]
	v_mfma_f32_16x16x32_bf16 v[88:91], v[140:143], v[180:183], v[88:91]
	v_mfma_f32_16x16x32_bf16 v[76:79], v[124:127], v[204:207], v[76:79]
	v_mfma_f32_16x16x32_bf16 v[72:75], v[140:143], v[204:207], v[72:75]
	s_setprio 0
	s_setprio 1
	v_mfma_f32_16x16x32_bf16 v[116:119], v[144:147], v[160:163], v[116:119]
	v_mfma_f32_16x16x32_bf16 v[112:115], v[152:155], v[160:163], v[112:115]
	v_mfma_f32_16x16x32_bf16 v[100:103], v[144:147], v[168:171], v[100:103]
	v_mfma_f32_16x16x32_bf16 v[96:99], v[152:155], v[168:171], v[96:99]
	v_mfma_f32_16x16x32_bf16 v[84:87], v[144:147], v[176:179], v[84:87]
	v_mfma_f32_16x16x32_bf16 v[80:83], v[152:155], v[176:179], v[80:83]
	v_mfma_f32_16x16x32_bf16 v[68:71], v[144:147], v[200:203], v[68:71]
	v_mfma_f32_16x16x32_bf16 v[64:67], v[152:155], v[200:203], v[64:67]
	v_mfma_f32_16x16x32_bf16 v[116:119], v[148:151], v[164:167], v[116:119]
	v_mfma_f32_16x16x32_bf16 v[112:115], v[156:159], v[164:167], v[112:115]
	v_mfma_f32_16x16x32_bf16 v[100:103], v[148:151], v[172:175], v[100:103]
	v_mfma_f32_16x16x32_bf16 v[96:99], v[156:159], v[172:175], v[96:99]
	s_setprio 2
	s_barrier
	s_add_i32 s26, s65, s43
	s_mov_b32 m0, s26
	v_lshl_add_u64 v[208:209], v[208:209], 0, s[20:21]
	global_load_lds_dwordx4 v[208:209], off
	v_mfma_f32_16x16x32_bf16 v[84:87], v[148:151], v[180:183], v[84:87]
	s_add_i32 m0, s26, 0x2000
	s_add_u32 s26, s30, 0xb0080
	v_lshl_add_u64 v[208:209], v[210:211], 0, s[20:21]
	s_addc_u32 s27, s31, 0
	s_add_i32 s30, s66, s43
	global_load_lds_dwordx4 v[208:209], off
	v_mfma_f32_16x16x32_bf16 v[80:83], v[156:159], v[180:183], v[80:83]
	s_mov_b32 m0, s30
	v_lshl_add_u64 v[208:209], s[26:27], 0, v[186:187]
	global_load_lds_dwordx4 v[208:209], off
	v_mfma_f32_16x16x32_bf16 v[68:71], v[148:151], v[204:207], v[68:71]
	s_add_i32 m0, s30, 0x2000
	v_lshl_add_u64 v[208:209], s[26:27], 0, v[190:191]
	global_load_lds_dwordx4 v[208:209], off
	v_mfma_f32_16x16x32_bf16 v[64:67], v[156:159], v[204:207], v[64:67]
	ds_read_b128 v[160:163], v235 offset:49152
	ds_read_b128 v[164:167], v235 offset:50176
	ds_read_b128 v[168:171], v235 offset:51200
	ds_read_b128 v[172:175], v235 offset:52224
	ds_read_b128 v[176:179], v235 offset:53248
	ds_read_b128 v[180:183], v235 offset:54272
	ds_read_b128 v[200:203], v235 offset:55296
	ds_read_b128 v[204:207], v235 offset:56320
	s_mov_b32 m0, s49
	v_lshl_add_u64 v[208:209], v[212:213], 0, s[20:21]
	global_load_lds_dwordx4 v[208:209], off
	s_mov_b32 m0, s50
	v_lshl_add_u64 v[208:209], v[214:215], 0, s[20:21]
	global_load_lds_dwordx4 v[208:209], off
	s_waitcnt vmcnt(8)
	s_waitcnt lgkmcnt(0)
	s_barrier
	s_setprio 1
	s_waitcnt lgkmcnt(0)
	v_mfma_f32_16x16x32_bf16 v[60:63], v[120:123], v[160:163], v[60:63]
	v_mfma_f32_16x16x32_bf16 v[56:59], v[136:139], v[160:163], v[56:59]
	v_mfma_f32_16x16x32_bf16 v[44:47], v[120:123], v[168:171], v[44:47]
	v_mfma_f32_16x16x32_bf16 v[40:43], v[136:139], v[168:171], v[40:43]
	v_mfma_f32_16x16x32_bf16 v[28:31], v[120:123], v[176:179], v[28:31]
	v_mfma_f32_16x16x32_bf16 v[24:27], v[136:139], v[176:179], v[24:27]
	v_mfma_f32_16x16x32_bf16 v[12:15], v[120:123], v[200:203], v[12:15]
	v_mfma_f32_16x16x32_bf16 v[8:11], v[136:139], v[200:203], v[8:11]
	v_mfma_f32_16x16x32_bf16 v[60:63], v[124:127], v[164:167], v[60:63]
	v_mfma_f32_16x16x32_bf16 v[56:59], v[140:143], v[164:167], v[56:59]
	v_mfma_f32_16x16x32_bf16 v[44:47], v[124:127], v[172:175], v[44:47]
	v_mfma_f32_16x16x32_bf16 v[40:43], v[140:143], v[172:175], v[40:43]
	v_mfma_f32_16x16x32_bf16 v[28:31], v[124:127], v[180:183], v[28:31]
	v_mfma_f32_16x16x32_bf16 v[24:27], v[140:143], v[180:183], v[24:27]
	v_mfma_f32_16x16x32_bf16 v[12:15], v[124:127], v[204:207], v[12:15]
	v_mfma_f32_16x16x32_bf16 v[8:11], v[140:143], v[204:207], v[8:11]
	s_setprio 0
	s_setprio 1
	v_mfma_f32_16x16x32_bf16 v[52:55], v[144:147], v[160:163], v[52:55]
	v_mfma_f32_16x16x32_bf16 v[48:51], v[152:155], v[160:163], v[48:51]
	v_mfma_f32_16x16x32_bf16 v[36:39], v[144:147], v[168:171], v[36:39]
	v_mfma_f32_16x16x32_bf16 v[32:35], v[152:155], v[168:171], v[32:35]
	v_mfma_f32_16x16x32_bf16 v[20:23], v[144:147], v[176:179], v[20:23]
	v_mfma_f32_16x16x32_bf16 v[16:19], v[152:155], v[176:179], v[16:19]
	v_mfma_f32_16x16x32_bf16 v[4:7], v[144:147], v[200:203], v[4:7]
	v_mfma_f32_16x16x32_bf16 v[0:3], v[152:155], v[200:203], v[0:3]
	v_mfma_f32_16x16x32_bf16 v[52:55], v[148:151], v[164:167], v[52:55]
	v_mfma_f32_16x16x32_bf16 v[48:51], v[156:159], v[164:167], v[48:51]
	v_mfma_f32_16x16x32_bf16 v[36:39], v[148:151], v[172:175], v[36:39]
	v_mfma_f32_16x16x32_bf16 v[32:35], v[156:159], v[172:175], v[32:35]
	s_setprio 2
	s_barrier
	v_mfma_f32_16x16x32_bf16 v[20:23], v[148:151], v[180:183], v[20:23]
	v_mfma_f32_16x16x32_bf16 v[16:19], v[156:159], v[180:183], v[16:19]
	v_mfma_f32_16x16x32_bf16 v[4:7], v[148:151], v[204:207], v[4:7]
	v_mfma_f32_16x16x32_bf16 v[0:3], v[156:159], v[204:207], v[0:3]
	s_setprio 0
	s_add_i32 s64, s64, 2
	s_add_u32 s62, s62, 0x100
	s_addc_u32 s63, s63, 0
	s_cmp_gt_u32 s64, 41
	s_mov_b64 s[26:27], s[28:29]
	s_cbranch_scc0 .LBB0_866

.LBB0_951:
	s_ashr_i32 s27, s26, 31
	s_lshl_b64 s[30:31], s[26:27], 19
	s_add_u32 s30, s47, s30
	s_addc_u32 s31, s48, s31
	s_and_b64 s[36:37], s[4:5], exec
	s_cselect_b32 s27, s31, s7
	s_cselect_b32 s39, s30, s6
	s_ashr_i32 s29, s28, 31
	s_lshl_b64 s[36:37], s[28:29], 19
	s_add_u32 s36, s49, s36
	s_addc_u32 s37, s50, s37
	s_and_b64 s[44:45], s[4:5], exec
	s_cselect_b32 s29, s37, s41
	s_cselect_b32 s43, s36, s40
	s_add_u32 s6, s6, 0x40080
	s_addc_u32 s7, s7, 0
	s_add_u32 s71, s40, 0x100
	s_addc_u32 s72, s41, 0
	s_mov_b32 s73, -2
	ds_read_b128 v[144:147], v179
	ds_read_b128 v[148:151], v179 offset:1024
	ds_read_b128 v[152:155], v179 offset:2048
	ds_read_b128 v[156:159], v179 offset:3072
	ds_read_b128 v[160:163], v180
	ds_read_b128 v[164:167], v180 offset:1024
	ds_read_b128 v[168:171], v180 offset:2048
	ds_read_b128 v[172:175], v180 offset:3072
	s_add_u32 s40, s6, 0xfffc0080
	s_addc_u32 s41, s7, -1
	s_cmp_eq_u32 s73, 12
	s_cselect_b32 s45, s27, s41
	s_cselect_b32 s44, s39, s40
	s_cselect_b32 s41, s29, s72
	s_cselect_b32 s40, s43, s71
	v_lshl_add_u64 v[176:177], s[6:7], 0, v[136:137]
	s_add_i32 m0, s54, 0xc000
	ds_read_b128 v[184:187], v181
	ds_read_b128 v[188:191], v181 offset:1024
	ds_read_b128 v[192:195], v181 offset:2048
	ds_read_b128 v[196:199], v181 offset:3072
	ds_read_b128 v[200:203], v181 offset:4096
	ds_read_b128 v[204:207], v181 offset:5120
	ds_read_b128 v[208:211], v181 offset:6144
	ds_read_b128 v[212:215], v181 offset:7168
	global_load_lds_dwordx4 v[176:177], off
	s_add_i32 m0, s54, 0xe000
	v_lshl_add_u64 v[176:177], s[6:7], 0, v[138:139]
	global_load_lds_dwordx4 v[176:177], off
	s_waitcnt vmcnt(8)
	s_waitcnt lgkmcnt(0)
	s_barrier
	s_setprio 1
	s_waitcnt lgkmcnt(0)
	v_mfma_f32_16x16x32_bf16 v[124:127], v[144:147], v[184:187], 0
	v_mfma_f32_16x16x32_bf16 v[120:123], v[152:155], v[184:187], 0
	v_mfma_f32_16x16x32_bf16 v[108:111], v[144:147], v[192:195], 0
	v_mfma_f32_16x16x32_bf16 v[104:107], v[152:155], v[192:195], 0
	v_mfma_f32_16x16x32_bf16 v[92:95], v[144:147], v[200:203], 0
	v_mfma_f32_16x16x32_bf16 v[88:91], v[152:155], v[200:203], 0
	v_mfma_f32_16x16x32_bf16 v[76:79], v[144:147], v[208:211], 0
	v_mfma_f32_16x16x32_bf16 v[72:75], v[152:155], v[208:211], 0
	v_mfma_f32_16x16x32_bf16 v[124:127], v[148:151], v[188:191], v[124:127]
	v_mfma_f32_16x16x32_bf16 v[120:123], v[156:159], v[188:191], v[120:123]
	v_mfma_f32_16x16x32_bf16 v[108:111], v[148:151], v[196:199], v[108:111]
	v_mfma_f32_16x16x32_bf16 v[104:107], v[156:159], v[196:199], v[104:107]
	v_mfma_f32_16x16x32_bf16 v[92:95], v[148:151], v[204:207], v[92:95]
	v_mfma_f32_16x16x32_bf16 v[88:91], v[156:159], v[204:207], v[88:91]
	v_mfma_f32_16x16x32_bf16 v[76:79], v[148:151], v[212:215], v[76:79]
	v_mfma_f32_16x16x32_bf16 v[72:75], v[156:159], v[212:215], v[72:75]
	s_setprio 0
	s_setprio 1
	v_mfma_f32_16x16x32_bf16 v[116:119], v[160:163], v[184:187], 0
	v_mfma_f32_16x16x32_bf16 v[112:115], v[168:171], v[184:187], 0
	v_mfma_f32_16x16x32_bf16 v[100:103], v[160:163], v[192:195], 0
	v_mfma_f32_16x16x32_bf16 v[96:99], v[168:171], v[192:195], 0
	v_mfma_f32_16x16x32_bf16 v[84:87], v[160:163], v[200:203], 0
	v_mfma_f32_16x16x32_bf16 v[80:83], v[168:171], v[200:203], 0
	v_mfma_f32_16x16x32_bf16 v[68:71], v[160:163], v[208:211], 0
	v_mfma_f32_16x16x32_bf16 v[64:67], v[168:171], v[208:211], 0
	v_mfma_f32_16x16x32_bf16 v[116:119], v[164:167], v[188:191], v[116:119]
	v_mfma_f32_16x16x32_bf16 v[112:115], v[172:175], v[188:191], v[112:115]
	v_mfma_f32_16x16x32_bf16 v[100:103], v[164:167], v[196:199], v[100:103]
	v_mfma_f32_16x16x32_bf16 v[96:99], v[172:175], v[196:199], v[96:99]
	s_setprio 2
	s_barrier
	s_add_i32 s74, s69, s51
	s_mov_b32 m0, s74
	v_lshl_add_u64 v[176:177], s[40:41], 0, v[130:131]
	global_load_lds_dwordx4 v[176:177], off
	v_mfma_f32_16x16x32_bf16 v[84:87], v[164:167], v[204:207], v[84:87]
	s_add_i32 m0, s74, 0x2000
	s_add_u32 s74, s40, 0x40000
	v_lshl_add_u64 v[216:217], s[40:41], 0, v[134:135]
	s_addc_u32 s75, s41, 0
	s_add_i32 s76, s70, s51
	global_load_lds_dwordx4 v[216:217], off
	v_mfma_f32_16x16x32_bf16 v[80:83], v[172:175], v[204:207], v[80:83]
	v_lshl_add_u64 v[218:219], s[74:75], 0, v[130:131]
	s_mov_b32 m0, s76
	v_lshl_add_u64 v[220:221], s[44:45], 0, v[132:133]
	global_load_lds_dwordx4 v[218:219], off
	v_mfma_f32_16x16x32_bf16 v[68:71], v[164:167], v[212:215], v[68:71]
	s_add_i32 m0, s76, 0x2000
	v_lshl_add_u64 v[218:219], s[74:75], 0, v[134:135]
	global_load_lds_dwordx4 v[218:219], off
	v_mfma_f32_16x16x32_bf16 v[64:67], v[172:175], v[212:215], v[64:67]
	ds_read_b128 v[184:187], v181 offset:16384
	ds_read_b128 v[188:191], v181 offset:17408
	ds_read_b128 v[192:195], v181 offset:18432
	ds_read_b128 v[196:199], v181 offset:19456
	ds_read_b128 v[200:203], v181 offset:20480
	ds_read_b128 v[204:207], v181 offset:21504
	ds_read_b128 v[208:211], v181 offset:22528
	ds_read_b128 v[212:215], v181 offset:23552
	s_mov_b32 m0, s54
	v_lshl_add_u64 v[218:219], s[44:45], 0, v[128:129]
	global_load_lds_dwordx4 v[218:219], off
	s_mov_b32 m0, s55
	s_nop 0
	global_load_lds_dwordx4 v[220:221], off
	s_waitcnt vmcnt(8)
	s_waitcnt lgkmcnt(0)
	s_barrier
	s_setprio 1
	s_waitcnt lgkmcnt(0)
	v_mfma_f32_16x16x32_bf16 v[60:63], v[144:147], v[184:187], 0
	v_mfma_f32_16x16x32_bf16 v[56:59], v[152:155], v[184:187], 0
	v_mfma_f32_16x16x32_bf16 v[44:47], v[144:147], v[192:195], 0
	v_mfma_f32_16x16x32_bf16 v[40:43], v[152:155], v[192:195], 0
	v_mfma_f32_16x16x32_bf16 v[28:31], v[144:147], v[200:203], 0
	v_mfma_f32_16x16x32_bf16 v[24:27], v[152:155], v[200:203], 0
	v_mfma_f32_16x16x32_bf16 v[12:15], v[144:147], v[208:211], 0
	v_mfma_f32_16x16x32_bf16 v[8:11], v[152:155], v[208:211], 0
	v_mfma_f32_16x16x32_bf16 v[60:63], v[148:151], v[188:191], v[60:63]
	v_mfma_f32_16x16x32_bf16 v[56:59], v[156:159], v[188:191], v[56:59]
	v_mfma_f32_16x16x32_bf16 v[44:47], v[148:151], v[196:199], v[44:47]
	v_mfma_f32_16x16x32_bf16 v[40:43], v[156:159], v[196:199], v[40:43]
	v_mfma_f32_16x16x32_bf16 v[28:31], v[148:151], v[204:207], v[28:31]
	v_mfma_f32_16x16x32_bf16 v[24:27], v[156:159], v[204:207], v[24:27]
	v_mfma_f32_16x16x32_bf16 v[12:15], v[148:151], v[212:215], v[12:15]
	v_mfma_f32_16x16x32_bf16 v[8:11], v[156:159], v[212:215], v[8:11]
	s_setprio 0
	s_setprio 1
	v_mfma_f32_16x16x32_bf16 v[52:55], v[160:163], v[184:187], 0
	v_mfma_f32_16x16x32_bf16 v[48:51], v[168:171], v[184:187], 0
	v_mfma_f32_16x16x32_bf16 v[36:39], v[160:163], v[192:195], 0
	v_mfma_f32_16x16x32_bf16 v[32:35], v[168:171], v[192:195], 0
	v_mfma_f32_16x16x32_bf16 v[20:23], v[160:163], v[200:203], 0
	v_mfma_f32_16x16x32_bf16 v[16:19], v[168:171], v[200:203], 0
	v_mfma_f32_16x16x32_bf16 v[4:7], v[160:163], v[208:211], 0
	v_mfma_f32_16x16x32_bf16 v[0:3], v[168:171], v[208:211], 0
	v_mfma_f32_16x16x32_bf16 v[52:55], v[164:167], v[188:191], v[52:55]
	v_mfma_f32_16x16x32_bf16 v[48:51], v[172:175], v[188:191], v[48:51]
	v_mfma_f32_16x16x32_bf16 v[36:39], v[164:167], v[196:199], v[36:39]
	v_mfma_f32_16x16x32_bf16 v[32:35], v[172:175], v[196:199], v[32:35]
	s_setprio 2
	s_barrier
	v_mfma_f32_16x16x32_bf16 v[20:23], v[164:167], v[204:207], v[20:23]
	v_mfma_f32_16x16x32_bf16 v[16:19], v[172:175], v[204:207], v[16:19]
	v_mfma_f32_16x16x32_bf16 v[4:7], v[164:167], v[212:215], v[4:7]
	v_mfma_f32_16x16x32_bf16 v[0:3], v[172:175], v[212:215], v[0:3]
	s_setprio 0
	s_add_i32 s74, 0, 0x18000
	s_add_i32 s75, 0, 0x1c000
	v_add_u32_e32 v156, s74, v178
	v_add_u32_e32 v172, s75, v178
	ds_read_b128 v[144:147], v156
	ds_read_b128 v[148:151], v156 offset:1024
	ds_read_b128 v[152:155], v156 offset:2048
	ds_read_b128 v[156:159], v156 offset:3072
	ds_read_b128 v[160:163], v172
	ds_read_b128 v[164:167], v172 offset:1024
	ds_read_b128 v[168:171], v172 offset:2048
	ds_read_b128 v[172:175], v172 offset:3072
	s_add_u32 s44, s44, 0x40000
	s_addc_u32 s45, s45, 0
	s_mov_b32 m0, s56
	v_lshl_add_u64 v[222:223], s[44:45], 0, v[128:129]
	ds_read_b128 v[184:187], v181 offset:32768
	ds_read_b128 v[188:191], v181 offset:33792
	ds_read_b128 v[192:195], v181 offset:34816
	ds_read_b128 v[196:199], v181 offset:35840
	ds_read_b128 v[200:203], v181 offset:36864
	ds_read_b128 v[204:207], v181 offset:37888
	ds_read_b128 v[208:211], v181 offset:38912
	ds_read_b128 v[212:215], v181 offset:39936
	global_load_lds_dwordx4 v[222:223], off
	s_mov_b32 m0, s57
	v_lshl_add_u64 v[222:223], s[44:45], 0, v[132:133]
	global_load_lds_dwordx4 v[222:223], off
	s_waitcnt vmcnt(8)
	s_waitcnt lgkmcnt(0)
	s_barrier
	s_setprio 1
	s_waitcnt lgkmcnt(0)
	v_mfma_f32_16x16x32_bf16 v[124:127], v[144:147], v[184:187], v[124:127]
	v_mfma_f32_16x16x32_bf16 v[120:123], v[152:155], v[184:187], v[120:123]
	v_mfma_f32_16x16x32_bf16 v[108:111], v[144:147], v[192:195], v[108:111]
	v_mfma_f32_16x16x32_bf16 v[104:107], v[152:155], v[192:195], v[104:107]
	v_mfma_f32_16x16x32_bf16 v[92:95], v[144:147], v[200:203], v[92:95]
	v_mfma_f32_16x16x32_bf16 v[88:91], v[152:155], v[200:203], v[88:91]
	v_mfma_f32_16x16x32_bf16 v[76:79], v[144:147], v[208:211], v[76:79]
	v_mfma_f32_16x16x32_bf16 v[72:75], v[152:155], v[208:211], v[72:75]
	v_mfma_f32_16x16x32_bf16 v[124:127], v[148:151], v[188:191], v[124:127]
	v_mfma_f32_16x16x32_bf16 v[120:123], v[156:159], v[188:191], v[120:123]
	v_mfma_f32_16x16x32_bf16 v[108:111], v[148:151], v[196:199], v[108:111]
	v_mfma_f32_16x16x32_bf16 v[104:107], v[156:159], v[196:199], v[104:107]
	v_mfma_f32_16x16x32_bf16 v[92:95], v[148:151], v[204:207], v[92:95]
	v_mfma_f32_16x16x32_bf16 v[88:91], v[156:159], v[204:207], v[88:91]
	v_mfma_f32_16x16x32_bf16 v[76:79], v[148:151], v[212:215], v[76:79]
	v_mfma_f32_16x16x32_bf16 v[72:75], v[156:159], v[212:215], v[72:75]
	s_setprio 0
	s_setprio 1
	v_mfma_f32_16x16x32_bf16 v[116:119], v[160:163], v[184:187], v[116:119]
	v_mfma_f32_16x16x32_bf16 v[112:115], v[168:171], v[184:187], v[112:115]
	v_mfma_f32_16x16x32_bf16 v[100:103], v[160:163], v[192:195], v[100:103]
	v_mfma_f32_16x16x32_bf16 v[96:99], v[168:171], v[192:195], v[96:99]
	v_mfma_f32_16x16x32_bf16 v[84:87], v[160:163], v[200:203], v[84:87]
	v_mfma_f32_16x16x32_bf16 v[80:83], v[168:171], v[200:203], v[80:83]
	v_mfma_f32_16x16x32_bf16 v[68:71], v[160:163], v[208:211], v[68:71]
	v_mfma_f32_16x16x32_bf16 v[64:67], v[168:171], v[208:211], v[64:67]
	v_mfma_f32_16x16x32_bf16 v[116:119], v[164:167], v[188:191], v[116:119]
	v_mfma_f32_16x16x32_bf16 v[112:115], v[172:175], v[188:191], v[112:115]
	v_mfma_f32_16x16x32_bf16 v[100:103], v[164:167], v[196:199], v[100:103]
	v_mfma_f32_16x16x32_bf16 v[96:99], v[172:175], v[196:199], v[96:99]
	s_setprio 2
	s_barrier
	s_add_i32 s44, s74, s51
	s_mov_b32 m0, s44
	v_lshl_add_u64 v[176:177], v[176:177], 0, s[22:23]
	global_load_lds_dwordx4 v[176:177], off
	v_mfma_f32_16x16x32_bf16 v[84:87], v[164:167], v[204:207], v[84:87]
	s_add_i32 m0, s44, 0x2000
	s_add_u32 s40, s40, 0x40080
	v_lshl_add_u64 v[176:177], v[216:217], 0, s[22:23]
	s_addc_u32 s41, s41, 0
	s_add_i32 s44, s75, s51
	global_load_lds_dwordx4 v[176:177], off
	v_mfma_f32_16x16x32_bf16 v[80:83], v[172:175], v[204:207], v[80:83]
	s_mov_b32 m0, s44
	v_lshl_add_u64 v[176:177], s[40:41], 0, v[130:131]
	global_load_lds_dwordx4 v[176:177], off
	v_mfma_f32_16x16x32_bf16 v[68:71], v[164:167], v[212:215], v[68:71]
	s_add_i32 m0, s44, 0x2000
	v_lshl_add_u64 v[176:177], s[40:41], 0, v[134:135]
	global_load_lds_dwordx4 v[176:177], off
	v_mfma_f32_16x16x32_bf16 v[64:67], v[172:175], v[212:215], v[64:67]
	ds_read_b128 v[184:187], v181 offset:49152
	ds_read_b128 v[188:191], v181 offset:50176
	ds_read_b128 v[192:195], v181 offset:51200
	ds_read_b128 v[196:199], v181 offset:52224
	ds_read_b128 v[200:203], v181 offset:53248
	ds_read_b128 v[204:207], v181 offset:54272
	ds_read_b128 v[208:211], v181 offset:55296
	ds_read_b128 v[212:215], v181 offset:56320
	s_mov_b32 m0, s64
	v_lshl_add_u64 v[176:177], v[218:219], 0, s[22:23]
	global_load_lds_dwordx4 v[176:177], off
	s_mov_b32 m0, s65
	v_lshl_add_u64 v[176:177], v[220:221], 0, s[22:23]
	global_load_lds_dwordx4 v[176:177], off
	s_waitcnt vmcnt(8)
	s_waitcnt lgkmcnt(0)
	s_barrier
	s_setprio 1
	s_waitcnt lgkmcnt(0)
	v_mfma_f32_16x16x32_bf16 v[60:63], v[144:147], v[184:187], v[60:63]
	v_mfma_f32_16x16x32_bf16 v[56:59], v[152:155], v[184:187], v[56:59]
	v_mfma_f32_16x16x32_bf16 v[44:47], v[144:147], v[192:195], v[44:47]
	v_mfma_f32_16x16x32_bf16 v[40:43], v[152:155], v[192:195], v[40:43]
	v_mfma_f32_16x16x32_bf16 v[28:31], v[144:147], v[200:203], v[28:31]
	v_mfma_f32_16x16x32_bf16 v[24:27], v[152:155], v[200:203], v[24:27]
	v_mfma_f32_16x16x32_bf16 v[12:15], v[144:147], v[208:211], v[12:15]
	v_mfma_f32_16x16x32_bf16 v[8:11], v[152:155], v[208:211], v[8:11]
	v_mfma_f32_16x16x32_bf16 v[60:63], v[148:151], v[188:191], v[60:63]
	v_mfma_f32_16x16x32_bf16 v[56:59], v[156:159], v[188:191], v[56:59]
	v_mfma_f32_16x16x32_bf16 v[44:47], v[148:151], v[196:199], v[44:47]
	v_mfma_f32_16x16x32_bf16 v[40:43], v[156:159], v[196:199], v[40:43]
	v_mfma_f32_16x16x32_bf16 v[28:31], v[148:151], v[204:207], v[28:31]
	v_mfma_f32_16x16x32_bf16 v[24:27], v[156:159], v[204:207], v[24:27]
	v_mfma_f32_16x16x32_bf16 v[12:15], v[148:151], v[212:215], v[12:15]
	v_mfma_f32_16x16x32_bf16 v[8:11], v[156:159], v[212:215], v[8:11]
	s_setprio 0
	s_setprio 1
	v_mfma_f32_16x16x32_bf16 v[52:55], v[160:163], v[184:187], v[52:55]
	v_mfma_f32_16x16x32_bf16 v[48:51], v[168:171], v[184:187], v[48:51]
	v_mfma_f32_16x16x32_bf16 v[36:39], v[160:163], v[192:195], v[36:39]
	v_mfma_f32_16x16x32_bf16 v[32:35], v[168:171], v[192:195], v[32:35]
	v_mfma_f32_16x16x32_bf16 v[20:23], v[160:163], v[200:203], v[20:23]
	v_mfma_f32_16x16x32_bf16 v[16:19], v[168:171], v[200:203], v[16:19]
	v_mfma_f32_16x16x32_bf16 v[4:7], v[160:163], v[208:211], v[4:7]
	v_mfma_f32_16x16x32_bf16 v[0:3], v[168:171], v[208:211], v[0:3]
	v_mfma_f32_16x16x32_bf16 v[52:55], v[164:167], v[188:191], v[52:55]
	v_mfma_f32_16x16x32_bf16 v[48:51], v[172:175], v[188:191], v[48:51]
	v_mfma_f32_16x16x32_bf16 v[36:39], v[164:167], v[196:199], v[36:39]
	v_mfma_f32_16x16x32_bf16 v[32:35], v[172:175], v[196:199], v[32:35]
	s_setprio 2
	s_barrier
	v_mfma_f32_16x16x32_bf16 v[20:23], v[164:167], v[204:207], v[20:23]
	v_mfma_f32_16x16x32_bf16 v[16:19], v[172:175], v[204:207], v[16:19]
	v_mfma_f32_16x16x32_bf16 v[4:7], v[164:167], v[212:215], v[4:7]
	v_mfma_f32_16x16x32_bf16 v[0:3], v[172:175], v[212:215], v[0:3]
	s_setprio 0
	s_add_i32 s73, s73, 2
	s_add_u32 s6, s6, 0x100
	s_addc_u32 s7, s7, 0
	s_add_u32 s71, s71, 0x100
	s_addc_u32 s72, s72, 0
	s_cmp_gt_u32 s73, 13
.LBB0_952:
	ds_read_b128 v[144:147], v179
	ds_read_b128 v[148:151], v179 offset:1024
	ds_read_b128 v[152:155], v179 offset:2048
	ds_read_b128 v[156:159], v179 offset:3072
	ds_read_b128 v[160:163], v180
	ds_read_b128 v[164:167], v180 offset:1024
	ds_read_b128 v[168:171], v180 offset:2048
	ds_read_b128 v[172:175], v180 offset:3072
	s_add_u32 s40, s6, 0xfffc0080
	s_addc_u32 s41, s7, -1
	s_cmp_eq_u32 s73, 12
	s_cselect_b32 s45, s27, s41
	s_cselect_b32 s44, s39, s40
	s_cselect_b32 s41, s29, s72
	s_cselect_b32 s40, s43, s71
	v_lshl_add_u64 v[176:177], s[6:7], 0, v[136:137]
	s_add_i32 m0, s54, 0xc000
	ds_read_b128 v[184:187], v181
	ds_read_b128 v[188:191], v181 offset:1024
	ds_read_b128 v[192:195], v181 offset:2048
	ds_read_b128 v[196:199], v181 offset:3072
	ds_read_b128 v[200:203], v181 offset:4096
	ds_read_b128 v[204:207], v181 offset:5120
	ds_read_b128 v[208:211], v181 offset:6144
	ds_read_b128 v[212:215], v181 offset:7168
	global_load_lds_dwordx4 v[176:177], off
	s_add_i32 m0, s54, 0xe000
	v_lshl_add_u64 v[176:177], s[6:7], 0, v[138:139]
	global_load_lds_dwordx4 v[176:177], off
	s_waitcnt vmcnt(8)
	s_waitcnt lgkmcnt(0)
	s_barrier
	s_setprio 1
	s_waitcnt lgkmcnt(0)
	v_mfma_f32_16x16x32_bf16 v[124:127], v[144:147], v[184:187], v[124:127]
	v_mfma_f32_16x16x32_bf16 v[120:123], v[152:155], v[184:187], v[120:123]
	v_mfma_f32_16x16x32_bf16 v[108:111], v[144:147], v[192:195], v[108:111]
	v_mfma_f32_16x16x32_bf16 v[104:107], v[152:155], v[192:195], v[104:107]
	v_mfma_f32_16x16x32_bf16 v[92:95], v[144:147], v[200:203], v[92:95]
	v_mfma_f32_16x16x32_bf16 v[88:91], v[152:155], v[200:203], v[88:91]
	v_mfma_f32_16x16x32_bf16 v[76:79], v[144:147], v[208:211], v[76:79]
	v_mfma_f32_16x16x32_bf16 v[72:75], v[152:155], v[208:211], v[72:75]
	v_mfma_f32_16x16x32_bf16 v[124:127], v[148:151], v[188:191], v[124:127]
	v_mfma_f32_16x16x32_bf16 v[120:123], v[156:159], v[188:191], v[120:123]
	v_mfma_f32_16x16x32_bf16 v[108:111], v[148:151], v[196:199], v[108:111]
	v_mfma_f32_16x16x32_bf16 v[104:107], v[156:159], v[196:199], v[104:107]
	v_mfma_f32_16x16x32_bf16 v[92:95], v[148:151], v[204:207], v[92:95]
	v_mfma_f32_16x16x32_bf16 v[88:91], v[156:159], v[204:207], v[88:91]
	v_mfma_f32_16x16x32_bf16 v[76:79], v[148:151], v[212:215], v[76:79]
	v_mfma_f32_16x16x32_bf16 v[72:75], v[156:159], v[212:215], v[72:75]
	s_setprio 0
	s_setprio 1
	v_mfma_f32_16x16x32_bf16 v[116:119], v[160:163], v[184:187], v[116:119]
	v_mfma_f32_16x16x32_bf16 v[112:115], v[168:171], v[184:187], v[112:115]
	v_mfma_f32_16x16x32_bf16 v[100:103], v[160:163], v[192:195], v[100:103]
	v_mfma_f32_16x16x32_bf16 v[96:99], v[168:171], v[192:195], v[96:99]
	v_mfma_f32_16x16x32_bf16 v[84:87], v[160:163], v[200:203], v[84:87]
	v_mfma_f32_16x16x32_bf16 v[80:83], v[168:171], v[200:203], v[80:83]
	v_mfma_f32_16x16x32_bf16 v[68:71], v[160:163], v[208:211], v[68:71]
	v_mfma_f32_16x16x32_bf16 v[64:67], v[168:171], v[208:211], v[64:67]
	v_mfma_f32_16x16x32_bf16 v[116:119], v[164:167], v[188:191], v[116:119]
	v_mfma_f32_16x16x32_bf16 v[112:115], v[172:175], v[188:191], v[112:115]
	v_mfma_f32_16x16x32_bf16 v[100:103], v[164:167], v[196:199], v[100:103]
	v_mfma_f32_16x16x32_bf16 v[96:99], v[172:175], v[196:199], v[96:99]
	s_setprio 2
	s_barrier
	s_add_i32 s74, s69, s51
	s_mov_b32 m0, s74
	v_lshl_add_u64 v[176:177], s[40:41], 0, v[130:131]
	global_load_lds_dwordx4 v[176:177], off
	v_mfma_f32_16x16x32_bf16 v[84:87], v[164:167], v[204:207], v[84:87]
	s_add_i32 m0, s74, 0x2000
	s_add_u32 s74, s40, 0x40000
	v_lshl_add_u64 v[216:217], s[40:41], 0, v[134:135]
	s_addc_u32 s75, s41, 0
	s_add_i32 s76, s70, s51
	global_load_lds_dwordx4 v[216:217], off
	v_mfma_f32_16x16x32_bf16 v[80:83], v[172:175], v[204:207], v[80:83]
	v_lshl_add_u64 v[218:219], s[74:75], 0, v[130:131]
	s_mov_b32 m0, s76
	v_lshl_add_u64 v[220:221], s[44:45], 0, v[132:133]
	global_load_lds_dwordx4 v[218:219], off
	v_mfma_f32_16x16x32_bf16 v[68:71], v[164:167], v[212:215], v[68:71]
	s_add_i32 m0, s76, 0x2000
	v_lshl_add_u64 v[218:219], s[74:75], 0, v[134:135]
	global_load_lds_dwordx4 v[218:219], off
	v_mfma_f32_16x16x32_bf16 v[64:67], v[172:175], v[212:215], v[64:67]
	ds_read_b128 v[184:187], v181 offset:16384
	ds_read_b128 v[188:191], v181 offset:17408
	ds_read_b128 v[192:195], v181 offset:18432
	ds_read_b128 v[196:199], v181 offset:19456
	ds_read_b128 v[200:203], v181 offset:20480
	ds_read_b128 v[204:207], v181 offset:21504
	ds_read_b128 v[208:211], v181 offset:22528
	ds_read_b128 v[212:215], v181 offset:23552
	s_mov_b32 m0, s54
	v_lshl_add_u64 v[218:219], s[44:45], 0, v[128:129]
	global_load_lds_dwordx4 v[218:219], off
	s_mov_b32 m0, s55
	s_nop 0
	global_load_lds_dwordx4 v[220:221], off
	s_waitcnt vmcnt(8)
	s_waitcnt lgkmcnt(0)
	s_barrier
	s_setprio 1
	s_waitcnt lgkmcnt(0)
	v_mfma_f32_16x16x32_bf16 v[60:63], v[144:147], v[184:187], v[60:63]
	v_mfma_f32_16x16x32_bf16 v[56:59], v[152:155], v[184:187], v[56:59]
	v_mfma_f32_16x16x32_bf16 v[44:47], v[144:147], v[192:195], v[44:47]
	v_mfma_f32_16x16x32_bf16 v[40:43], v[152:155], v[192:195], v[40:43]
	v_mfma_f32_16x16x32_bf16 v[28:31], v[144:147], v[200:203], v[28:31]
	v_mfma_f32_16x16x32_bf16 v[24:27], v[152:155], v[200:203], v[24:27]
	v_mfma_f32_16x16x32_bf16 v[12:15], v[144:147], v[208:211], v[12:15]
	v_mfma_f32_16x16x32_bf16 v[8:11], v[152:155], v[208:211], v[8:11]
	v_mfma_f32_16x16x32_bf16 v[60:63], v[148:151], v[188:191], v[60:63]
	v_mfma_f32_16x16x32_bf16 v[56:59], v[156:159], v[188:191], v[56:59]
	v_mfma_f32_16x16x32_bf16 v[44:47], v[148:151], v[196:199], v[44:47]
	v_mfma_f32_16x16x32_bf16 v[40:43], v[156:159], v[196:199], v[40:43]
	v_mfma_f32_16x16x32_bf16 v[28:31], v[148:151], v[204:207], v[28:31]
	v_mfma_f32_16x16x32_bf16 v[24:27], v[156:159], v[204:207], v[24:27]
	v_mfma_f32_16x16x32_bf16 v[12:15], v[148:151], v[212:215], v[12:15]
	v_mfma_f32_16x16x32_bf16 v[8:11], v[156:159], v[212:215], v[8:11]
	s_setprio 0
	s_setprio 1
	v_mfma_f32_16x16x32_bf16 v[52:55], v[160:163], v[184:187], v[52:55]
	v_mfma_f32_16x16x32_bf16 v[48:51], v[168:171], v[184:187], v[48:51]
	v_mfma_f32_16x16x32_bf16 v[36:39], v[160:163], v[192:195], v[36:39]
	v_mfma_f32_16x16x32_bf16 v[32:35], v[168:171], v[192:195], v[32:35]
	v_mfma_f32_16x16x32_bf16 v[20:23], v[160:163], v[200:203], v[20:23]
	v_mfma_f32_16x16x32_bf16 v[16:19], v[168:171], v[200:203], v[16:19]
	v_mfma_f32_16x16x32_bf16 v[4:7], v[160:163], v[208:211], v[4:7]
	v_mfma_f32_16x16x32_bf16 v[0:3], v[168:171], v[208:211], v[0:3]
	v_mfma_f32_16x16x32_bf16 v[52:55], v[164:167], v[188:191], v[52:55]
	v_mfma_f32_16x16x32_bf16 v[48:51], v[172:175], v[188:191], v[48:51]
	v_mfma_f32_16x16x32_bf16 v[36:39], v[164:167], v[196:199], v[36:39]
	v_mfma_f32_16x16x32_bf16 v[32:35], v[172:175], v[196:199], v[32:35]
	s_setprio 2
	s_barrier
	v_mfma_f32_16x16x32_bf16 v[20:23], v[164:167], v[204:207], v[20:23]
	v_mfma_f32_16x16x32_bf16 v[16:19], v[172:175], v[204:207], v[16:19]
	v_mfma_f32_16x16x32_bf16 v[4:7], v[164:167], v[212:215], v[4:7]
	v_mfma_f32_16x16x32_bf16 v[0:3], v[172:175], v[212:215], v[0:3]
	s_setprio 0
	s_add_i32 s74, 0, 0x18000
	s_add_i32 s75, 0, 0x1c000
	v_add_u32_e32 v156, s74, v178
	v_add_u32_e32 v172, s75, v178
	ds_read_b128 v[144:147], v156
	ds_read_b128 v[148:151], v156 offset:1024
	ds_read_b128 v[152:155], v156 offset:2048
	ds_read_b128 v[156:159], v156 offset:3072
	ds_read_b128 v[160:163], v172
	ds_read_b128 v[164:167], v172 offset:1024
	ds_read_b128 v[168:171], v172 offset:2048
	ds_read_b128 v[172:175], v172 offset:3072
	s_add_u32 s44, s44, 0x40000
	s_addc_u32 s45, s45, 0
	s_mov_b32 m0, s56
	v_lshl_add_u64 v[222:223], s[44:45], 0, v[128:129]
	ds_read_b128 v[184:187], v181 offset:32768
	ds_read_b128 v[188:191], v181 offset:33792
	ds_read_b128 v[192:195], v181 offset:34816
	ds_read_b128 v[196:199], v181 offset:35840
	ds_read_b128 v[200:203], v181 offset:36864
	ds_read_b128 v[204:207], v181 offset:37888
	ds_read_b128 v[208:211], v181 offset:38912
	ds_read_b128 v[212:215], v181 offset:39936
	global_load_lds_dwordx4 v[222:223], off
	s_mov_b32 m0, s57
	v_lshl_add_u64 v[222:223], s[44:45], 0, v[132:133]
	global_load_lds_dwordx4 v[222:223], off
	s_waitcnt vmcnt(8)
	s_waitcnt lgkmcnt(0)
	s_barrier
	s_setprio 1
	s_waitcnt lgkmcnt(0)
	v_mfma_f32_16x16x32_bf16 v[124:127], v[144:147], v[184:187], v[124:127]
	v_mfma_f32_16x16x32_bf16 v[120:123], v[152:155], v[184:187], v[120:123]
	v_mfma_f32_16x16x32_bf16 v[108:111], v[144:147], v[192:195], v[108:111]
	v_mfma_f32_16x16x32_bf16 v[104:107], v[152:155], v[192:195], v[104:107]
	v_mfma_f32_16x16x32_bf16 v[92:95], v[144:147], v[200:203], v[92:95]
	v_mfma_f32_16x16x32_bf16 v[88:91], v[152:155], v[200:203], v[88:91]
	v_mfma_f32_16x16x32_bf16 v[76:79], v[144:147], v[208:211], v[76:79]
	v_mfma_f32_16x16x32_bf16 v[72:75], v[152:155], v[208:211], v[72:75]
	v_mfma_f32_16x16x32_bf16 v[124:127], v[148:151], v[188:191], v[124:127]
	v_mfma_f32_16x16x32_bf16 v[120:123], v[156:159], v[188:191], v[120:123]
	v_mfma_f32_16x16x32_bf16 v[108:111], v[148:151], v[196:199], v[108:111]
	v_mfma_f32_16x16x32_bf16 v[104:107], v[156:159], v[196:199], v[104:107]
	v_mfma_f32_16x16x32_bf16 v[92:95], v[148:151], v[204:207], v[92:95]
	v_mfma_f32_16x16x32_bf16 v[88:91], v[156:159], v[204:207], v[88:91]
	v_mfma_f32_16x16x32_bf16 v[76:79], v[148:151], v[212:215], v[76:79]
	v_mfma_f32_16x16x32_bf16 v[72:75], v[156:159], v[212:215], v[72:75]
	s_setprio 0
	s_setprio 1
	v_mfma_f32_16x16x32_bf16 v[116:119], v[160:163], v[184:187], v[116:119]
	v_mfma_f32_16x16x32_bf16 v[112:115], v[168:171], v[184:187], v[112:115]
	v_mfma_f32_16x16x32_bf16 v[100:103], v[160:163], v[192:195], v[100:103]
	v_mfma_f32_16x16x32_bf16 v[96:99], v[168:171], v[192:195], v[96:99]
	v_mfma_f32_16x16x32_bf16 v[84:87], v[160:163], v[200:203], v[84:87]
	v_mfma_f32_16x16x32_bf16 v[80:83], v[168:171], v[200:203], v[80:83]
	v_mfma_f32_16x16x32_bf16 v[68:71], v[160:163], v[208:211], v[68:71]
	v_mfma_f32_16x16x32_bf16 v[64:67], v[168:171], v[208:211], v[64:67]
	v_mfma_f32_16x16x32_bf16 v[116:119], v[164:167], v[188:191], v[116:119]
	v_mfma_f32_16x16x32_bf16 v[112:115], v[172:175], v[188:191], v[112:115]
	v_mfma_f32_16x16x32_bf16 v[100:103], v[164:167], v[196:199], v[100:103]
	v_mfma_f32_16x16x32_bf16 v[96:99], v[172:175], v[196:199], v[96:99]
	s_setprio 2
	s_barrier
	s_add_i32 s44, s74, s51
	s_mov_b32 m0, s44
	v_lshl_add_u64 v[176:177], v[176:177], 0, s[22:23]
	global_load_lds_dwordx4 v[176:177], off
	v_mfma_f32_16x16x32_bf16 v[84:87], v[164:167], v[204:207], v[84:87]
	s_add_i32 m0, s44, 0x2000
	s_add_u32 s40, s40, 0x40080
	v_lshl_add_u64 v[176:177], v[216:217], 0, s[22:23]
	s_addc_u32 s41, s41, 0
	s_add_i32 s44, s75, s51
	global_load_lds_dwordx4 v[176:177], off
	v_mfma_f32_16x16x32_bf16 v[80:83], v[172:175], v[204:207], v[80:83]
	s_mov_b32 m0, s44
	v_lshl_add_u64 v[176:177], s[40:41], 0, v[130:131]
	global_load_lds_dwordx4 v[176:177], off
	v_mfma_f32_16x16x32_bf16 v[68:71], v[164:167], v[212:215], v[68:71]
	s_add_i32 m0, s44, 0x2000
	v_lshl_add_u64 v[176:177], s[40:41], 0, v[134:135]
	global_load_lds_dwordx4 v[176:177], off
	v_mfma_f32_16x16x32_bf16 v[64:67], v[172:175], v[212:215], v[64:67]
	ds_read_b128 v[184:187], v181 offset:49152
	ds_read_b128 v[188:191], v181 offset:50176
	ds_read_b128 v[192:195], v181 offset:51200
	ds_read_b128 v[196:199], v181 offset:52224
	ds_read_b128 v[200:203], v181 offset:53248
	ds_read_b128 v[204:207], v181 offset:54272
	ds_read_b128 v[208:211], v181 offset:55296
	ds_read_b128 v[212:215], v181 offset:56320
	s_mov_b32 m0, s64
	v_lshl_add_u64 v[176:177], v[218:219], 0, s[22:23]
	global_load_lds_dwordx4 v[176:177], off
	s_mov_b32 m0, s65
	v_lshl_add_u64 v[176:177], v[220:221], 0, s[22:23]
	global_load_lds_dwordx4 v[176:177], off
	s_waitcnt vmcnt(8)
	s_waitcnt lgkmcnt(0)
	s_barrier
	s_setprio 1
	s_waitcnt lgkmcnt(0)
	v_mfma_f32_16x16x32_bf16 v[60:63], v[144:147], v[184:187], v[60:63]
	v_mfma_f32_16x16x32_bf16 v[56:59], v[152:155], v[184:187], v[56:59]
	v_mfma_f32_16x16x32_bf16 v[44:47], v[144:147], v[192:195], v[44:47]
	v_mfma_f32_16x16x32_bf16 v[40:43], v[152:155], v[192:195], v[40:43]
	v_mfma_f32_16x16x32_bf16 v[28:31], v[144:147], v[200:203], v[28:31]
	v_mfma_f32_16x16x32_bf16 v[24:27], v[152:155], v[200:203], v[24:27]
	v_mfma_f32_16x16x32_bf16 v[12:15], v[144:147], v[208:211], v[12:15]
	v_mfma_f32_16x16x32_bf16 v[8:11], v[152:155], v[208:211], v[8:11]
	v_mfma_f32_16x16x32_bf16 v[60:63], v[148:151], v[188:191], v[60:63]
	v_mfma_f32_16x16x32_bf16 v[56:59], v[156:159], v[188:191], v[56:59]
	v_mfma_f32_16x16x32_bf16 v[44:47], v[148:151], v[196:199], v[44:47]
	v_mfma_f32_16x16x32_bf16 v[40:43], v[156:159], v[196:199], v[40:43]
	v_mfma_f32_16x16x32_bf16 v[28:31], v[148:151], v[204:207], v[28:31]
	v_mfma_f32_16x16x32_bf16 v[24:27], v[156:159], v[204:207], v[24:27]
	v_mfma_f32_16x16x32_bf16 v[12:15], v[148:151], v[212:215], v[12:15]
	v_mfma_f32_16x16x32_bf16 v[8:11], v[156:159], v[212:215], v[8:11]
	s_setprio 0
	s_setprio 1
	v_mfma_f32_16x16x32_bf16 v[52:55], v[160:163], v[184:187], v[52:55]
	v_mfma_f32_16x16x32_bf16 v[48:51], v[168:171], v[184:187], v[48:51]
	v_mfma_f32_16x16x32_bf16 v[36:39], v[160:163], v[192:195], v[36:39]
	v_mfma_f32_16x16x32_bf16 v[32:35], v[168:171], v[192:195], v[32:35]
	v_mfma_f32_16x16x32_bf16 v[20:23], v[160:163], v[200:203], v[20:23]
	v_mfma_f32_16x16x32_bf16 v[16:19], v[168:171], v[200:203], v[16:19]
	v_mfma_f32_16x16x32_bf16 v[4:7], v[160:163], v[208:211], v[4:7]
	v_mfma_f32_16x16x32_bf16 v[0:3], v[168:171], v[208:211], v[0:3]
	v_mfma_f32_16x16x32_bf16 v[52:55], v[164:167], v[188:191], v[52:55]
	v_mfma_f32_16x16x32_bf16 v[48:51], v[172:175], v[188:191], v[48:51]
	v_mfma_f32_16x16x32_bf16 v[36:39], v[164:167], v[196:199], v[36:39]
	v_mfma_f32_16x16x32_bf16 v[32:35], v[172:175], v[196:199], v[32:35]
	s_setprio 2
	s_barrier
	v_mfma_f32_16x16x32_bf16 v[20:23], v[164:167], v[204:207], v[20:23]
	v_mfma_f32_16x16x32_bf16 v[16:19], v[172:175], v[204:207], v[16:19]
	v_mfma_f32_16x16x32_bf16 v[4:7], v[164:167], v[212:215], v[4:7]
	v_mfma_f32_16x16x32_bf16 v[0:3], v[172:175], v[212:215], v[0:3]
	s_setprio 0
	s_add_i32 s73, s73, 2
	s_add_u32 s6, s6, 0x100
	s_addc_u32 s7, s7, 0
	s_add_u32 s71, s71, 0x100
	s_addc_u32 s72, s72, 0
	s_cmp_gt_u32 s73, 13
	s_cbranch_scc0 .LBB0_952

.LBB0_1145:
	s_ashr_i32 s23, s22, 31
	s_lshl_b64 s[26:27], s[22:23], 19
	s_add_u32 s26, s45, s26
	s_addc_u32 s27, s46, s27
	s_and_b64 s[28:29], s[4:5], exec
	s_cselect_b32 s23, s27, s39
	s_cselect_b32 s31, s26, s38
	s_ashr_i32 s25, s24, 31
	s_lshl_b64 s[28:29], s[24:25], 19
	s_add_u32 s28, s47, s28
	s_addc_u32 s29, s48, s29
	s_and_b64 s[42:43], s[4:5], exec
	s_cselect_b32 s25, s29, s41
	s_cselect_b32 s37, s28, s40
	s_add_u32 s38, s38, 0x40080
	s_addc_u32 s39, s39, 0
	s_add_u32 s64, s40, 0x100
	s_addc_u32 s65, s41, 0
	s_mov_b32 s66, -2
	ds_read_b128 v[120:123], v233
	ds_read_b128 v[132:135], v233 offset:1024
	ds_read_b128 v[136:139], v233 offset:2048
	ds_read_b128 v[140:143], v233 offset:3072
	ds_read_b128 v[144:147], v234
	ds_read_b128 v[148:151], v234 offset:1024
	ds_read_b128 v[152:155], v234 offset:2048
	ds_read_b128 v[156:159], v234 offset:3072
	s_add_u32 s40, s38, 0xfffc0080
	s_addc_u32 s41, s39, -1
	s_cmp_eq_u32 s66, 12
	s_cselect_b32 s43, s23, s41
	s_cselect_b32 s42, s31, s40
	s_cselect_b32 s41, s25, s65
	s_cselect_b32 s40, s37, s64
	v_lshl_add_u64 v[208:209], s[38:39], 0, v[192:193]
	s_add_i32 m0, s50, 0xc000
	ds_read_b128 v[160:163], v235
	ds_read_b128 v[164:167], v235 offset:1024
	ds_read_b128 v[168:171], v235 offset:2048
	ds_read_b128 v[172:175], v235 offset:3072
	ds_read_b128 v[176:179], v235 offset:4096
	ds_read_b128 v[180:183], v235 offset:5120
	ds_read_b128 v[200:203], v235 offset:6144
	ds_read_b128 v[204:207], v235 offset:7168
	global_load_lds_dwordx4 v[208:209], off
	s_add_i32 m0, s50, 0xe000
	v_lshl_add_u64 v[208:209], s[38:39], 0, v[194:195]
	global_load_lds_dwordx4 v[208:209], off
	s_waitcnt vmcnt(8)
	s_waitcnt lgkmcnt(0)
	s_barrier
	s_setprio 1
	s_waitcnt lgkmcnt(0)
	v_mfma_f32_16x16x32_bf16 v[128:131], v[120:123], v[160:163], 0
	v_mfma_f32_16x16x32_bf16 v[124:127], v[136:139], v[160:163], 0
	v_mfma_f32_16x16x32_bf16 v[108:111], v[120:123], v[168:171], 0
	v_mfma_f32_16x16x32_bf16 v[104:107], v[136:139], v[168:171], 0
	v_mfma_f32_16x16x32_bf16 v[92:95], v[120:123], v[176:179], 0
	v_mfma_f32_16x16x32_bf16 v[88:91], v[136:139], v[176:179], 0
	v_mfma_f32_16x16x32_bf16 v[76:79], v[120:123], v[200:203], 0
	v_mfma_f32_16x16x32_bf16 v[72:75], v[136:139], v[200:203], 0
	v_mfma_f32_16x16x32_bf16 v[128:131], v[132:135], v[164:167], v[128:131]
	v_mfma_f32_16x16x32_bf16 v[124:127], v[140:143], v[164:167], v[124:127]
	v_mfma_f32_16x16x32_bf16 v[108:111], v[132:135], v[172:175], v[108:111]
	v_mfma_f32_16x16x32_bf16 v[104:107], v[140:143], v[172:175], v[104:107]
	v_mfma_f32_16x16x32_bf16 v[92:95], v[132:135], v[180:183], v[92:95]
	v_mfma_f32_16x16x32_bf16 v[88:91], v[140:143], v[180:183], v[88:91]
	v_mfma_f32_16x16x32_bf16 v[76:79], v[132:135], v[204:207], v[76:79]
	v_mfma_f32_16x16x32_bf16 v[72:75], v[140:143], v[204:207], v[72:75]
	s_setprio 0
	s_setprio 1
	v_mfma_f32_16x16x32_bf16 v[116:119], v[144:147], v[160:163], 0
	v_mfma_f32_16x16x32_bf16 v[112:115], v[152:155], v[160:163], 0
	v_mfma_f32_16x16x32_bf16 v[100:103], v[144:147], v[168:171], 0
	v_mfma_f32_16x16x32_bf16 v[96:99], v[152:155], v[168:171], 0
	v_mfma_f32_16x16x32_bf16 v[84:87], v[144:147], v[176:179], 0
	v_mfma_f32_16x16x32_bf16 v[80:83], v[152:155], v[176:179], 0
	v_mfma_f32_16x16x32_bf16 v[68:71], v[144:147], v[200:203], 0
	v_mfma_f32_16x16x32_bf16 v[64:67], v[152:155], v[200:203], 0
	v_mfma_f32_16x16x32_bf16 v[116:119], v[148:151], v[164:167], v[116:119]
	v_mfma_f32_16x16x32_bf16 v[112:115], v[156:159], v[164:167], v[112:115]
	v_mfma_f32_16x16x32_bf16 v[100:103], v[148:151], v[172:175], v[100:103]
	v_mfma_f32_16x16x32_bf16 v[96:99], v[156:159], v[172:175], v[96:99]
	s_setprio 2
	s_barrier
	s_add_i32 s67, s62, s49
	s_mov_b32 m0, s67
	v_lshl_add_u64 v[208:209], s[40:41], 0, v[186:187]
	global_load_lds_dwordx4 v[208:209], off
	v_mfma_f32_16x16x32_bf16 v[84:87], v[148:151], v[180:183], v[84:87]
	s_add_i32 m0, s67, 0x2000
	s_add_u32 s68, s40, 0x40000
	v_lshl_add_u64 v[210:211], s[40:41], 0, v[190:191]
	s_addc_u32 s69, s41, 0
	s_add_i32 s67, s63, s49
	global_load_lds_dwordx4 v[210:211], off
	v_mfma_f32_16x16x32_bf16 v[80:83], v[156:159], v[180:183], v[80:83]
	v_lshl_add_u64 v[212:213], s[68:69], 0, v[186:187]
	s_mov_b32 m0, s67
	v_lshl_add_u64 v[214:215], s[42:43], 0, v[188:189]
	global_load_lds_dwordx4 v[212:213], off
	v_mfma_f32_16x16x32_bf16 v[68:71], v[148:151], v[204:207], v[68:71]
	s_add_i32 m0, s67, 0x2000
	v_lshl_add_u64 v[212:213], s[68:69], 0, v[190:191]
	global_load_lds_dwordx4 v[212:213], off
	v_mfma_f32_16x16x32_bf16 v[64:67], v[156:159], v[204:207], v[64:67]
	ds_read_b128 v[160:163], v235 offset:16384
	ds_read_b128 v[164:167], v235 offset:17408
	ds_read_b128 v[168:171], v235 offset:18432
	ds_read_b128 v[172:175], v235 offset:19456
	ds_read_b128 v[176:179], v235 offset:20480
	ds_read_b128 v[180:183], v235 offset:21504
	ds_read_b128 v[200:203], v235 offset:22528
	ds_read_b128 v[204:207], v235 offset:23552
	s_mov_b32 m0, s50
	v_lshl_add_u64 v[212:213], s[42:43], 0, v[184:185]
	global_load_lds_dwordx4 v[212:213], off
	s_mov_b32 m0, s51
	s_nop 0
	global_load_lds_dwordx4 v[214:215], off
	s_waitcnt vmcnt(8)
	s_waitcnt lgkmcnt(0)
	s_barrier
	s_setprio 1
	s_waitcnt lgkmcnt(0)
	v_mfma_f32_16x16x32_bf16 v[60:63], v[120:123], v[160:163], 0
	v_mfma_f32_16x16x32_bf16 v[56:59], v[136:139], v[160:163], 0
	v_mfma_f32_16x16x32_bf16 v[44:47], v[120:123], v[168:171], 0
	v_mfma_f32_16x16x32_bf16 v[40:43], v[136:139], v[168:171], 0
	v_mfma_f32_16x16x32_bf16 v[28:31], v[120:123], v[176:179], 0
	v_mfma_f32_16x16x32_bf16 v[24:27], v[136:139], v[176:179], 0
	v_mfma_f32_16x16x32_bf16 v[12:15], v[120:123], v[200:203], 0
	v_mfma_f32_16x16x32_bf16 v[8:11], v[136:139], v[200:203], 0
	v_mfma_f32_16x16x32_bf16 v[60:63], v[132:135], v[164:167], v[60:63]
	v_mfma_f32_16x16x32_bf16 v[56:59], v[140:143], v[164:167], v[56:59]
	v_mfma_f32_16x16x32_bf16 v[44:47], v[132:135], v[172:175], v[44:47]
	v_mfma_f32_16x16x32_bf16 v[40:43], v[140:143], v[172:175], v[40:43]
	v_mfma_f32_16x16x32_bf16 v[28:31], v[132:135], v[180:183], v[28:31]
	v_mfma_f32_16x16x32_bf16 v[24:27], v[140:143], v[180:183], v[24:27]
	v_mfma_f32_16x16x32_bf16 v[12:15], v[132:135], v[204:207], v[12:15]
	v_mfma_f32_16x16x32_bf16 v[8:11], v[140:143], v[204:207], v[8:11]
	s_setprio 0
	s_setprio 1
	v_mfma_f32_16x16x32_bf16 v[52:55], v[144:147], v[160:163], 0
	v_mfma_f32_16x16x32_bf16 v[48:51], v[152:155], v[160:163], 0
	v_mfma_f32_16x16x32_bf16 v[36:39], v[144:147], v[168:171], 0
	v_mfma_f32_16x16x32_bf16 v[32:35], v[152:155], v[168:171], 0
	v_mfma_f32_16x16x32_bf16 v[20:23], v[144:147], v[176:179], 0
	v_mfma_f32_16x16x32_bf16 v[16:19], v[152:155], v[176:179], 0
	v_mfma_f32_16x16x32_bf16 v[4:7], v[144:147], v[200:203], 0
	v_mfma_f32_16x16x32_bf16 v[0:3], v[152:155], v[200:203], 0
	v_mfma_f32_16x16x32_bf16 v[52:55], v[148:151], v[164:167], v[52:55]
	v_mfma_f32_16x16x32_bf16 v[48:51], v[156:159], v[164:167], v[48:51]
	v_mfma_f32_16x16x32_bf16 v[36:39], v[148:151], v[172:175], v[36:39]
	v_mfma_f32_16x16x32_bf16 v[32:35], v[156:159], v[172:175], v[32:35]
	s_setprio 2
	s_barrier
	v_mfma_f32_16x16x32_bf16 v[20:23], v[148:151], v[180:183], v[20:23]
	v_mfma_f32_16x16x32_bf16 v[16:19], v[156:159], v[180:183], v[16:19]
	v_mfma_f32_16x16x32_bf16 v[4:7], v[148:151], v[204:207], v[4:7]
	v_mfma_f32_16x16x32_bf16 v[0:3], v[156:159], v[204:207], v[0:3]
	s_setprio 0
	s_add_i32 s67, 0, 0x18000
	s_add_i32 s68, 0, 0x1c000
	v_add_u32_e32 v140, s67, v232
	v_add_u32_e32 v156, s68, v232
	ds_read_b128 v[120:123], v140
	ds_read_b128 v[132:135], v140 offset:1024
	ds_read_b128 v[136:139], v140 offset:2048
	ds_read_b128 v[140:143], v140 offset:3072
	ds_read_b128 v[144:147], v156
	ds_read_b128 v[148:151], v156 offset:1024
	ds_read_b128 v[152:155], v156 offset:2048
	ds_read_b128 v[156:159], v156 offset:3072
	s_add_u32 s42, s42, 0x40000
	s_addc_u32 s43, s43, 0
	s_mov_b32 m0, s54
	v_lshl_add_u64 v[216:217], s[42:43], 0, v[184:185]
	ds_read_b128 v[160:163], v235 offset:32768
	ds_read_b128 v[164:167], v235 offset:33792
	ds_read_b128 v[168:171], v235 offset:34816
	ds_read_b128 v[172:175], v235 offset:35840
	ds_read_b128 v[176:179], v235 offset:36864
	ds_read_b128 v[180:183], v235 offset:37888
	ds_read_b128 v[200:203], v235 offset:38912
	ds_read_b128 v[204:207], v235 offset:39936
	global_load_lds_dwordx4 v[216:217], off
	s_mov_b32 m0, s55
	v_lshl_add_u64 v[216:217], s[42:43], 0, v[188:189]
	global_load_lds_dwordx4 v[216:217], off
	s_waitcnt vmcnt(8)
	s_waitcnt lgkmcnt(0)
	s_barrier
	s_setprio 1
	s_waitcnt lgkmcnt(0)
	v_mfma_f32_16x16x32_bf16 v[128:131], v[120:123], v[160:163], v[128:131]
	v_mfma_f32_16x16x32_bf16 v[124:127], v[136:139], v[160:163], v[124:127]
	v_mfma_f32_16x16x32_bf16 v[108:111], v[120:123], v[168:171], v[108:111]
	v_mfma_f32_16x16x32_bf16 v[104:107], v[136:139], v[168:171], v[104:107]
	v_mfma_f32_16x16x32_bf16 v[92:95], v[120:123], v[176:179], v[92:95]
	v_mfma_f32_16x16x32_bf16 v[88:91], v[136:139], v[176:179], v[88:91]
	v_mfma_f32_16x16x32_bf16 v[76:79], v[120:123], v[200:203], v[76:79]
	v_mfma_f32_16x16x32_bf16 v[72:75], v[136:139], v[200:203], v[72:75]
	v_mfma_f32_16x16x32_bf16 v[128:131], v[132:135], v[164:167], v[128:131]
	v_mfma_f32_16x16x32_bf16 v[124:127], v[140:143], v[164:167], v[124:127]
	v_mfma_f32_16x16x32_bf16 v[108:111], v[132:135], v[172:175], v[108:111]
	v_mfma_f32_16x16x32_bf16 v[104:107], v[140:143], v[172:175], v[104:107]
	v_mfma_f32_16x16x32_bf16 v[92:95], v[132:135], v[180:183], v[92:95]
	v_mfma_f32_16x16x32_bf16 v[88:91], v[140:143], v[180:183], v[88:91]
	v_mfma_f32_16x16x32_bf16 v[76:79], v[132:135], v[204:207], v[76:79]
	v_mfma_f32_16x16x32_bf16 v[72:75], v[140:143], v[204:207], v[72:75]
	s_setprio 0
	s_setprio 1
	v_mfma_f32_16x16x32_bf16 v[116:119], v[144:147], v[160:163], v[116:119]
	v_mfma_f32_16x16x32_bf16 v[112:115], v[152:155], v[160:163], v[112:115]
	v_mfma_f32_16x16x32_bf16 v[100:103], v[144:147], v[168:171], v[100:103]
	v_mfma_f32_16x16x32_bf16 v[96:99], v[152:155], v[168:171], v[96:99]
	v_mfma_f32_16x16x32_bf16 v[84:87], v[144:147], v[176:179], v[84:87]
	v_mfma_f32_16x16x32_bf16 v[80:83], v[152:155], v[176:179], v[80:83]
	v_mfma_f32_16x16x32_bf16 v[68:71], v[144:147], v[200:203], v[68:71]
	v_mfma_f32_16x16x32_bf16 v[64:67], v[152:155], v[200:203], v[64:67]
	v_mfma_f32_16x16x32_bf16 v[116:119], v[148:151], v[164:167], v[116:119]
	v_mfma_f32_16x16x32_bf16 v[112:115], v[156:159], v[164:167], v[112:115]
	v_mfma_f32_16x16x32_bf16 v[100:103], v[148:151], v[172:175], v[100:103]
	v_mfma_f32_16x16x32_bf16 v[96:99], v[156:159], v[172:175], v[96:99]
	s_setprio 2
	s_barrier
	s_add_i32 s42, s67, s49
	s_mov_b32 m0, s42
	v_lshl_add_u64 v[208:209], v[208:209], 0, s[18:19]
	global_load_lds_dwordx4 v[208:209], off
	v_mfma_f32_16x16x32_bf16 v[84:87], v[148:151], v[180:183], v[84:87]
	s_add_i32 m0, s42, 0x2000
	s_add_u32 s40, s40, 0x40080
	v_lshl_add_u64 v[208:209], v[210:211], 0, s[18:19]
	s_addc_u32 s41, s41, 0
	s_add_i32 s42, s68, s49
	global_load_lds_dwordx4 v[208:209], off
	v_mfma_f32_16x16x32_bf16 v[80:83], v[156:159], v[180:183], v[80:83]
	s_mov_b32 m0, s42
	v_lshl_add_u64 v[208:209], s[40:41], 0, v[186:187]
	global_load_lds_dwordx4 v[208:209], off
	v_mfma_f32_16x16x32_bf16 v[68:71], v[148:151], v[204:207], v[68:71]
	s_add_i32 m0, s42, 0x2000
	v_lshl_add_u64 v[208:209], s[40:41], 0, v[190:191]
	global_load_lds_dwordx4 v[208:209], off
	v_mfma_f32_16x16x32_bf16 v[64:67], v[156:159], v[204:207], v[64:67]
	ds_read_b128 v[160:163], v235 offset:49152
	ds_read_b128 v[164:167], v235 offset:50176
	ds_read_b128 v[168:171], v235 offset:51200
	ds_read_b128 v[172:175], v235 offset:52224
	ds_read_b128 v[176:179], v235 offset:53248
	ds_read_b128 v[180:183], v235 offset:54272
	ds_read_b128 v[200:203], v235 offset:55296
	ds_read_b128 v[204:207], v235 offset:56320
	s_mov_b32 m0, s57
	v_lshl_add_u64 v[208:209], v[212:213], 0, s[18:19]
	global_load_lds_dwordx4 v[208:209], off
	s_mov_b32 m0, s58
	v_lshl_add_u64 v[208:209], v[214:215], 0, s[18:19]
	global_load_lds_dwordx4 v[208:209], off
	s_waitcnt vmcnt(8)
	s_waitcnt lgkmcnt(0)
	s_barrier
	s_setprio 1
	s_waitcnt lgkmcnt(0)
	v_mfma_f32_16x16x32_bf16 v[60:63], v[120:123], v[160:163], v[60:63]
	v_mfma_f32_16x16x32_bf16 v[56:59], v[136:139], v[160:163], v[56:59]
	v_mfma_f32_16x16x32_bf16 v[44:47], v[120:123], v[168:171], v[44:47]
	v_mfma_f32_16x16x32_bf16 v[40:43], v[136:139], v[168:171], v[40:43]
	v_mfma_f32_16x16x32_bf16 v[28:31], v[120:123], v[176:179], v[28:31]
	v_mfma_f32_16x16x32_bf16 v[24:27], v[136:139], v[176:179], v[24:27]
	v_mfma_f32_16x16x32_bf16 v[12:15], v[120:123], v[200:203], v[12:15]
	v_mfma_f32_16x16x32_bf16 v[8:11], v[136:139], v[200:203], v[8:11]
	v_mfma_f32_16x16x32_bf16 v[60:63], v[132:135], v[164:167], v[60:63]
	v_mfma_f32_16x16x32_bf16 v[56:59], v[140:143], v[164:167], v[56:59]
	v_mfma_f32_16x16x32_bf16 v[44:47], v[132:135], v[172:175], v[44:47]
	v_mfma_f32_16x16x32_bf16 v[40:43], v[140:143], v[172:175], v[40:43]
	v_mfma_f32_16x16x32_bf16 v[28:31], v[132:135], v[180:183], v[28:31]
	v_mfma_f32_16x16x32_bf16 v[24:27], v[140:143], v[180:183], v[24:27]
	v_mfma_f32_16x16x32_bf16 v[12:15], v[132:135], v[204:207], v[12:15]
	v_mfma_f32_16x16x32_bf16 v[8:11], v[140:143], v[204:207], v[8:11]
	s_setprio 0
	s_setprio 1
	v_mfma_f32_16x16x32_bf16 v[52:55], v[144:147], v[160:163], v[52:55]
	v_mfma_f32_16x16x32_bf16 v[48:51], v[152:155], v[160:163], v[48:51]
	v_mfma_f32_16x16x32_bf16 v[36:39], v[144:147], v[168:171], v[36:39]
	v_mfma_f32_16x16x32_bf16 v[32:35], v[152:155], v[168:171], v[32:35]
	v_mfma_f32_16x16x32_bf16 v[20:23], v[144:147], v[176:179], v[20:23]
	v_mfma_f32_16x16x32_bf16 v[16:19], v[152:155], v[176:179], v[16:19]
	v_mfma_f32_16x16x32_bf16 v[4:7], v[144:147], v[200:203], v[4:7]
	v_mfma_f32_16x16x32_bf16 v[0:3], v[152:155], v[200:203], v[0:3]
	v_mfma_f32_16x16x32_bf16 v[52:55], v[148:151], v[164:167], v[52:55]
	v_mfma_f32_16x16x32_bf16 v[48:51], v[156:159], v[164:167], v[48:51]
	v_mfma_f32_16x16x32_bf16 v[36:39], v[148:151], v[172:175], v[36:39]
	v_mfma_f32_16x16x32_bf16 v[32:35], v[156:159], v[172:175], v[32:35]
	s_setprio 2
	s_barrier
	v_mfma_f32_16x16x32_bf16 v[20:23], v[148:151], v[180:183], v[20:23]
	v_mfma_f32_16x16x32_bf16 v[16:19], v[156:159], v[180:183], v[16:19]
	v_mfma_f32_16x16x32_bf16 v[4:7], v[148:151], v[204:207], v[4:7]
	v_mfma_f32_16x16x32_bf16 v[0:3], v[156:159], v[204:207], v[0:3]
	s_setprio 0
	s_add_i32 s66, s66, 2
	s_add_u32 s38, s38, 0x100
	s_addc_u32 s39, s39, 0
	s_add_u32 s64, s64, 0x100
	s_addc_u32 s65, s65, 0
	s_cmp_gt_u32 s66, 13
.LBB0_1146:
	ds_read_b128 v[120:123], v233
	ds_read_b128 v[132:135], v233 offset:1024
	ds_read_b128 v[136:139], v233 offset:2048
	ds_read_b128 v[140:143], v233 offset:3072
	ds_read_b128 v[144:147], v234
	ds_read_b128 v[148:151], v234 offset:1024
	ds_read_b128 v[152:155], v234 offset:2048
	ds_read_b128 v[156:159], v234 offset:3072
	s_add_u32 s40, s38, 0xfffc0080
	s_addc_u32 s41, s39, -1
	s_cmp_eq_u32 s66, 12
	s_cselect_b32 s43, s23, s41
	s_cselect_b32 s42, s31, s40
	s_cselect_b32 s41, s25, s65
	s_cselect_b32 s40, s37, s64
	v_lshl_add_u64 v[208:209], s[38:39], 0, v[192:193]
	s_add_i32 m0, s50, 0xc000
	ds_read_b128 v[160:163], v235
	ds_read_b128 v[164:167], v235 offset:1024
	ds_read_b128 v[168:171], v235 offset:2048
	ds_read_b128 v[172:175], v235 offset:3072
	ds_read_b128 v[176:179], v235 offset:4096
	ds_read_b128 v[180:183], v235 offset:5120
	ds_read_b128 v[200:203], v235 offset:6144
	ds_read_b128 v[204:207], v235 offset:7168
	global_load_lds_dwordx4 v[208:209], off
	s_add_i32 m0, s50, 0xe000
	v_lshl_add_u64 v[208:209], s[38:39], 0, v[194:195]
	global_load_lds_dwordx4 v[208:209], off
	s_waitcnt vmcnt(8)
	s_waitcnt lgkmcnt(0)
	s_barrier
	s_setprio 1
	s_waitcnt lgkmcnt(0)
	v_mfma_f32_16x16x32_bf16 v[128:131], v[120:123], v[160:163], v[128:131]
	v_mfma_f32_16x16x32_bf16 v[124:127], v[136:139], v[160:163], v[124:127]
	v_mfma_f32_16x16x32_bf16 v[108:111], v[120:123], v[168:171], v[108:111]
	v_mfma_f32_16x16x32_bf16 v[104:107], v[136:139], v[168:171], v[104:107]
	v_mfma_f32_16x16x32_bf16 v[92:95], v[120:123], v[176:179], v[92:95]
	v_mfma_f32_16x16x32_bf16 v[88:91], v[136:139], v[176:179], v[88:91]
	v_mfma_f32_16x16x32_bf16 v[76:79], v[120:123], v[200:203], v[76:79]
	v_mfma_f32_16x16x32_bf16 v[72:75], v[136:139], v[200:203], v[72:75]
	v_mfma_f32_16x16x32_bf16 v[128:131], v[132:135], v[164:167], v[128:131]
	v_mfma_f32_16x16x32_bf16 v[124:127], v[140:143], v[164:167], v[124:127]
	v_mfma_f32_16x16x32_bf16 v[108:111], v[132:135], v[172:175], v[108:111]
	v_mfma_f32_16x16x32_bf16 v[104:107], v[140:143], v[172:175], v[104:107]
	v_mfma_f32_16x16x32_bf16 v[92:95], v[132:135], v[180:183], v[92:95]
	v_mfma_f32_16x16x32_bf16 v[88:91], v[140:143], v[180:183], v[88:91]
	v_mfma_f32_16x16x32_bf16 v[76:79], v[132:135], v[204:207], v[76:79]
	v_mfma_f32_16x16x32_bf16 v[72:75], v[140:143], v[204:207], v[72:75]
	s_setprio 0
	s_setprio 1
	v_mfma_f32_16x16x32_bf16 v[116:119], v[144:147], v[160:163], v[116:119]
	v_mfma_f32_16x16x32_bf16 v[112:115], v[152:155], v[160:163], v[112:115]
	v_mfma_f32_16x16x32_bf16 v[100:103], v[144:147], v[168:171], v[100:103]
	v_mfma_f32_16x16x32_bf16 v[96:99], v[152:155], v[168:171], v[96:99]
	v_mfma_f32_16x16x32_bf16 v[84:87], v[144:147], v[176:179], v[84:87]
	v_mfma_f32_16x16x32_bf16 v[80:83], v[152:155], v[176:179], v[80:83]
	v_mfma_f32_16x16x32_bf16 v[68:71], v[144:147], v[200:203], v[68:71]
	v_mfma_f32_16x16x32_bf16 v[64:67], v[152:155], v[200:203], v[64:67]
	v_mfma_f32_16x16x32_bf16 v[116:119], v[148:151], v[164:167], v[116:119]
	v_mfma_f32_16x16x32_bf16 v[112:115], v[156:159], v[164:167], v[112:115]
	v_mfma_f32_16x16x32_bf16 v[100:103], v[148:151], v[172:175], v[100:103]
	v_mfma_f32_16x16x32_bf16 v[96:99], v[156:159], v[172:175], v[96:99]
	s_setprio 2
	s_barrier
	s_add_i32 s67, s62, s49
	s_mov_b32 m0, s67
	v_lshl_add_u64 v[208:209], s[40:41], 0, v[186:187]
	global_load_lds_dwordx4 v[208:209], off
	v_mfma_f32_16x16x32_bf16 v[84:87], v[148:151], v[180:183], v[84:87]
	s_add_i32 m0, s67, 0x2000
	s_add_u32 s68, s40, 0x40000
	v_lshl_add_u64 v[210:211], s[40:41], 0, v[190:191]
	s_addc_u32 s69, s41, 0
	s_add_i32 s67, s63, s49
	global_load_lds_dwordx4 v[210:211], off
	v_mfma_f32_16x16x32_bf16 v[80:83], v[156:159], v[180:183], v[80:83]
	v_lshl_add_u64 v[212:213], s[68:69], 0, v[186:187]
	s_mov_b32 m0, s67
	v_lshl_add_u64 v[214:215], s[42:43], 0, v[188:189]
	global_load_lds_dwordx4 v[212:213], off
	v_mfma_f32_16x16x32_bf16 v[68:71], v[148:151], v[204:207], v[68:71]
	s_add_i32 m0, s67, 0x2000
	v_lshl_add_u64 v[212:213], s[68:69], 0, v[190:191]
	global_load_lds_dwordx4 v[212:213], off
	v_mfma_f32_16x16x32_bf16 v[64:67], v[156:159], v[204:207], v[64:67]
	ds_read_b128 v[160:163], v235 offset:16384
	ds_read_b128 v[164:167], v235 offset:17408
	ds_read_b128 v[168:171], v235 offset:18432
	ds_read_b128 v[172:175], v235 offset:19456
	ds_read_b128 v[176:179], v235 offset:20480
	ds_read_b128 v[180:183], v235 offset:21504
	ds_read_b128 v[200:203], v235 offset:22528
	ds_read_b128 v[204:207], v235 offset:23552
	s_mov_b32 m0, s50
	v_lshl_add_u64 v[212:213], s[42:43], 0, v[184:185]
	global_load_lds_dwordx4 v[212:213], off
	s_mov_b32 m0, s51
	s_nop 0
	global_load_lds_dwordx4 v[214:215], off
	s_waitcnt vmcnt(8)
	s_waitcnt lgkmcnt(0)
	s_barrier
	s_setprio 1
	s_waitcnt lgkmcnt(0)
	v_mfma_f32_16x16x32_bf16 v[60:63], v[120:123], v[160:163], v[60:63]
	v_mfma_f32_16x16x32_bf16 v[56:59], v[136:139], v[160:163], v[56:59]
	v_mfma_f32_16x16x32_bf16 v[44:47], v[120:123], v[168:171], v[44:47]
	v_mfma_f32_16x16x32_bf16 v[40:43], v[136:139], v[168:171], v[40:43]
	v_mfma_f32_16x16x32_bf16 v[28:31], v[120:123], v[176:179], v[28:31]
	v_mfma_f32_16x16x32_bf16 v[24:27], v[136:139], v[176:179], v[24:27]
	v_mfma_f32_16x16x32_bf16 v[12:15], v[120:123], v[200:203], v[12:15]
	v_mfma_f32_16x16x32_bf16 v[8:11], v[136:139], v[200:203], v[8:11]
	v_mfma_f32_16x16x32_bf16 v[60:63], v[132:135], v[164:167], v[60:63]
	v_mfma_f32_16x16x32_bf16 v[56:59], v[140:143], v[164:167], v[56:59]
	v_mfma_f32_16x16x32_bf16 v[44:47], v[132:135], v[172:175], v[44:47]
	v_mfma_f32_16x16x32_bf16 v[40:43], v[140:143], v[172:175], v[40:43]
	v_mfma_f32_16x16x32_bf16 v[28:31], v[132:135], v[180:183], v[28:31]
	v_mfma_f32_16x16x32_bf16 v[24:27], v[140:143], v[180:183], v[24:27]
	v_mfma_f32_16x16x32_bf16 v[12:15], v[132:135], v[204:207], v[12:15]
	v_mfma_f32_16x16x32_bf16 v[8:11], v[140:143], v[204:207], v[8:11]
	s_setprio 0
	s_setprio 1
	v_mfma_f32_16x16x32_bf16 v[52:55], v[144:147], v[160:163], v[52:55]
	v_mfma_f32_16x16x32_bf16 v[48:51], v[152:155], v[160:163], v[48:51]
	v_mfma_f32_16x16x32_bf16 v[36:39], v[144:147], v[168:171], v[36:39]
	v_mfma_f32_16x16x32_bf16 v[32:35], v[152:155], v[168:171], v[32:35]
	v_mfma_f32_16x16x32_bf16 v[20:23], v[144:147], v[176:179], v[20:23]
	v_mfma_f32_16x16x32_bf16 v[16:19], v[152:155], v[176:179], v[16:19]
	v_mfma_f32_16x16x32_bf16 v[4:7], v[144:147], v[200:203], v[4:7]
	v_mfma_f32_16x16x32_bf16 v[0:3], v[152:155], v[200:203], v[0:3]
	v_mfma_f32_16x16x32_bf16 v[52:55], v[148:151], v[164:167], v[52:55]
	v_mfma_f32_16x16x32_bf16 v[48:51], v[156:159], v[164:167], v[48:51]
	v_mfma_f32_16x16x32_bf16 v[36:39], v[148:151], v[172:175], v[36:39]
	v_mfma_f32_16x16x32_bf16 v[32:35], v[156:159], v[172:175], v[32:35]
	s_setprio 2
	s_barrier
	v_mfma_f32_16x16x32_bf16 v[20:23], v[148:151], v[180:183], v[20:23]
	v_mfma_f32_16x16x32_bf16 v[16:19], v[156:159], v[180:183], v[16:19]
	v_mfma_f32_16x16x32_bf16 v[4:7], v[148:151], v[204:207], v[4:7]
	v_mfma_f32_16x16x32_bf16 v[0:3], v[156:159], v[204:207], v[0:3]
	s_setprio 0
	s_add_i32 s67, 0, 0x18000
	s_add_i32 s68, 0, 0x1c000
	v_add_u32_e32 v140, s67, v232
	v_add_u32_e32 v156, s68, v232
	ds_read_b128 v[120:123], v140
	ds_read_b128 v[132:135], v140 offset:1024
	ds_read_b128 v[136:139], v140 offset:2048
	ds_read_b128 v[140:143], v140 offset:3072
	ds_read_b128 v[144:147], v156
	ds_read_b128 v[148:151], v156 offset:1024
	ds_read_b128 v[152:155], v156 offset:2048
	ds_read_b128 v[156:159], v156 offset:3072
	s_add_u32 s42, s42, 0x40000
	s_addc_u32 s43, s43, 0
	s_mov_b32 m0, s54
	v_lshl_add_u64 v[216:217], s[42:43], 0, v[184:185]
	ds_read_b128 v[160:163], v235 offset:32768
	ds_read_b128 v[164:167], v235 offset:33792
	ds_read_b128 v[168:171], v235 offset:34816
	ds_read_b128 v[172:175], v235 offset:35840
	ds_read_b128 v[176:179], v235 offset:36864
	ds_read_b128 v[180:183], v235 offset:37888
	ds_read_b128 v[200:203], v235 offset:38912
	ds_read_b128 v[204:207], v235 offset:39936
	global_load_lds_dwordx4 v[216:217], off
	s_mov_b32 m0, s55
	v_lshl_add_u64 v[216:217], s[42:43], 0, v[188:189]
	global_load_lds_dwordx4 v[216:217], off
	s_waitcnt vmcnt(8)
	s_waitcnt lgkmcnt(0)
	s_barrier
	s_setprio 1
	s_waitcnt lgkmcnt(0)
	v_mfma_f32_16x16x32_bf16 v[128:131], v[120:123], v[160:163], v[128:131]
	v_mfma_f32_16x16x32_bf16 v[124:127], v[136:139], v[160:163], v[124:127]
	v_mfma_f32_16x16x32_bf16 v[108:111], v[120:123], v[168:171], v[108:111]
	v_mfma_f32_16x16x32_bf16 v[104:107], v[136:139], v[168:171], v[104:107]
	v_mfma_f32_16x16x32_bf16 v[92:95], v[120:123], v[176:179], v[92:95]
	v_mfma_f32_16x16x32_bf16 v[88:91], v[136:139], v[176:179], v[88:91]
	v_mfma_f32_16x16x32_bf16 v[76:79], v[120:123], v[200:203], v[76:79]
	v_mfma_f32_16x16x32_bf16 v[72:75], v[136:139], v[200:203], v[72:75]
	v_mfma_f32_16x16x32_bf16 v[128:131], v[132:135], v[164:167], v[128:131]
	v_mfma_f32_16x16x32_bf16 v[124:127], v[140:143], v[164:167], v[124:127]
	v_mfma_f32_16x16x32_bf16 v[108:111], v[132:135], v[172:175], v[108:111]
	v_mfma_f32_16x16x32_bf16 v[104:107], v[140:143], v[172:175], v[104:107]
	v_mfma_f32_16x16x32_bf16 v[92:95], v[132:135], v[180:183], v[92:95]
	v_mfma_f32_16x16x32_bf16 v[88:91], v[140:143], v[180:183], v[88:91]
	v_mfma_f32_16x16x32_bf16 v[76:79], v[132:135], v[204:207], v[76:79]
	v_mfma_f32_16x16x32_bf16 v[72:75], v[140:143], v[204:207], v[72:75]
	s_setprio 0
	s_setprio 1
	v_mfma_f32_16x16x32_bf16 v[116:119], v[144:147], v[160:163], v[116:119]
	v_mfma_f32_16x16x32_bf16 v[112:115], v[152:155], v[160:163], v[112:115]
	v_mfma_f32_16x16x32_bf16 v[100:103], v[144:147], v[168:171], v[100:103]
	v_mfma_f32_16x16x32_bf16 v[96:99], v[152:155], v[168:171], v[96:99]
	v_mfma_f32_16x16x32_bf16 v[84:87], v[144:147], v[176:179], v[84:87]
	v_mfma_f32_16x16x32_bf16 v[80:83], v[152:155], v[176:179], v[80:83]
	v_mfma_f32_16x16x32_bf16 v[68:71], v[144:147], v[200:203], v[68:71]
	v_mfma_f32_16x16x32_bf16 v[64:67], v[152:155], v[200:203], v[64:67]
	v_mfma_f32_16x16x32_bf16 v[116:119], v[148:151], v[164:167], v[116:119]
	v_mfma_f32_16x16x32_bf16 v[112:115], v[156:159], v[164:167], v[112:115]
	v_mfma_f32_16x16x32_bf16 v[100:103], v[148:151], v[172:175], v[100:103]
	v_mfma_f32_16x16x32_bf16 v[96:99], v[156:159], v[172:175], v[96:99]
	s_setprio 2
	s_barrier
	s_add_i32 s42, s67, s49
	s_mov_b32 m0, s42
	v_lshl_add_u64 v[208:209], v[208:209], 0, s[18:19]
	global_load_lds_dwordx4 v[208:209], off
	v_mfma_f32_16x16x32_bf16 v[84:87], v[148:151], v[180:183], v[84:87]
	s_add_i32 m0, s42, 0x2000
	s_add_u32 s40, s40, 0x40080
	v_lshl_add_u64 v[208:209], v[210:211], 0, s[18:19]
	s_addc_u32 s41, s41, 0
	s_add_i32 s42, s68, s49
	global_load_lds_dwordx4 v[208:209], off
	v_mfma_f32_16x16x32_bf16 v[80:83], v[156:159], v[180:183], v[80:83]
	s_mov_b32 m0, s42
	v_lshl_add_u64 v[208:209], s[40:41], 0, v[186:187]
	global_load_lds_dwordx4 v[208:209], off
	v_mfma_f32_16x16x32_bf16 v[68:71], v[148:151], v[204:207], v[68:71]
	s_add_i32 m0, s42, 0x2000
	v_lshl_add_u64 v[208:209], s[40:41], 0, v[190:191]
	global_load_lds_dwordx4 v[208:209], off
	v_mfma_f32_16x16x32_bf16 v[64:67], v[156:159], v[204:207], v[64:67]
	ds_read_b128 v[160:163], v235 offset:49152
	ds_read_b128 v[164:167], v235 offset:50176
	ds_read_b128 v[168:171], v235 offset:51200
	ds_read_b128 v[172:175], v235 offset:52224
	ds_read_b128 v[176:179], v235 offset:53248
	ds_read_b128 v[180:183], v235 offset:54272
	ds_read_b128 v[200:203], v235 offset:55296
	ds_read_b128 v[204:207], v235 offset:56320
	s_mov_b32 m0, s57
	v_lshl_add_u64 v[208:209], v[212:213], 0, s[18:19]
	global_load_lds_dwordx4 v[208:209], off
	s_mov_b32 m0, s58
	v_lshl_add_u64 v[208:209], v[214:215], 0, s[18:19]
	global_load_lds_dwordx4 v[208:209], off
	s_waitcnt vmcnt(8)
	s_waitcnt lgkmcnt(0)
	s_barrier
	s_setprio 1
	s_waitcnt lgkmcnt(0)
	v_mfma_f32_16x16x32_bf16 v[60:63], v[120:123], v[160:163], v[60:63]
	v_mfma_f32_16x16x32_bf16 v[56:59], v[136:139], v[160:163], v[56:59]
	v_mfma_f32_16x16x32_bf16 v[44:47], v[120:123], v[168:171], v[44:47]
	v_mfma_f32_16x16x32_bf16 v[40:43], v[136:139], v[168:171], v[40:43]
	v_mfma_f32_16x16x32_bf16 v[28:31], v[120:123], v[176:179], v[28:31]
	v_mfma_f32_16x16x32_bf16 v[24:27], v[136:139], v[176:179], v[24:27]
	v_mfma_f32_16x16x32_bf16 v[12:15], v[120:123], v[200:203], v[12:15]
	v_mfma_f32_16x16x32_bf16 v[8:11], v[136:139], v[200:203], v[8:11]
	v_mfma_f32_16x16x32_bf16 v[60:63], v[132:135], v[164:167], v[60:63]
	v_mfma_f32_16x16x32_bf16 v[56:59], v[140:143], v[164:167], v[56:59]
	v_mfma_f32_16x16x32_bf16 v[44:47], v[132:135], v[172:175], v[44:47]
	v_mfma_f32_16x16x32_bf16 v[40:43], v[140:143], v[172:175], v[40:43]
	v_mfma_f32_16x16x32_bf16 v[28:31], v[132:135], v[180:183], v[28:31]
	v_mfma_f32_16x16x32_bf16 v[24:27], v[140:143], v[180:183], v[24:27]
	v_mfma_f32_16x16x32_bf16 v[12:15], v[132:135], v[204:207], v[12:15]
	v_mfma_f32_16x16x32_bf16 v[8:11], v[140:143], v[204:207], v[8:11]
	s_setprio 0
	s_setprio 1
	v_mfma_f32_16x16x32_bf16 v[52:55], v[144:147], v[160:163], v[52:55]
	v_mfma_f32_16x16x32_bf16 v[48:51], v[152:155], v[160:163], v[48:51]
	v_mfma_f32_16x16x32_bf16 v[36:39], v[144:147], v[168:171], v[36:39]
	v_mfma_f32_16x16x32_bf16 v[32:35], v[152:155], v[168:171], v[32:35]
	v_mfma_f32_16x16x32_bf16 v[20:23], v[144:147], v[176:179], v[20:23]
	v_mfma_f32_16x16x32_bf16 v[16:19], v[152:155], v[176:179], v[16:19]
	v_mfma_f32_16x16x32_bf16 v[4:7], v[144:147], v[200:203], v[4:7]
	v_mfma_f32_16x16x32_bf16 v[0:3], v[152:155], v[200:203], v[0:3]
	v_mfma_f32_16x16x32_bf16 v[52:55], v[148:151], v[164:167], v[52:55]
	v_mfma_f32_16x16x32_bf16 v[48:51], v[156:159], v[164:167], v[48:51]
	v_mfma_f32_16x16x32_bf16 v[36:39], v[148:151], v[172:175], v[36:39]
	v_mfma_f32_16x16x32_bf16 v[32:35], v[156:159], v[172:175], v[32:35]
	s_setprio 2
	s_barrier
	v_mfma_f32_16x16x32_bf16 v[20:23], v[148:151], v[180:183], v[20:23]
	v_mfma_f32_16x16x32_bf16 v[16:19], v[156:159], v[180:183], v[16:19]
	v_mfma_f32_16x16x32_bf16 v[4:7], v[148:151], v[204:207], v[4:7]
	v_mfma_f32_16x16x32_bf16 v[0:3], v[156:159], v[204:207], v[0:3]
	s_setprio 0
	s_add_i32 s66, s66, 2
	s_add_u32 s38, s38, 0x100
	s_addc_u32 s39, s39, 0
	s_add_u32 s64, s64, 0x100
	s_addc_u32 s65, s65, 0
	s_cmp_gt_u32 s66, 13
	s_cbranch_scc0 .LBB0_1146

.LBB0_1309:
	s_add_u32 s51, s26, 0x100
	s_addc_u32 s52, s27, 0
	s_mov_b32 s53, -2
	ds_read_b128 v[128:131], v197
	ds_read_b128 v[132:135], v197 offset:1024
	ds_read_b128 v[136:139], v197 offset:2048
	ds_read_b128 v[140:143], v197 offset:3072
	ds_read_b128 v[144:147], v198
	ds_read_b128 v[148:151], v198 offset:1024
	ds_read_b128 v[152:155], v198 offset:2048
	ds_read_b128 v[156:159], v198 offset:3072
	s_add_u32 s4, s24, 0x100
	s_addc_u32 s5, s25, 0
	s_cmp_eq_u32 s53, 40
	s_cselect_b32 s29, s21, s5
	s_cselect_b32 s28, s20, s4
	s_cselect_b32 s27, s23, s52
	s_cselect_b32 s26, s22, s51
	v_lshl_add_u64 v[212:213], s[24:25], 0, v[172:173]
	s_add_i32 m0, s36, 0xc000
	ds_read_b128 v[160:163], v199
	ds_read_b128 v[180:183], v199 offset:1024
	ds_read_b128 v[184:187], v199 offset:2048
	ds_read_b128 v[188:191], v199 offset:3072
	ds_read_b128 v[192:195], v199 offset:4096
	ds_read_b128 v[200:203], v199 offset:5120
	ds_read_b128 v[204:207], v199 offset:6144
	ds_read_b128 v[208:211], v199 offset:7168
	global_load_lds_dwordx4 v[212:213], off
	s_add_i32 m0, s36, 0xe000
	v_lshl_add_u64 v[212:213], s[24:25], 0, v[174:175]
	global_load_lds_dwordx4 v[212:213], off
	s_waitcnt vmcnt(8)
	s_waitcnt lgkmcnt(0)
	s_barrier
	s_setprio 1
	s_waitcnt lgkmcnt(0)
	v_mfma_f32_16x16x32_bf16 v[124:127], v[128:131], v[160:163], 0
	v_mfma_f32_16x16x32_bf16 v[120:123], v[136:139], v[160:163], 0
	v_mfma_f32_16x16x32_bf16 v[116:119], v[128:131], v[184:187], 0
	v_mfma_f32_16x16x32_bf16 v[108:111], v[136:139], v[184:187], 0
	v_mfma_f32_16x16x32_bf16 v[88:91], v[128:131], v[192:195], 0
	v_mfma_f32_16x16x32_bf16 v[100:103], v[136:139], v[192:195], 0
	v_mfma_f32_16x16x32_bf16 v[72:75], v[128:131], v[204:207], 0
	v_mfma_f32_16x16x32_bf16 v[76:79], v[136:139], v[204:207], 0
	v_mfma_f32_16x16x32_bf16 v[124:127], v[132:135], v[180:183], v[124:127]
	v_mfma_f32_16x16x32_bf16 v[120:123], v[140:143], v[180:183], v[120:123]
	v_mfma_f32_16x16x32_bf16 v[116:119], v[132:135], v[188:191], v[116:119]
	v_mfma_f32_16x16x32_bf16 v[108:111], v[140:143], v[188:191], v[108:111]
	v_mfma_f32_16x16x32_bf16 v[88:91], v[132:135], v[200:203], v[88:91]
	v_mfma_f32_16x16x32_bf16 v[100:103], v[140:143], v[200:203], v[100:103]
	v_mfma_f32_16x16x32_bf16 v[72:75], v[132:135], v[208:211], v[72:75]
	v_mfma_f32_16x16x32_bf16 v[76:79], v[140:143], v[208:211], v[76:79]
	s_setprio 0
	s_setprio 1
	v_mfma_f32_16x16x32_bf16 v[112:115], v[144:147], v[160:163], 0
	v_mfma_f32_16x16x32_bf16 v[104:107], v[152:155], v[160:163], 0
	v_mfma_f32_16x16x32_bf16 v[96:99], v[144:147], v[184:187], 0
	v_mfma_f32_16x16x32_bf16 v[92:95], v[152:155], v[184:187], 0
	v_mfma_f32_16x16x32_bf16 v[80:83], v[144:147], v[192:195], 0
	v_mfma_f32_16x16x32_bf16 v[84:87], v[152:155], v[192:195], 0
	v_mfma_f32_16x16x32_bf16 v[64:67], v[144:147], v[204:207], 0
	v_mfma_f32_16x16x32_bf16 v[68:71], v[152:155], v[204:207], 0
	v_mfma_f32_16x16x32_bf16 v[112:115], v[148:151], v[180:183], v[112:115]
	v_mfma_f32_16x16x32_bf16 v[104:107], v[156:159], v[180:183], v[104:107]
	v_mfma_f32_16x16x32_bf16 v[96:99], v[148:151], v[188:191], v[96:99]
	v_mfma_f32_16x16x32_bf16 v[92:95], v[156:159], v[188:191], v[92:95]
	s_setprio 2
	s_barrier
	s_add_i32 s24, s45, s35
	s_mov_b32 m0, s24
	v_lshl_add_u64 v[212:213], s[26:27], 0, v[166:167]
	global_load_lds_dwordx4 v[212:213], off
	v_mfma_f32_16x16x32_bf16 v[80:83], v[148:151], v[200:203], v[80:83]
	s_add_i32 m0, s24, 0x2000
	s_add_u32 s24, s26, 0xb0000
	v_lshl_add_u64 v[214:215], s[26:27], 0, v[170:171]
	s_addc_u32 s25, s27, 0
	s_add_i32 s54, s46, s35
	global_load_lds_dwordx4 v[214:215], off
	v_mfma_f32_16x16x32_bf16 v[84:87], v[156:159], v[200:203], v[84:87]
	v_lshl_add_u64 v[216:217], s[24:25], 0, v[166:167]
	s_mov_b32 m0, s54
	v_lshl_add_u64 v[218:219], s[28:29], 0, v[168:169]
	global_load_lds_dwordx4 v[216:217], off
	v_mfma_f32_16x16x32_bf16 v[64:67], v[148:151], v[208:211], v[64:67]
	s_add_i32 m0, s54, 0x2000
	v_lshl_add_u64 v[216:217], s[24:25], 0, v[170:171]
	global_load_lds_dwordx4 v[216:217], off
	v_mfma_f32_16x16x32_bf16 v[68:71], v[156:159], v[208:211], v[68:71]
	ds_read_b128 v[160:163], v199 offset:16384
	ds_read_b128 v[180:183], v199 offset:17408
	ds_read_b128 v[184:187], v199 offset:18432
	ds_read_b128 v[188:191], v199 offset:19456
	ds_read_b128 v[192:195], v199 offset:20480
	ds_read_b128 v[200:203], v199 offset:21504
	ds_read_b128 v[204:207], v199 offset:22528
	ds_read_b128 v[208:211], v199 offset:23552
	s_mov_b32 m0, s36
	v_lshl_add_u64 v[216:217], s[28:29], 0, v[164:165]
	global_load_lds_dwordx4 v[216:217], off
	s_mov_b32 m0, s37
	s_nop 0
	global_load_lds_dwordx4 v[218:219], off
	s_waitcnt vmcnt(8)
	s_waitcnt lgkmcnt(0)
	s_barrier
	s_setprio 1
	s_waitcnt lgkmcnt(0)
	v_mfma_f32_16x16x32_bf16 v[56:59], v[128:131], v[160:163], 0
	v_mfma_f32_16x16x32_bf16 v[60:63], v[136:139], v[160:163], 0
	v_mfma_f32_16x16x32_bf16 v[40:43], v[128:131], v[184:187], 0
	v_mfma_f32_16x16x32_bf16 v[44:47], v[136:139], v[184:187], 0
	v_mfma_f32_16x16x32_bf16 v[24:27], v[128:131], v[192:195], 0
	v_mfma_f32_16x16x32_bf16 v[28:31], v[136:139], v[192:195], 0
	v_mfma_f32_16x16x32_bf16 v[8:11], v[128:131], v[204:207], 0
	v_mfma_f32_16x16x32_bf16 v[12:15], v[136:139], v[204:207], 0
	v_mfma_f32_16x16x32_bf16 v[56:59], v[132:135], v[180:183], v[56:59]
	v_mfma_f32_16x16x32_bf16 v[60:63], v[140:143], v[180:183], v[60:63]
	v_mfma_f32_16x16x32_bf16 v[40:43], v[132:135], v[188:191], v[40:43]
	v_mfma_f32_16x16x32_bf16 v[44:47], v[140:143], v[188:191], v[44:47]
	v_mfma_f32_16x16x32_bf16 v[24:27], v[132:135], v[200:203], v[24:27]
	v_mfma_f32_16x16x32_bf16 v[28:31], v[140:143], v[200:203], v[28:31]
	v_mfma_f32_16x16x32_bf16 v[8:11], v[132:135], v[208:211], v[8:11]
	v_mfma_f32_16x16x32_bf16 v[12:15], v[140:143], v[208:211], v[12:15]
	s_setprio 0
	s_setprio 1
	v_mfma_f32_16x16x32_bf16 v[48:51], v[144:147], v[160:163], 0
	v_mfma_f32_16x16x32_bf16 v[52:55], v[152:155], v[160:163], 0
	v_mfma_f32_16x16x32_bf16 v[32:35], v[144:147], v[184:187], 0
	v_mfma_f32_16x16x32_bf16 v[36:39], v[152:155], v[184:187], 0
	v_mfma_f32_16x16x32_bf16 v[16:19], v[144:147], v[192:195], 0
	v_mfma_f32_16x16x32_bf16 v[20:23], v[152:155], v[192:195], 0
	v_mfma_f32_16x16x32_bf16 v[0:3], v[144:147], v[204:207], 0
	v_mfma_f32_16x16x32_bf16 v[4:7], v[152:155], v[204:207], 0
	v_mfma_f32_16x16x32_bf16 v[48:51], v[148:151], v[180:183], v[48:51]
	v_mfma_f32_16x16x32_bf16 v[52:55], v[156:159], v[180:183], v[52:55]
	v_mfma_f32_16x16x32_bf16 v[32:35], v[148:151], v[188:191], v[32:35]
	v_mfma_f32_16x16x32_bf16 v[36:39], v[156:159], v[188:191], v[36:39]
	s_setprio 2
	s_barrier
	v_mfma_f32_16x16x32_bf16 v[16:19], v[148:151], v[200:203], v[16:19]
	v_mfma_f32_16x16x32_bf16 v[20:23], v[156:159], v[200:203], v[20:23]
	v_mfma_f32_16x16x32_bf16 v[0:3], v[148:151], v[208:211], v[0:3]
	v_mfma_f32_16x16x32_bf16 v[4:7], v[156:159], v[208:211], v[4:7]
	s_setprio 0
	s_add_i32 s54, 0, 0x18000
	s_add_i32 s55, 0, 0x1c000
	v_add_u32_e32 v140, s54, v196
	v_add_u32_e32 v156, s55, v196
	ds_read_b128 v[128:131], v140
	ds_read_b128 v[132:135], v140 offset:1024
	ds_read_b128 v[136:139], v140 offset:2048
	ds_read_b128 v[140:143], v140 offset:3072
	ds_read_b128 v[144:147], v156
	ds_read_b128 v[148:151], v156 offset:1024
	ds_read_b128 v[152:155], v156 offset:2048
	ds_read_b128 v[156:159], v156 offset:3072
	s_add_u32 s24, s28, 0xb0000
	s_addc_u32 s25, s29, 0
	s_mov_b32 m0, s38
	v_lshl_add_u64 v[220:221], s[24:25], 0, v[164:165]
	ds_read_b128 v[160:163], v199 offset:32768
	ds_read_b128 v[180:183], v199 offset:33792
	ds_read_b128 v[184:187], v199 offset:34816
	ds_read_b128 v[188:191], v199 offset:35840
	ds_read_b128 v[192:195], v199 offset:36864
	ds_read_b128 v[200:203], v199 offset:37888
	ds_read_b128 v[204:207], v199 offset:38912
	ds_read_b128 v[208:211], v199 offset:39936
	global_load_lds_dwordx4 v[220:221], off
	s_mov_b32 m0, s39
	v_lshl_add_u64 v[220:221], s[24:25], 0, v[168:169]
	global_load_lds_dwordx4 v[220:221], off
	s_waitcnt vmcnt(8)
	s_waitcnt lgkmcnt(0)
	s_barrier
	s_setprio 1
	s_waitcnt lgkmcnt(0)
	v_mfma_f32_16x16x32_bf16 v[124:127], v[128:131], v[160:163], v[124:127]
	v_mfma_f32_16x16x32_bf16 v[120:123], v[136:139], v[160:163], v[120:123]
	v_mfma_f32_16x16x32_bf16 v[116:119], v[128:131], v[184:187], v[116:119]
	v_mfma_f32_16x16x32_bf16 v[108:111], v[136:139], v[184:187], v[108:111]
	v_mfma_f32_16x16x32_bf16 v[88:91], v[128:131], v[192:195], v[88:91]
	v_mfma_f32_16x16x32_bf16 v[100:103], v[136:139], v[192:195], v[100:103]
	v_mfma_f32_16x16x32_bf16 v[72:75], v[128:131], v[204:207], v[72:75]
	v_mfma_f32_16x16x32_bf16 v[76:79], v[136:139], v[204:207], v[76:79]
	v_mfma_f32_16x16x32_bf16 v[124:127], v[132:135], v[180:183], v[124:127]
	v_mfma_f32_16x16x32_bf16 v[120:123], v[140:143], v[180:183], v[120:123]
	v_mfma_f32_16x16x32_bf16 v[116:119], v[132:135], v[188:191], v[116:119]
	v_mfma_f32_16x16x32_bf16 v[108:111], v[140:143], v[188:191], v[108:111]
	v_mfma_f32_16x16x32_bf16 v[88:91], v[132:135], v[200:203], v[88:91]
	v_mfma_f32_16x16x32_bf16 v[100:103], v[140:143], v[200:203], v[100:103]
	v_mfma_f32_16x16x32_bf16 v[72:75], v[132:135], v[208:211], v[72:75]
	v_mfma_f32_16x16x32_bf16 v[76:79], v[140:143], v[208:211], v[76:79]
	s_setprio 0
	s_setprio 1
	v_mfma_f32_16x16x32_bf16 v[112:115], v[144:147], v[160:163], v[112:115]
	v_mfma_f32_16x16x32_bf16 v[104:107], v[152:155], v[160:163], v[104:107]
	v_mfma_f32_16x16x32_bf16 v[96:99], v[144:147], v[184:187], v[96:99]
	v_mfma_f32_16x16x32_bf16 v[92:95], v[152:155], v[184:187], v[92:95]
	v_mfma_f32_16x16x32_bf16 v[80:83], v[144:147], v[192:195], v[80:83]
	v_mfma_f32_16x16x32_bf16 v[84:87], v[152:155], v[192:195], v[84:87]
	v_mfma_f32_16x16x32_bf16 v[64:67], v[144:147], v[204:207], v[64:67]
	v_mfma_f32_16x16x32_bf16 v[68:71], v[152:155], v[204:207], v[68:71]
	v_mfma_f32_16x16x32_bf16 v[112:115], v[148:151], v[180:183], v[112:115]
	v_mfma_f32_16x16x32_bf16 v[104:107], v[156:159], v[180:183], v[104:107]
	v_mfma_f32_16x16x32_bf16 v[96:99], v[148:151], v[188:191], v[96:99]
	v_mfma_f32_16x16x32_bf16 v[92:95], v[156:159], v[188:191], v[92:95]
	s_setprio 2
	s_barrier
	s_add_i32 s24, s54, s35
	s_mov_b32 m0, s24
	v_lshl_add_u64 v[212:213], v[212:213], 0, s[16:17]
	global_load_lds_dwordx4 v[212:213], off
	v_mfma_f32_16x16x32_bf16 v[80:83], v[148:151], v[200:203], v[80:83]
	s_add_i32 m0, s24, 0x2000
	s_add_u32 s24, s26, 0xb0080
	v_lshl_add_u64 v[212:213], v[214:215], 0, s[16:17]
	s_addc_u32 s25, s27, 0
	s_add_i32 s26, s55, s35
	global_load_lds_dwordx4 v[212:213], off
	v_mfma_f32_16x16x32_bf16 v[84:87], v[156:159], v[200:203], v[84:87]
	s_mov_b32 m0, s26
	v_lshl_add_u64 v[212:213], s[24:25], 0, v[166:167]
	global_load_lds_dwordx4 v[212:213], off
	v_mfma_f32_16x16x32_bf16 v[64:67], v[148:151], v[208:211], v[64:67]
	s_add_i32 m0, s26, 0x2000
	v_lshl_add_u64 v[212:213], s[24:25], 0, v[170:171]
	global_load_lds_dwordx4 v[212:213], off
	v_mfma_f32_16x16x32_bf16 v[68:71], v[156:159], v[208:211], v[68:71]
	ds_read_b128 v[160:163], v199 offset:49152
	ds_read_b128 v[180:183], v199 offset:50176
	ds_read_b128 v[184:187], v199 offset:51200
	ds_read_b128 v[188:191], v199 offset:52224
	ds_read_b128 v[192:195], v199 offset:53248
	ds_read_b128 v[200:203], v199 offset:54272
	ds_read_b128 v[204:207], v199 offset:55296
	ds_read_b128 v[208:211], v199 offset:56320
	s_mov_b32 m0, s41
	v_lshl_add_u64 v[212:213], v[216:217], 0, s[16:17]
	global_load_lds_dwordx4 v[212:213], off
	s_mov_b32 m0, s42
	v_lshl_add_u64 v[212:213], v[218:219], 0, s[16:17]
	global_load_lds_dwordx4 v[212:213], off
	s_waitcnt vmcnt(8)
	s_waitcnt lgkmcnt(0)
	s_barrier
	s_setprio 1
	s_waitcnt lgkmcnt(0)
	v_mfma_f32_16x16x32_bf16 v[56:59], v[128:131], v[160:163], v[56:59]
	v_mfma_f32_16x16x32_bf16 v[60:63], v[136:139], v[160:163], v[60:63]
	v_mfma_f32_16x16x32_bf16 v[40:43], v[128:131], v[184:187], v[40:43]
	v_mfma_f32_16x16x32_bf16 v[44:47], v[136:139], v[184:187], v[44:47]
	v_mfma_f32_16x16x32_bf16 v[24:27], v[128:131], v[192:195], v[24:27]
	v_mfma_f32_16x16x32_bf16 v[28:31], v[136:139], v[192:195], v[28:31]
	v_mfma_f32_16x16x32_bf16 v[8:11], v[128:131], v[204:207], v[8:11]
	v_mfma_f32_16x16x32_bf16 v[12:15], v[136:139], v[204:207], v[12:15]
	v_mfma_f32_16x16x32_bf16 v[56:59], v[132:135], v[180:183], v[56:59]
	v_mfma_f32_16x16x32_bf16 v[60:63], v[140:143], v[180:183], v[60:63]
	v_mfma_f32_16x16x32_bf16 v[40:43], v[132:135], v[188:191], v[40:43]
	v_mfma_f32_16x16x32_bf16 v[44:47], v[140:143], v[188:191], v[44:47]
	v_mfma_f32_16x16x32_bf16 v[24:27], v[132:135], v[200:203], v[24:27]
	v_mfma_f32_16x16x32_bf16 v[28:31], v[140:143], v[200:203], v[28:31]
	v_mfma_f32_16x16x32_bf16 v[8:11], v[132:135], v[208:211], v[8:11]
	v_mfma_f32_16x16x32_bf16 v[12:15], v[140:143], v[208:211], v[12:15]
	s_setprio 0
	s_setprio 1
	v_mfma_f32_16x16x32_bf16 v[48:51], v[144:147], v[160:163], v[48:51]
	v_mfma_f32_16x16x32_bf16 v[52:55], v[152:155], v[160:163], v[52:55]
	v_mfma_f32_16x16x32_bf16 v[32:35], v[144:147], v[184:187], v[32:35]
	v_mfma_f32_16x16x32_bf16 v[36:39], v[152:155], v[184:187], v[36:39]
	v_mfma_f32_16x16x32_bf16 v[16:19], v[144:147], v[192:195], v[16:19]
	v_mfma_f32_16x16x32_bf16 v[20:23], v[152:155], v[192:195], v[20:23]
	v_mfma_f32_16x16x32_bf16 v[0:3], v[144:147], v[204:207], v[0:3]
	v_mfma_f32_16x16x32_bf16 v[4:7], v[152:155], v[204:207], v[4:7]
	v_mfma_f32_16x16x32_bf16 v[48:51], v[148:151], v[180:183], v[48:51]
	v_mfma_f32_16x16x32_bf16 v[52:55], v[156:159], v[180:183], v[52:55]
	v_mfma_f32_16x16x32_bf16 v[32:35], v[148:151], v[188:191], v[32:35]
	v_mfma_f32_16x16x32_bf16 v[36:39], v[156:159], v[188:191], v[36:39]
	s_setprio 2
	s_barrier
	v_mfma_f32_16x16x32_bf16 v[16:19], v[148:151], v[200:203], v[16:19]
	v_mfma_f32_16x16x32_bf16 v[20:23], v[156:159], v[200:203], v[20:23]
	v_mfma_f32_16x16x32_bf16 v[0:3], v[148:151], v[208:211], v[0:3]
	v_mfma_f32_16x16x32_bf16 v[4:7], v[156:159], v[208:211], v[4:7]
	s_setprio 0
	s_add_i32 s53, s53, 2
	s_add_u32 s51, s51, 0x100
	s_addc_u32 s52, s52, 0
	s_cmp_gt_u32 s53, 41
	s_mov_b64 s[24:25], s[4:5]
.LBB0_1310:
	ds_read_b128 v[128:131], v197
	ds_read_b128 v[132:135], v197 offset:1024
	ds_read_b128 v[136:139], v197 offset:2048
	ds_read_b128 v[140:143], v197 offset:3072
	ds_read_b128 v[144:147], v198
	ds_read_b128 v[148:151], v198 offset:1024
	ds_read_b128 v[152:155], v198 offset:2048
	ds_read_b128 v[156:159], v198 offset:3072
	s_add_u32 s4, s24, 0x100
	s_addc_u32 s5, s25, 0
	s_cmp_eq_u32 s53, 40
	s_cselect_b32 s29, s21, s5
	s_cselect_b32 s28, s20, s4
	s_cselect_b32 s27, s23, s52
	s_cselect_b32 s26, s22, s51
	v_lshl_add_u64 v[212:213], s[24:25], 0, v[172:173]
	s_add_i32 m0, s36, 0xc000
	ds_read_b128 v[160:163], v199
	ds_read_b128 v[180:183], v199 offset:1024
	ds_read_b128 v[184:187], v199 offset:2048
	ds_read_b128 v[188:191], v199 offset:3072
	ds_read_b128 v[192:195], v199 offset:4096
	ds_read_b128 v[200:203], v199 offset:5120
	ds_read_b128 v[204:207], v199 offset:6144
	ds_read_b128 v[208:211], v199 offset:7168
	global_load_lds_dwordx4 v[212:213], off
	s_add_i32 m0, s36, 0xe000
	v_lshl_add_u64 v[212:213], s[24:25], 0, v[174:175]
	global_load_lds_dwordx4 v[212:213], off
	s_waitcnt vmcnt(8)
	s_waitcnt lgkmcnt(0)
	s_barrier
	s_setprio 1
	s_waitcnt lgkmcnt(0)
	v_mfma_f32_16x16x32_bf16 v[124:127], v[128:131], v[160:163], v[124:127]
	v_mfma_f32_16x16x32_bf16 v[120:123], v[136:139], v[160:163], v[120:123]
	v_mfma_f32_16x16x32_bf16 v[116:119], v[128:131], v[184:187], v[116:119]
	v_mfma_f32_16x16x32_bf16 v[108:111], v[136:139], v[184:187], v[108:111]
	v_mfma_f32_16x16x32_bf16 v[88:91], v[128:131], v[192:195], v[88:91]
	v_mfma_f32_16x16x32_bf16 v[100:103], v[136:139], v[192:195], v[100:103]
	v_mfma_f32_16x16x32_bf16 v[72:75], v[128:131], v[204:207], v[72:75]
	v_mfma_f32_16x16x32_bf16 v[76:79], v[136:139], v[204:207], v[76:79]
	v_mfma_f32_16x16x32_bf16 v[124:127], v[132:135], v[180:183], v[124:127]
	v_mfma_f32_16x16x32_bf16 v[120:123], v[140:143], v[180:183], v[120:123]
	v_mfma_f32_16x16x32_bf16 v[116:119], v[132:135], v[188:191], v[116:119]
	v_mfma_f32_16x16x32_bf16 v[108:111], v[140:143], v[188:191], v[108:111]
	v_mfma_f32_16x16x32_bf16 v[88:91], v[132:135], v[200:203], v[88:91]
	v_mfma_f32_16x16x32_bf16 v[100:103], v[140:143], v[200:203], v[100:103]
	v_mfma_f32_16x16x32_bf16 v[72:75], v[132:135], v[208:211], v[72:75]
	v_mfma_f32_16x16x32_bf16 v[76:79], v[140:143], v[208:211], v[76:79]
	s_setprio 0
	s_setprio 1
	v_mfma_f32_16x16x32_bf16 v[112:115], v[144:147], v[160:163], v[112:115]
	v_mfma_f32_16x16x32_bf16 v[104:107], v[152:155], v[160:163], v[104:107]
	v_mfma_f32_16x16x32_bf16 v[96:99], v[144:147], v[184:187], v[96:99]
	v_mfma_f32_16x16x32_bf16 v[92:95], v[152:155], v[184:187], v[92:95]
	v_mfma_f32_16x16x32_bf16 v[80:83], v[144:147], v[192:195], v[80:83]
	v_mfma_f32_16x16x32_bf16 v[84:87], v[152:155], v[192:195], v[84:87]
	v_mfma_f32_16x16x32_bf16 v[64:67], v[144:147], v[204:207], v[64:67]
	v_mfma_f32_16x16x32_bf16 v[68:71], v[152:155], v[204:207], v[68:71]
	v_mfma_f32_16x16x32_bf16 v[112:115], v[148:151], v[180:183], v[112:115]
	v_mfma_f32_16x16x32_bf16 v[104:107], v[156:159], v[180:183], v[104:107]
	v_mfma_f32_16x16x32_bf16 v[96:99], v[148:151], v[188:191], v[96:99]
	v_mfma_f32_16x16x32_bf16 v[92:95], v[156:159], v[188:191], v[92:95]
	s_setprio 2
	s_barrier
	s_add_i32 s24, s45, s35
	s_mov_b32 m0, s24
	v_lshl_add_u64 v[212:213], s[26:27], 0, v[166:167]
	global_load_lds_dwordx4 v[212:213], off
	v_mfma_f32_16x16x32_bf16 v[80:83], v[148:151], v[200:203], v[80:83]
	s_add_i32 m0, s24, 0x2000
	s_add_u32 s24, s26, 0xb0000
	v_lshl_add_u64 v[214:215], s[26:27], 0, v[170:171]
	s_addc_u32 s25, s27, 0
	s_add_i32 s54, s46, s35
	global_load_lds_dwordx4 v[214:215], off
	v_mfma_f32_16x16x32_bf16 v[84:87], v[156:159], v[200:203], v[84:87]
	v_lshl_add_u64 v[216:217], s[24:25], 0, v[166:167]
	s_mov_b32 m0, s54
	v_lshl_add_u64 v[218:219], s[28:29], 0, v[168:169]
	global_load_lds_dwordx4 v[216:217], off
	v_mfma_f32_16x16x32_bf16 v[64:67], v[148:151], v[208:211], v[64:67]
	s_add_i32 m0, s54, 0x2000
	v_lshl_add_u64 v[216:217], s[24:25], 0, v[170:171]
	global_load_lds_dwordx4 v[216:217], off
	v_mfma_f32_16x16x32_bf16 v[68:71], v[156:159], v[208:211], v[68:71]
	ds_read_b128 v[160:163], v199 offset:16384
	ds_read_b128 v[180:183], v199 offset:17408
	ds_read_b128 v[184:187], v199 offset:18432
	ds_read_b128 v[188:191], v199 offset:19456
	ds_read_b128 v[192:195], v199 offset:20480
	ds_read_b128 v[200:203], v199 offset:21504
	ds_read_b128 v[204:207], v199 offset:22528
	ds_read_b128 v[208:211], v199 offset:23552
	s_mov_b32 m0, s36
	v_lshl_add_u64 v[216:217], s[28:29], 0, v[164:165]
	global_load_lds_dwordx4 v[216:217], off
	s_mov_b32 m0, s37
	s_nop 0
	global_load_lds_dwordx4 v[218:219], off
	s_waitcnt vmcnt(8)
	s_waitcnt lgkmcnt(0)
	s_barrier
	s_setprio 1
	s_waitcnt lgkmcnt(0)
	v_mfma_f32_16x16x32_bf16 v[56:59], v[128:131], v[160:163], v[56:59]
	v_mfma_f32_16x16x32_bf16 v[60:63], v[136:139], v[160:163], v[60:63]
	v_mfma_f32_16x16x32_bf16 v[40:43], v[128:131], v[184:187], v[40:43]
	v_mfma_f32_16x16x32_bf16 v[44:47], v[136:139], v[184:187], v[44:47]
	v_mfma_f32_16x16x32_bf16 v[24:27], v[128:131], v[192:195], v[24:27]
	v_mfma_f32_16x16x32_bf16 v[28:31], v[136:139], v[192:195], v[28:31]
	v_mfma_f32_16x16x32_bf16 v[8:11], v[128:131], v[204:207], v[8:11]
	v_mfma_f32_16x16x32_bf16 v[12:15], v[136:139], v[204:207], v[12:15]
	v_mfma_f32_16x16x32_bf16 v[56:59], v[132:135], v[180:183], v[56:59]
	v_mfma_f32_16x16x32_bf16 v[60:63], v[140:143], v[180:183], v[60:63]
	v_mfma_f32_16x16x32_bf16 v[40:43], v[132:135], v[188:191], v[40:43]
	v_mfma_f32_16x16x32_bf16 v[44:47], v[140:143], v[188:191], v[44:47]
	v_mfma_f32_16x16x32_bf16 v[24:27], v[132:135], v[200:203], v[24:27]
	v_mfma_f32_16x16x32_bf16 v[28:31], v[140:143], v[200:203], v[28:31]
	v_mfma_f32_16x16x32_bf16 v[8:11], v[132:135], v[208:211], v[8:11]
	v_mfma_f32_16x16x32_bf16 v[12:15], v[140:143], v[208:211], v[12:15]
	s_setprio 0
	s_setprio 1
	v_mfma_f32_16x16x32_bf16 v[48:51], v[144:147], v[160:163], v[48:51]
	v_mfma_f32_16x16x32_bf16 v[52:55], v[152:155], v[160:163], v[52:55]
	v_mfma_f32_16x16x32_bf16 v[32:35], v[144:147], v[184:187], v[32:35]
	v_mfma_f32_16x16x32_bf16 v[36:39], v[152:155], v[184:187], v[36:39]
	v_mfma_f32_16x16x32_bf16 v[16:19], v[144:147], v[192:195], v[16:19]
	v_mfma_f32_16x16x32_bf16 v[20:23], v[152:155], v[192:195], v[20:23]
	v_mfma_f32_16x16x32_bf16 v[0:3], v[144:147], v[204:207], v[0:3]
	v_mfma_f32_16x16x32_bf16 v[4:7], v[152:155], v[204:207], v[4:7]
	v_mfma_f32_16x16x32_bf16 v[48:51], v[148:151], v[180:183], v[48:51]
	v_mfma_f32_16x16x32_bf16 v[52:55], v[156:159], v[180:183], v[52:55]
	v_mfma_f32_16x16x32_bf16 v[32:35], v[148:151], v[188:191], v[32:35]
	v_mfma_f32_16x16x32_bf16 v[36:39], v[156:159], v[188:191], v[36:39]
	s_setprio 2
	s_barrier
	v_mfma_f32_16x16x32_bf16 v[16:19], v[148:151], v[200:203], v[16:19]
	v_mfma_f32_16x16x32_bf16 v[20:23], v[156:159], v[200:203], v[20:23]
	v_mfma_f32_16x16x32_bf16 v[0:3], v[148:151], v[208:211], v[0:3]
	v_mfma_f32_16x16x32_bf16 v[4:7], v[156:159], v[208:211], v[4:7]
	s_setprio 0
	s_add_i32 s54, 0, 0x18000
	s_add_i32 s55, 0, 0x1c000
	v_add_u32_e32 v140, s54, v196
	v_add_u32_e32 v156, s55, v196
	ds_read_b128 v[128:131], v140
	ds_read_b128 v[132:135], v140 offset:1024
	ds_read_b128 v[136:139], v140 offset:2048
	ds_read_b128 v[140:143], v140 offset:3072
	ds_read_b128 v[144:147], v156
	ds_read_b128 v[148:151], v156 offset:1024
	ds_read_b128 v[152:155], v156 offset:2048
	ds_read_b128 v[156:159], v156 offset:3072
	s_add_u32 s24, s28, 0xb0000
	s_addc_u32 s25, s29, 0
	s_mov_b32 m0, s38
	v_lshl_add_u64 v[220:221], s[24:25], 0, v[164:165]
	ds_read_b128 v[160:163], v199 offset:32768
	ds_read_b128 v[180:183], v199 offset:33792
	ds_read_b128 v[184:187], v199 offset:34816
	ds_read_b128 v[188:191], v199 offset:35840
	ds_read_b128 v[192:195], v199 offset:36864
	ds_read_b128 v[200:203], v199 offset:37888
	ds_read_b128 v[204:207], v199 offset:38912
	ds_read_b128 v[208:211], v199 offset:39936
	global_load_lds_dwordx4 v[220:221], off
	s_mov_b32 m0, s39
	v_lshl_add_u64 v[220:221], s[24:25], 0, v[168:169]
	global_load_lds_dwordx4 v[220:221], off
	s_waitcnt vmcnt(8)
	s_waitcnt lgkmcnt(0)
	s_barrier
	s_setprio 1
	s_waitcnt lgkmcnt(0)
	v_mfma_f32_16x16x32_bf16 v[124:127], v[128:131], v[160:163], v[124:127]
	v_mfma_f32_16x16x32_bf16 v[120:123], v[136:139], v[160:163], v[120:123]
	v_mfma_f32_16x16x32_bf16 v[116:119], v[128:131], v[184:187], v[116:119]
	v_mfma_f32_16x16x32_bf16 v[108:111], v[136:139], v[184:187], v[108:111]
	v_mfma_f32_16x16x32_bf16 v[88:91], v[128:131], v[192:195], v[88:91]
	v_mfma_f32_16x16x32_bf16 v[100:103], v[136:139], v[192:195], v[100:103]
	v_mfma_f32_16x16x32_bf16 v[72:75], v[128:131], v[204:207], v[72:75]
	v_mfma_f32_16x16x32_bf16 v[76:79], v[136:139], v[204:207], v[76:79]
	v_mfma_f32_16x16x32_bf16 v[124:127], v[132:135], v[180:183], v[124:127]
	v_mfma_f32_16x16x32_bf16 v[120:123], v[140:143], v[180:183], v[120:123]
	v_mfma_f32_16x16x32_bf16 v[116:119], v[132:135], v[188:191], v[116:119]
	v_mfma_f32_16x16x32_bf16 v[108:111], v[140:143], v[188:191], v[108:111]
	v_mfma_f32_16x16x32_bf16 v[88:91], v[132:135], v[200:203], v[88:91]
	v_mfma_f32_16x16x32_bf16 v[100:103], v[140:143], v[200:203], v[100:103]
	v_mfma_f32_16x16x32_bf16 v[72:75], v[132:135], v[208:211], v[72:75]
	v_mfma_f32_16x16x32_bf16 v[76:79], v[140:143], v[208:211], v[76:79]
	s_setprio 0
	s_setprio 1
	v_mfma_f32_16x16x32_bf16 v[112:115], v[144:147], v[160:163], v[112:115]
	v_mfma_f32_16x16x32_bf16 v[104:107], v[152:155], v[160:163], v[104:107]
	v_mfma_f32_16x16x32_bf16 v[96:99], v[144:147], v[184:187], v[96:99]
	v_mfma_f32_16x16x32_bf16 v[92:95], v[152:155], v[184:187], v[92:95]
	v_mfma_f32_16x16x32_bf16 v[80:83], v[144:147], v[192:195], v[80:83]
	v_mfma_f32_16x16x32_bf16 v[84:87], v[152:155], v[192:195], v[84:87]
	v_mfma_f32_16x16x32_bf16 v[64:67], v[144:147], v[204:207], v[64:67]
	v_mfma_f32_16x16x32_bf16 v[68:71], v[152:155], v[204:207], v[68:71]
	v_mfma_f32_16x16x32_bf16 v[112:115], v[148:151], v[180:183], v[112:115]
	v_mfma_f32_16x16x32_bf16 v[104:107], v[156:159], v[180:183], v[104:107]
	v_mfma_f32_16x16x32_bf16 v[96:99], v[148:151], v[188:191], v[96:99]
	v_mfma_f32_16x16x32_bf16 v[92:95], v[156:159], v[188:191], v[92:95]
	s_setprio 2
	s_barrier
	s_add_i32 s24, s54, s35
	s_mov_b32 m0, s24
	v_lshl_add_u64 v[212:213], v[212:213], 0, s[16:17]
	global_load_lds_dwordx4 v[212:213], off
	v_mfma_f32_16x16x32_bf16 v[80:83], v[148:151], v[200:203], v[80:83]
	s_add_i32 m0, s24, 0x2000
	s_add_u32 s24, s26, 0xb0080
	v_lshl_add_u64 v[212:213], v[214:215], 0, s[16:17]
	s_addc_u32 s25, s27, 0
	s_add_i32 s26, s55, s35
	global_load_lds_dwordx4 v[212:213], off
	v_mfma_f32_16x16x32_bf16 v[84:87], v[156:159], v[200:203], v[84:87]
	s_mov_b32 m0, s26
	v_lshl_add_u64 v[212:213], s[24:25], 0, v[166:167]
	global_load_lds_dwordx4 v[212:213], off
	v_mfma_f32_16x16x32_bf16 v[64:67], v[148:151], v[208:211], v[64:67]
	s_add_i32 m0, s26, 0x2000
	v_lshl_add_u64 v[212:213], s[24:25], 0, v[170:171]
	global_load_lds_dwordx4 v[212:213], off
	v_mfma_f32_16x16x32_bf16 v[68:71], v[156:159], v[208:211], v[68:71]
	ds_read_b128 v[160:163], v199 offset:49152
	ds_read_b128 v[180:183], v199 offset:50176
	ds_read_b128 v[184:187], v199 offset:51200
	ds_read_b128 v[188:191], v199 offset:52224
	ds_read_b128 v[192:195], v199 offset:53248
	ds_read_b128 v[200:203], v199 offset:54272
	ds_read_b128 v[204:207], v199 offset:55296
	ds_read_b128 v[208:211], v199 offset:56320
	s_mov_b32 m0, s41
	v_lshl_add_u64 v[212:213], v[216:217], 0, s[16:17]
	global_load_lds_dwordx4 v[212:213], off
	s_mov_b32 m0, s42
	v_lshl_add_u64 v[212:213], v[218:219], 0, s[16:17]
	global_load_lds_dwordx4 v[212:213], off
	s_waitcnt vmcnt(8)
	s_waitcnt lgkmcnt(0)
	s_barrier
	s_setprio 1
	s_waitcnt lgkmcnt(0)
	v_mfma_f32_16x16x32_bf16 v[56:59], v[128:131], v[160:163], v[56:59]
	v_mfma_f32_16x16x32_bf16 v[60:63], v[136:139], v[160:163], v[60:63]
	v_mfma_f32_16x16x32_bf16 v[40:43], v[128:131], v[184:187], v[40:43]
	v_mfma_f32_16x16x32_bf16 v[44:47], v[136:139], v[184:187], v[44:47]
	v_mfma_f32_16x16x32_bf16 v[24:27], v[128:131], v[192:195], v[24:27]
	v_mfma_f32_16x16x32_bf16 v[28:31], v[136:139], v[192:195], v[28:31]
	v_mfma_f32_16x16x32_bf16 v[8:11], v[128:131], v[204:207], v[8:11]
	v_mfma_f32_16x16x32_bf16 v[12:15], v[136:139], v[204:207], v[12:15]
	v_mfma_f32_16x16x32_bf16 v[56:59], v[132:135], v[180:183], v[56:59]
	v_mfma_f32_16x16x32_bf16 v[60:63], v[140:143], v[180:183], v[60:63]
	v_mfma_f32_16x16x32_bf16 v[40:43], v[132:135], v[188:191], v[40:43]
	v_mfma_f32_16x16x32_bf16 v[44:47], v[140:143], v[188:191], v[44:47]
	v_mfma_f32_16x16x32_bf16 v[24:27], v[132:135], v[200:203], v[24:27]
	v_mfma_f32_16x16x32_bf16 v[28:31], v[140:143], v[200:203], v[28:31]
	v_mfma_f32_16x16x32_bf16 v[8:11], v[132:135], v[208:211], v[8:11]
	v_mfma_f32_16x16x32_bf16 v[12:15], v[140:143], v[208:211], v[12:15]
	s_setprio 0
	s_setprio 1
	v_mfma_f32_16x16x32_bf16 v[48:51], v[144:147], v[160:163], v[48:51]
	v_mfma_f32_16x16x32_bf16 v[52:55], v[152:155], v[160:163], v[52:55]
	v_mfma_f32_16x16x32_bf16 v[32:35], v[144:147], v[184:187], v[32:35]
	v_mfma_f32_16x16x32_bf16 v[36:39], v[152:155], v[184:187], v[36:39]
	v_mfma_f32_16x16x32_bf16 v[16:19], v[144:147], v[192:195], v[16:19]
	v_mfma_f32_16x16x32_bf16 v[20:23], v[152:155], v[192:195], v[20:23]
	v_mfma_f32_16x16x32_bf16 v[0:3], v[144:147], v[204:207], v[0:3]
	v_mfma_f32_16x16x32_bf16 v[4:7], v[152:155], v[204:207], v[4:7]
	v_mfma_f32_16x16x32_bf16 v[48:51], v[148:151], v[180:183], v[48:51]
	v_mfma_f32_16x16x32_bf16 v[52:55], v[156:159], v[180:183], v[52:55]
	v_mfma_f32_16x16x32_bf16 v[32:35], v[148:151], v[188:191], v[32:35]
	v_mfma_f32_16x16x32_bf16 v[36:39], v[156:159], v[188:191], v[36:39]
	s_setprio 2
	s_barrier
	v_mfma_f32_16x16x32_bf16 v[16:19], v[148:151], v[200:203], v[16:19]
	v_mfma_f32_16x16x32_bf16 v[20:23], v[156:159], v[200:203], v[20:23]
	v_mfma_f32_16x16x32_bf16 v[0:3], v[148:151], v[208:211], v[0:3]
	v_mfma_f32_16x16x32_bf16 v[4:7], v[156:159], v[208:211], v[4:7]
	s_setprio 0
	s_add_i32 s53, s53, 2
	s_add_u32 s51, s51, 0x100
	s_addc_u32 s52, s52, 0
	s_cmp_gt_u32 s53, 41
	s_mov_b64 s[24:25], s[4:5]
	s_cbranch_scc0 .LBB0_1310
